# v37 + mid-cluster setprio pair removed + conversion slots re-cut + direct XCD release in the grid barrier
# speedup vs baseline: 1.0131x; 1.0015x over previous
.LBB0_394:
	s_add_u32 s0, s24, 0xfff80080
	s_addc_u32 s1, s25, -1
	s_add_i32 s33, 0, 0x10000
	s_cmp_eq_u32 s60, 28
	s_cselect_b32 s29, s7, s1
	s_cselect_b32 s28, s19, s0
	s_cselect_b32 s27, s17, s59
	s_cselect_b32 s26, s49, s58
	s_add_i32 s55, 0, 0x14000
	ds_read_b128 v[142:145], v151
	ds_read_b128 v[146:149], v151 offset:1024
	ds_read_b128 v[154:157], v151 offset:2048
	ds_read_b128 v[158:161], v151 offset:3072
	ds_read_b128 v[162:165], v151 offset:16384
	ds_read_b128 v[166:169], v151 offset:17408
	ds_read_b128 v[170:173], v151 offset:18432
	ds_read_b128 v[174:177], v151 offset:19456
	s_add_i32 m0, s9, 0xc000
	ds_read_b128 v[178:181], v153
	ds_read_b128 v[182:185], v153 offset:1024
	ds_read_b128 v[186:189], v153 offset:2048
	ds_read_b128 v[190:193], v153 offset:3072
	ds_read_b128 v[194:197], v153 offset:4096
	ds_read_b128 v[198:201], v153 offset:5120
	ds_read_b128 v[208:211], v153 offset:6144
	ds_read_b128 v[212:215], v153 offset:7168
	global_load_lds_dwordx4 v138, s[24:25]
	s_add_i32 m0, s9, 0xe000
	s_nop 0
	global_load_lds_dwordx4 v140, s[24:25]
	s_waitcnt vmcnt(8)
	s_waitcnt lgkmcnt(0)
	s_setprio 1
	s_barrier
	v_mfma_f32_16x16x32_bf16 v[126:129], v[142:145], v[178:181], v[126:129]
	v_mfma_f32_16x16x32_bf16 v[122:125], v[154:157], v[178:181], v[122:125]
	v_mfma_f32_16x16x32_bf16 v[110:113], v[142:145], v[186:189], v[110:113]
	v_mfma_f32_16x16x32_bf16 v[106:109], v[154:157], v[186:189], v[106:109]
	v_mfma_f32_16x16x32_bf16 v[94:97], v[142:145], v[194:197], v[94:97]
	v_mfma_f32_16x16x32_bf16 v[90:93], v[154:157], v[194:197], v[90:93]
	v_mfma_f32_16x16x32_bf16 v[78:81], v[142:145], v[208:211], v[78:81]
	v_mfma_f32_16x16x32_bf16 v[74:77], v[154:157], v[208:211], v[74:77]
	v_mfma_f32_16x16x32_bf16 v[126:129], v[146:149], v[182:185], v[126:129]
	v_mfma_f32_16x16x32_bf16 v[122:125], v[158:161], v[182:185], v[122:125]
	v_mfma_f32_16x16x32_bf16 v[110:113], v[146:149], v[190:193], v[110:113]
	v_mfma_f32_16x16x32_bf16 v[106:109], v[158:161], v[190:193], v[106:109]
	v_mfma_f32_16x16x32_bf16 v[94:97], v[146:149], v[198:201], v[94:97]
	v_mfma_f32_16x16x32_bf16 v[90:93], v[158:161], v[198:201], v[90:93]
	v_mfma_f32_16x16x32_bf16 v[78:81], v[146:149], v[212:215], v[78:81]
	v_mfma_f32_16x16x32_bf16 v[74:77], v[158:161], v[212:215], v[74:77]
	v_mfma_f32_16x16x32_bf16 v[118:121], v[162:165], v[178:181], v[118:121]
	v_mfma_f32_16x16x32_bf16 v[114:117], v[170:173], v[178:181], v[114:117]
	v_mfma_f32_16x16x32_bf16 v[102:105], v[162:165], v[186:189], v[102:105]
	v_mfma_f32_16x16x32_bf16 v[98:101], v[170:173], v[186:189], v[98:101]
	v_mfma_f32_16x16x32_bf16 v[86:89], v[162:165], v[194:197], v[86:89]
	v_mfma_f32_16x16x32_bf16 v[82:85], v[170:173], v[194:197], v[82:85]
	v_mfma_f32_16x16x32_bf16 v[70:73], v[162:165], v[208:211], v[70:73]
	v_mfma_f32_16x16x32_bf16 v[66:69], v[170:173], v[208:211], v[66:69]
	v_mfma_f32_16x16x32_bf16 v[118:121], v[166:169], v[182:185], v[118:121]
	v_mfma_f32_16x16x32_bf16 v[114:117], v[174:177], v[182:185], v[114:117]
	v_mfma_f32_16x16x32_bf16 v[102:105], v[166:169], v[190:193], v[102:105]
	v_mfma_f32_16x16x32_bf16 v[98:101], v[174:177], v[190:193], v[98:101]
	v_mfma_f32_16x16x32_bf16 v[86:89], v[166:169], v[198:201], v[86:89]
	v_mfma_f32_16x16x32_bf16 v[82:85], v[174:177], v[198:201], v[82:85]
	v_mfma_f32_16x16x32_bf16 v[70:73], v[166:169], v[212:215], v[70:73]
	v_mfma_f32_16x16x32_bf16 v[66:69], v[174:177], v[212:215], v[66:69]
	s_barrier
	s_setprio 0
	s_add_i32 s0, s33, s34
	s_mov_b32 m0, s0
	ds_read_b128 v[178:181], v153 offset:16384
	ds_read_b128 v[182:185], v153 offset:17408
	ds_read_b128 v[186:189], v153 offset:18432
	ds_read_b128 v[190:193], v153 offset:19456
	ds_read_b128 v[194:197], v153 offset:20480
	ds_read_b128 v[198:201], v153 offset:21504
	ds_read_b128 v[208:211], v153 offset:22528
	ds_read_b128 v[212:215], v153 offset:23552
	global_load_lds_dwordx4 v132, s[26:27]
	s_add_i32 m0, s0, 0x2000
	s_add_u32 s0, s26, 0x80000
	s_addc_u32 s1, s27, 0
	s_add_i32 s33, s55, s34
	global_load_lds_dwordx4 v136, s[26:27]
	s_mov_b32 m0, s33
	s_nop 0
	global_load_lds_dwordx4 v132, s[0:1]
	s_add_i32 m0, s33, 0x2000
	s_nop 0
	global_load_lds_dwordx4 v136, s[0:1]
	s_mov_b32 m0, s9
	s_nop 0
	global_load_lds_dwordx4 v130, s[28:29]
	s_mov_b32 m0, s35
	s_nop 0
	global_load_lds_dwordx4 v134, s[28:29]
	s_waitcnt vmcnt(8)
	s_waitcnt lgkmcnt(0)
	s_setprio 1
	s_barrier
	v_mfma_f32_16x16x32_bf16 v[62:65], v[142:145], v[178:181], v[62:65]
	v_mfma_f32_16x16x32_bf16 v[58:61], v[154:157], v[178:181], v[58:61]
	v_mfma_f32_16x16x32_bf16 v[46:49], v[142:145], v[186:189], v[46:49]
	v_mfma_f32_16x16x32_bf16 v[42:45], v[154:157], v[186:189], v[42:45]
	v_mfma_f32_16x16x32_bf16 v[30:33], v[142:145], v[194:197], v[30:33]
	v_mfma_f32_16x16x32_bf16 v[26:29], v[154:157], v[194:197], v[26:29]
	v_mfma_f32_16x16x32_bf16 v[14:17], v[142:145], v[208:211], v[14:17]
	v_mfma_f32_16x16x32_bf16 v[10:13], v[154:157], v[208:211], v[10:13]
	v_mfma_f32_16x16x32_bf16 v[62:65], v[146:149], v[182:185], v[62:65]
	v_mfma_f32_16x16x32_bf16 v[58:61], v[158:161], v[182:185], v[58:61]
	v_mfma_f32_16x16x32_bf16 v[46:49], v[146:149], v[190:193], v[46:49]
	v_mfma_f32_16x16x32_bf16 v[42:45], v[158:161], v[190:193], v[42:45]
	v_mfma_f32_16x16x32_bf16 v[30:33], v[146:149], v[198:201], v[30:33]
	v_mfma_f32_16x16x32_bf16 v[26:29], v[158:161], v[198:201], v[26:29]
	v_mfma_f32_16x16x32_bf16 v[14:17], v[146:149], v[212:215], v[14:17]
	v_mfma_f32_16x16x32_bf16 v[10:13], v[158:161], v[212:215], v[10:13]
	v_mfma_f32_16x16x32_bf16 v[54:57], v[162:165], v[178:181], v[54:57]
	v_mfma_f32_16x16x32_bf16 v[50:53], v[170:173], v[178:181], v[50:53]
	v_mfma_f32_16x16x32_bf16 v[38:41], v[162:165], v[186:189], v[38:41]
	v_mfma_f32_16x16x32_bf16 v[34:37], v[170:173], v[186:189], v[34:37]
	v_mfma_f32_16x16x32_bf16 v[22:25], v[162:165], v[194:197], v[22:25]
	v_mfma_f32_16x16x32_bf16 v[18:21], v[170:173], v[194:197], v[18:21]
	v_mfma_f32_16x16x32_bf16 v[6:9], v[162:165], v[208:211], v[6:9]
	v_mfma_f32_16x16x32_bf16 v[2:5], v[170:173], v[208:211], v[2:5]
	v_mfma_f32_16x16x32_bf16 v[54:57], v[166:169], v[182:185], v[54:57]
	v_mfma_f32_16x16x32_bf16 v[50:53], v[174:177], v[182:185], v[50:53]
	v_mfma_f32_16x16x32_bf16 v[38:41], v[166:169], v[190:193], v[38:41]
	v_mfma_f32_16x16x32_bf16 v[34:37], v[174:177], v[190:193], v[34:37]
	v_mfma_f32_16x16x32_bf16 v[22:25], v[166:169], v[198:201], v[22:25]
	v_mfma_f32_16x16x32_bf16 v[18:21], v[174:177], v[198:201], v[18:21]
	v_mfma_f32_16x16x32_bf16 v[6:9], v[166:169], v[212:215], v[6:9]
	v_mfma_f32_16x16x32_bf16 v[2:5], v[174:177], v[212:215], v[2:5]
	s_barrier
	s_setprio 0
	s_add_i32 s33, 0, 0x18000
	s_add_i32 s55, 0, 0x1c000
	ds_read_b128 v[142:145], v151 offset:32768
	ds_read_b128 v[146:149], v151 offset:33792
	ds_read_b128 v[154:157], v151 offset:34816
	ds_read_b128 v[158:161], v151 offset:35840
	ds_read_b128 v[162:165], v151 offset:49152
	ds_read_b128 v[166:169], v151 offset:50176
	ds_read_b128 v[170:173], v151 offset:51200
	ds_read_b128 v[174:177], v151 offset:52224
	s_add_u32 s0, s28, 0x80000
	s_addc_u32 s1, s29, 0
	s_mov_b32 m0, s36
	ds_read_b128 v[178:181], v153 offset:32768
	ds_read_b128 v[182:185], v153 offset:33792
	ds_read_b128 v[186:189], v153 offset:34816
	ds_read_b128 v[190:193], v153 offset:35840
	ds_read_b128 v[194:197], v153 offset:36864
	ds_read_b128 v[198:201], v153 offset:37888
	ds_read_b128 v[208:211], v153 offset:38912
	ds_read_b128 v[212:215], v153 offset:39936
	global_load_lds_dwordx4 v130, s[0:1]
	s_mov_b32 m0, s37
	s_nop 0
	global_load_lds_dwordx4 v134, s[0:1]
	s_waitcnt vmcnt(8)
	s_waitcnt lgkmcnt(0)
	s_setprio 1
	s_barrier
	v_mfma_f32_16x16x32_bf16 v[126:129], v[142:145], v[178:181], v[126:129]
	v_mfma_f32_16x16x32_bf16 v[122:125], v[154:157], v[178:181], v[122:125]
	v_mfma_f32_16x16x32_bf16 v[110:113], v[142:145], v[186:189], v[110:113]
	v_mfma_f32_16x16x32_bf16 v[106:109], v[154:157], v[186:189], v[106:109]
	v_mfma_f32_16x16x32_bf16 v[94:97], v[142:145], v[194:197], v[94:97]
	v_mfma_f32_16x16x32_bf16 v[90:93], v[154:157], v[194:197], v[90:93]
	v_mfma_f32_16x16x32_bf16 v[78:81], v[142:145], v[208:211], v[78:81]
	v_mfma_f32_16x16x32_bf16 v[74:77], v[154:157], v[208:211], v[74:77]
	v_mfma_f32_16x16x32_bf16 v[126:129], v[146:149], v[182:185], v[126:129]
	v_mfma_f32_16x16x32_bf16 v[122:125], v[158:161], v[182:185], v[122:125]
	v_mfma_f32_16x16x32_bf16 v[110:113], v[146:149], v[190:193], v[110:113]
	v_mfma_f32_16x16x32_bf16 v[106:109], v[158:161], v[190:193], v[106:109]
	v_mfma_f32_16x16x32_bf16 v[94:97], v[146:149], v[198:201], v[94:97]
	v_mfma_f32_16x16x32_bf16 v[90:93], v[158:161], v[198:201], v[90:93]
	v_mfma_f32_16x16x32_bf16 v[78:81], v[146:149], v[212:215], v[78:81]
	v_mfma_f32_16x16x32_bf16 v[74:77], v[158:161], v[212:215], v[74:77]
	v_mfma_f32_16x16x32_bf16 v[118:121], v[162:165], v[178:181], v[118:121]
	v_mfma_f32_16x16x32_bf16 v[114:117], v[170:173], v[178:181], v[114:117]
	v_mfma_f32_16x16x32_bf16 v[102:105], v[162:165], v[186:189], v[102:105]
	v_mfma_f32_16x16x32_bf16 v[98:101], v[170:173], v[186:189], v[98:101]
	v_mfma_f32_16x16x32_bf16 v[86:89], v[162:165], v[194:197], v[86:89]
	v_mfma_f32_16x16x32_bf16 v[82:85], v[170:173], v[194:197], v[82:85]
	v_mfma_f32_16x16x32_bf16 v[70:73], v[162:165], v[208:211], v[70:73]
	v_mfma_f32_16x16x32_bf16 v[66:69], v[170:173], v[208:211], v[66:69]
	v_mfma_f32_16x16x32_bf16 v[118:121], v[166:169], v[182:185], v[118:121]
	v_mfma_f32_16x16x32_bf16 v[114:117], v[174:177], v[182:185], v[114:117]
	v_mfma_f32_16x16x32_bf16 v[102:105], v[166:169], v[190:193], v[102:105]
	v_mfma_f32_16x16x32_bf16 v[98:101], v[174:177], v[190:193], v[98:101]
	v_mfma_f32_16x16x32_bf16 v[86:89], v[166:169], v[198:201], v[86:89]
	v_mfma_f32_16x16x32_bf16 v[82:85], v[174:177], v[198:201], v[82:85]
	v_mfma_f32_16x16x32_bf16 v[70:73], v[166:169], v[212:215], v[70:73]
	v_mfma_f32_16x16x32_bf16 v[66:69], v[174:177], v[212:215], v[66:69]
	s_barrier
	s_setprio 0
	s_add_i32 s0, s33, s34
	s_add_u32 s100, s26, 0x80
	s_addc_u32 s101, s27, 0
	s_mov_b32 m0, s0
	ds_read_b128 v[178:181], v153 offset:49152
	ds_read_b128 v[182:185], v153 offset:50176
	ds_read_b128 v[186:189], v153 offset:51200
	ds_read_b128 v[190:193], v153 offset:52224
	ds_read_b128 v[194:197], v153 offset:53248
	ds_read_b128 v[198:201], v153 offset:54272
	ds_read_b128 v[208:211], v153 offset:55296
	ds_read_b128 v[212:215], v153 offset:56320
	global_load_lds_dwordx4 v132, s[100:101]
	s_add_i32 m0, s0, 0x2000
	s_add_u32 s100, s26, 0x80
	s_addc_u32 s101, s27, 0
	s_add_u32 s0, s26, 0x80080
	s_addc_u32 s1, s27, 0
	s_add_i32 s26, s55, s34
	global_load_lds_dwordx4 v136, s[100:101]
	s_mov_b32 m0, s26
	s_nop 0
	global_load_lds_dwordx4 v132, s[0:1]
	s_add_i32 m0, s26, 0x2000
	s_nop 0
	global_load_lds_dwordx4 v136, s[0:1]
	s_add_u32 s100, s28, 0x80
	s_addc_u32 s101, s29, 0
	s_mov_b32 m0, s39
	s_nop 0
	global_load_lds_dwordx4 v130, s[100:101]
	s_add_u32 s100, s28, 0x80
	s_addc_u32 s101, s29, 0
	s_mov_b32 m0, s40
	s_nop 0
	global_load_lds_dwordx4 v134, s[100:101]
	s_waitcnt vmcnt(8)
	s_waitcnt lgkmcnt(0)
	s_setprio 1
	s_barrier
	v_mfma_f32_16x16x32_bf16 v[62:65], v[142:145], v[178:181], v[62:65]
	v_mfma_f32_16x16x32_bf16 v[58:61], v[154:157], v[178:181], v[58:61]
	v_mfma_f32_16x16x32_bf16 v[46:49], v[142:145], v[186:189], v[46:49]
	v_mfma_f32_16x16x32_bf16 v[42:45], v[154:157], v[186:189], v[42:45]
	v_mfma_f32_16x16x32_bf16 v[30:33], v[142:145], v[194:197], v[30:33]
	v_mfma_f32_16x16x32_bf16 v[26:29], v[154:157], v[194:197], v[26:29]
	v_mfma_f32_16x16x32_bf16 v[14:17], v[142:145], v[208:211], v[14:17]
	v_mfma_f32_16x16x32_bf16 v[10:13], v[154:157], v[208:211], v[10:13]
	v_mfma_f32_16x16x32_bf16 v[62:65], v[146:149], v[182:185], v[62:65]
	v_mfma_f32_16x16x32_bf16 v[58:61], v[158:161], v[182:185], v[58:61]
	v_mfma_f32_16x16x32_bf16 v[46:49], v[146:149], v[190:193], v[46:49]
	v_mfma_f32_16x16x32_bf16 v[42:45], v[158:161], v[190:193], v[42:45]
	v_mfma_f32_16x16x32_bf16 v[30:33], v[146:149], v[198:201], v[30:33]
	v_mfma_f32_16x16x32_bf16 v[26:29], v[158:161], v[198:201], v[26:29]
	v_mfma_f32_16x16x32_bf16 v[14:17], v[146:149], v[212:215], v[14:17]
	v_mfma_f32_16x16x32_bf16 v[10:13], v[158:161], v[212:215], v[10:13]
	v_mfma_f32_16x16x32_bf16 v[54:57], v[162:165], v[178:181], v[54:57]
	v_mfma_f32_16x16x32_bf16 v[50:53], v[170:173], v[178:181], v[50:53]
	v_mfma_f32_16x16x32_bf16 v[38:41], v[162:165], v[186:189], v[38:41]
	v_mfma_f32_16x16x32_bf16 v[34:37], v[170:173], v[186:189], v[34:37]
	v_mfma_f32_16x16x32_bf16 v[22:25], v[162:165], v[194:197], v[22:25]
	v_mfma_f32_16x16x32_bf16 v[18:21], v[170:173], v[194:197], v[18:21]
	v_mfma_f32_16x16x32_bf16 v[6:9], v[162:165], v[208:211], v[6:9]
	v_mfma_f32_16x16x32_bf16 v[2:5], v[170:173], v[208:211], v[2:5]
	v_mfma_f32_16x16x32_bf16 v[54:57], v[166:169], v[182:185], v[54:57]
	v_mfma_f32_16x16x32_bf16 v[50:53], v[174:177], v[182:185], v[50:53]
	v_mfma_f32_16x16x32_bf16 v[38:41], v[166:169], v[190:193], v[38:41]
	v_mfma_f32_16x16x32_bf16 v[34:37], v[174:177], v[190:193], v[34:37]
	v_mfma_f32_16x16x32_bf16 v[22:25], v[166:169], v[198:201], v[22:25]
	v_mfma_f32_16x16x32_bf16 v[18:21], v[174:177], v[198:201], v[18:21]
	v_mfma_f32_16x16x32_bf16 v[6:9], v[166:169], v[212:215], v[6:9]
	v_mfma_f32_16x16x32_bf16 v[2:5], v[174:177], v[212:215], v[2:5]
	s_barrier
	s_setprio 0
	s_add_i32 s60, s60, 2
	s_add_u32 s24, s24, 0x100
	s_addc_u32 s25, s25, 0
	s_add_u32 s58, s58, 0x100
	s_addc_u32 s59, s59, 0
	s_cmp_gt_u32 s60, 29
	s_cbranch_scc0 .LBB0_394
	s_and_b64 vcc, exec, s[14:15]
	s_cbranch_vccz .LBB0_397
	s_barrier

.LBB0_692:
	s_add_u32 s0, s18, 0xfff00080
	s_addc_u32 s1, s19, -1
	s_add_i32 s33, 0, 0x10000
	s_cmp_eq_u32 s61, 60
	s_cselect_b32 s23, s11, s1
	s_cselect_b32 s22, s49, s0
	s_cselect_b32 s21, s9, s60
	s_cselect_b32 s20, s58, s59
	s_add_i32 s55, 0, 0x14000
	ds_read_b128 v[78:81], v205
	ds_read_b128 v[86:89], v205 offset:1024
	ds_read_b128 v[94:97], v205 offset:2048
	ds_read_b128 v[98:101], v205 offset:3072
	ds_read_b128 v[106:109], v205 offset:16384
	ds_read_b128 v[110:113], v205 offset:17408
	ds_read_b128 v[126:129], v205 offset:18432
	ds_read_b128 v[134:137], v205 offset:19456
	s_add_i32 m0, s27, 0xc000
	ds_read_b128 v[146:149], v239
	ds_read_b128 v[158:161], v239 offset:1024
	ds_read_b128 v[166:169], v239 offset:2048
	ds_read_b128 v[174:177], v239 offset:3072
	ds_read_b128 v[178:181], v239 offset:4096
	ds_read_b128 v[182:185], v239 offset:5120
	ds_read_b128 v[186:189], v239 offset:6144
	ds_read_b128 v[190:193], v239 offset:7168
	global_load_lds_dwordx4 v214, s[18:19]
	s_add_i32 m0, s27, 0xe000
	s_nop 0
	global_load_lds_dwordx4 v216, s[18:19]
	s_waitcnt vmcnt(8)
	s_waitcnt lgkmcnt(0)
	s_setprio 1
	s_barrier
	v_mfma_f32_16x16x32_bf16 v[170:173], v[78:81], v[146:149], v[170:173]
	v_mfma_f32_16x16x32_bf16 v[162:165], v[94:97], v[146:149], v[162:165]
	v_mfma_f32_16x16x32_bf16 v[142:145], v[78:81], v[166:169], v[142:145]
	v_mfma_f32_16x16x32_bf16 v[138:141], v[94:97], v[166:169], v[138:141]
	v_mfma_f32_16x16x32_bf16 v[118:121], v[78:81], v[178:181], v[118:121]
	v_mfma_f32_16x16x32_bf16 v[114:117], v[94:97], v[178:181], v[114:117]
	v_mfma_f32_16x16x32_bf16 v[82:85], v[78:81], v[186:189], v[82:85]
	v_mfma_f32_16x16x32_bf16 v[74:77], v[94:97], v[186:189], v[74:77]
	v_mfma_f32_16x16x32_bf16 v[170:173], v[86:89], v[158:161], v[170:173]
	v_mfma_f32_16x16x32_bf16 v[162:165], v[98:101], v[158:161], v[162:165]
	v_mfma_f32_16x16x32_bf16 v[142:145], v[86:89], v[174:177], v[142:145]
	v_mfma_f32_16x16x32_bf16 v[138:141], v[98:101], v[174:177], v[138:141]
	v_mfma_f32_16x16x32_bf16 v[118:121], v[86:89], v[182:185], v[118:121]
	v_mfma_f32_16x16x32_bf16 v[114:117], v[98:101], v[182:185], v[114:117]
	v_mfma_f32_16x16x32_bf16 v[82:85], v[86:89], v[190:193], v[82:85]
	v_mfma_f32_16x16x32_bf16 v[74:77], v[98:101], v[190:193], v[74:77]
	v_mfma_f32_16x16x32_bf16 v[154:157], v[106:109], v[146:149], v[154:157]
	v_mfma_f32_16x16x32_bf16 v[130:133], v[106:109], v[166:169], v[130:133]
	v_mfma_f32_16x16x32_bf16 v[122:125], v[126:129], v[166:169], v[122:125]
	v_mfma_f32_16x16x32_bf16 v[102:105], v[106:109], v[178:181], v[102:105]
	v_mfma_f32_16x16x32_bf16 v[90:93], v[126:129], v[178:181], v[90:93]
	v_mfma_f32_16x16x32_bf16 v[70:73], v[106:109], v[186:189], v[70:73]
	v_mfma_f32_16x16x32_bf16 v[66:69], v[126:129], v[186:189], v[66:69]
	v_mfma_f32_16x16x32_bf16 v[154:157], v[110:113], v[158:161], v[154:157]
	v_mfma_f32_16x16x32_bf16 v[146:149], v[126:129], v[146:149], v[150:153]
	v_mfma_f32_16x16x32_bf16 v[130:133], v[110:113], v[174:177], v[130:133]
	v_mfma_f32_16x16x32_bf16 v[122:125], v[134:137], v[174:177], v[122:125]
	v_mfma_f32_16x16x32_bf16 v[102:105], v[110:113], v[182:185], v[102:105]
	v_mfma_f32_16x16x32_bf16 v[90:93], v[134:137], v[182:185], v[90:93]
	v_mfma_f32_16x16x32_bf16 v[70:73], v[110:113], v[190:193], v[70:73]
	v_mfma_f32_16x16x32_bf16 v[66:69], v[134:137], v[190:193], v[66:69]
	v_mfma_f32_16x16x32_bf16 v[146:149], v[134:137], v[158:161], v[146:149]
	s_barrier
	s_setprio 0
	s_add_i32 s0, s33, s26
	s_mov_b32 m0, s0
	ds_read_b128 v[150:153], v239 offset:16384
	ds_read_b128 v[158:161], v239 offset:17408
	ds_read_b128 v[166:169], v239 offset:18432
	ds_read_b128 v[174:177], v239 offset:19456
	ds_read_b128 v[178:181], v239 offset:20480
	ds_read_b128 v[182:185], v239 offset:21504
	ds_read_b128 v[186:189], v239 offset:22528
	ds_read_b128 v[190:193], v239 offset:23552
	global_load_lds_dwordx4 v202, s[20:21]
	s_add_i32 m0, s0, 0x2000
	s_add_u32 s0, s20, 0x100000
	s_addc_u32 s1, s21, 0
	s_add_i32 s33, s55, s26
	global_load_lds_dwordx4 v208, s[20:21]
	s_mov_b32 m0, s33
	s_nop 0
	global_load_lds_dwordx4 v202, s[0:1]
	s_add_i32 m0, s33, 0x2000
	s_nop 0
	global_load_lds_dwordx4 v208, s[0:1]
	s_mov_b32 m0, s27
	s_nop 0
	global_load_lds_dwordx4 v212, s[22:23]
	s_mov_b32 m0, s28
	s_nop 0
	global_load_lds_dwordx4 v210, s[22:23]
	s_waitcnt vmcnt(8)
	s_waitcnt lgkmcnt(0)
	s_setprio 1
	s_barrier
	v_mfma_f32_16x16x32_bf16 v[62:65], v[78:81], v[150:153], v[62:65]
	v_mfma_f32_16x16x32_bf16 v[58:61], v[94:97], v[150:153], v[58:61]
	v_mfma_f32_16x16x32_bf16 v[46:49], v[78:81], v[166:169], v[46:49]
	v_mfma_f32_16x16x32_bf16 v[42:45], v[94:97], v[166:169], v[42:45]
	v_mfma_f32_16x16x32_bf16 v[30:33], v[78:81], v[178:181], v[30:33]
	v_mfma_f32_16x16x32_bf16 v[26:29], v[94:97], v[178:181], v[26:29]
	v_mfma_f32_16x16x32_bf16 v[14:17], v[78:81], v[186:189], v[14:17]
	v_mfma_f32_16x16x32_bf16 v[10:13], v[94:97], v[186:189], v[10:13]
	v_mfma_f32_16x16x32_bf16 v[62:65], v[86:89], v[158:161], v[62:65]
	v_mfma_f32_16x16x32_bf16 v[58:61], v[98:101], v[158:161], v[58:61]
	v_mfma_f32_16x16x32_bf16 v[46:49], v[86:89], v[174:177], v[46:49]
	v_mfma_f32_16x16x32_bf16 v[42:45], v[98:101], v[174:177], v[42:45]
	v_mfma_f32_16x16x32_bf16 v[30:33], v[86:89], v[182:185], v[30:33]
	v_mfma_f32_16x16x32_bf16 v[26:29], v[98:101], v[182:185], v[26:29]
	v_mfma_f32_16x16x32_bf16 v[14:17], v[86:89], v[190:193], v[14:17]
	v_mfma_f32_16x16x32_bf16 v[10:13], v[98:101], v[190:193], v[10:13]
	v_mfma_f32_16x16x32_bf16 v[54:57], v[106:109], v[150:153], v[54:57]
	v_mfma_f32_16x16x32_bf16 v[50:53], v[126:129], v[150:153], v[50:53]
	v_mfma_f32_16x16x32_bf16 v[38:41], v[106:109], v[166:169], v[38:41]
	v_mfma_f32_16x16x32_bf16 v[34:37], v[126:129], v[166:169], v[34:37]
	v_mfma_f32_16x16x32_bf16 v[22:25], v[106:109], v[178:181], v[22:25]
	v_mfma_f32_16x16x32_bf16 v[18:21], v[126:129], v[178:181], v[18:21]
	v_mfma_f32_16x16x32_bf16 v[6:9], v[106:109], v[186:189], v[6:9]
	v_mfma_f32_16x16x32_bf16 v[2:5], v[126:129], v[186:189], v[2:5]
	v_mfma_f32_16x16x32_bf16 v[54:57], v[110:113], v[158:161], v[54:57]
	v_mfma_f32_16x16x32_bf16 v[50:53], v[134:137], v[158:161], v[50:53]
	v_mfma_f32_16x16x32_bf16 v[38:41], v[110:113], v[174:177], v[38:41]
	v_mfma_f32_16x16x32_bf16 v[34:37], v[134:137], v[174:177], v[34:37]
	v_mfma_f32_16x16x32_bf16 v[22:25], v[110:113], v[182:185], v[22:25]
	v_mfma_f32_16x16x32_bf16 v[18:21], v[134:137], v[182:185], v[18:21]
	v_mfma_f32_16x16x32_bf16 v[6:9], v[110:113], v[190:193], v[6:9]
	v_mfma_f32_16x16x32_bf16 v[2:5], v[134:137], v[190:193], v[2:5]
	s_barrier
	s_setprio 0
	s_add_i32 s33, 0, 0x18000
	s_add_i32 s55, 0, 0x1c000
	ds_read_b128 v[78:81], v205 offset:32768
	ds_read_b128 v[86:89], v205 offset:33792
	ds_read_b128 v[94:97], v205 offset:34816
	ds_read_b128 v[98:101], v205 offset:35840
	ds_read_b128 v[106:109], v205 offset:49152
	ds_read_b128 v[110:113], v205 offset:50176
	ds_read_b128 v[126:129], v205 offset:51200
	ds_read_b128 v[134:137], v205 offset:52224
	s_add_u32 s0, s22, 0x100000
	s_addc_u32 s1, s23, 0
	s_mov_b32 m0, s29
	ds_read_b128 v[150:153], v239 offset:32768
	ds_read_b128 v[158:161], v239 offset:33792
	ds_read_b128 v[166:169], v239 offset:34816
	ds_read_b128 v[174:177], v239 offset:35840
	ds_read_b128 v[178:181], v239 offset:36864
	ds_read_b128 v[182:185], v239 offset:37888
	ds_read_b128 v[186:189], v239 offset:38912
	ds_read_b128 v[190:193], v239 offset:39936
	global_load_lds_dwordx4 v212, s[0:1]
	s_mov_b32 m0, s30
	s_nop 0
	global_load_lds_dwordx4 v210, s[0:1]
	s_waitcnt vmcnt(8)
	s_waitcnt lgkmcnt(0)
	s_setprio 1
	s_barrier
	v_mfma_f32_16x16x32_bf16 v[170:173], v[78:81], v[150:153], v[170:173]
	v_mfma_f32_16x16x32_bf16 v[162:165], v[94:97], v[150:153], v[162:165]
	v_mfma_f32_16x16x32_bf16 v[142:145], v[78:81], v[166:169], v[142:145]
	v_mfma_f32_16x16x32_bf16 v[138:141], v[94:97], v[166:169], v[138:141]
	v_mfma_f32_16x16x32_bf16 v[118:121], v[78:81], v[178:181], v[118:121]
	v_mfma_f32_16x16x32_bf16 v[114:117], v[94:97], v[178:181], v[114:117]
	v_mfma_f32_16x16x32_bf16 v[82:85], v[78:81], v[186:189], v[82:85]
	v_mfma_f32_16x16x32_bf16 v[74:77], v[94:97], v[186:189], v[74:77]
	v_mfma_f32_16x16x32_bf16 v[170:173], v[86:89], v[158:161], v[170:173]
	v_mfma_f32_16x16x32_bf16 v[162:165], v[98:101], v[158:161], v[162:165]
	v_mfma_f32_16x16x32_bf16 v[142:145], v[86:89], v[174:177], v[142:145]
	v_mfma_f32_16x16x32_bf16 v[138:141], v[98:101], v[174:177], v[138:141]
	v_mfma_f32_16x16x32_bf16 v[118:121], v[86:89], v[182:185], v[118:121]
	v_mfma_f32_16x16x32_bf16 v[114:117], v[98:101], v[182:185], v[114:117]
	v_mfma_f32_16x16x32_bf16 v[82:85], v[86:89], v[190:193], v[82:85]
	v_mfma_f32_16x16x32_bf16 v[74:77], v[98:101], v[190:193], v[74:77]
	v_mfma_f32_16x16x32_bf16 v[154:157], v[106:109], v[150:153], v[154:157]
	v_mfma_f32_16x16x32_bf16 v[146:149], v[126:129], v[150:153], v[146:149]
	v_mfma_f32_16x16x32_bf16 v[130:133], v[106:109], v[166:169], v[130:133]
	v_mfma_f32_16x16x32_bf16 v[122:125], v[126:129], v[166:169], v[122:125]
	v_mfma_f32_16x16x32_bf16 v[102:105], v[106:109], v[178:181], v[102:105]
	v_mfma_f32_16x16x32_bf16 v[90:93], v[126:129], v[178:181], v[90:93]
	v_mfma_f32_16x16x32_bf16 v[70:73], v[106:109], v[186:189], v[70:73]
	v_mfma_f32_16x16x32_bf16 v[66:69], v[126:129], v[186:189], v[66:69]
	v_mfma_f32_16x16x32_bf16 v[154:157], v[110:113], v[158:161], v[154:157]
	v_mfma_f32_16x16x32_bf16 v[150:153], v[134:137], v[158:161], v[146:149]
	v_mfma_f32_16x16x32_bf16 v[130:133], v[110:113], v[174:177], v[130:133]
	v_mfma_f32_16x16x32_bf16 v[122:125], v[134:137], v[174:177], v[122:125]
	v_mfma_f32_16x16x32_bf16 v[102:105], v[110:113], v[182:185], v[102:105]
	v_mfma_f32_16x16x32_bf16 v[90:93], v[134:137], v[182:185], v[90:93]
	v_mfma_f32_16x16x32_bf16 v[70:73], v[110:113], v[190:193], v[70:73]
	v_mfma_f32_16x16x32_bf16 v[66:69], v[134:137], v[190:193], v[66:69]
	s_barrier
	s_setprio 0
	s_add_i32 s0, s33, s26
	s_add_u32 s100, s20, 0x80
	s_addc_u32 s101, s21, 0
	s_mov_b32 m0, s0
	ds_read_b128 v[146:149], v239 offset:49152
	ds_read_b128 v[158:161], v239 offset:50176
	ds_read_b128 v[166:169], v239 offset:51200
	ds_read_b128 v[174:177], v239 offset:52224
	ds_read_b128 v[178:181], v239 offset:53248
	ds_read_b128 v[182:185], v239 offset:54272
	ds_read_b128 v[186:189], v239 offset:55296
	ds_read_b128 v[190:193], v239 offset:56320
	global_load_lds_dwordx4 v202, s[100:101]
	s_add_i32 m0, s0, 0x2000
	s_add_u32 s100, s20, 0x80
	s_addc_u32 s101, s21, 0
	s_add_u32 s0, s20, 0x100080
	s_addc_u32 s1, s21, 0
	s_add_i32 s20, s55, s26
	global_load_lds_dwordx4 v208, s[100:101]
	s_mov_b32 m0, s20
	s_nop 0
	global_load_lds_dwordx4 v202, s[0:1]
	s_add_i32 m0, s20, 0x2000
	s_nop 0
	global_load_lds_dwordx4 v208, s[0:1]
	s_add_u32 s100, s22, 0x80
	s_addc_u32 s101, s23, 0
	s_mov_b32 m0, s35
	s_nop 0
	global_load_lds_dwordx4 v212, s[100:101]
	s_add_u32 s100, s22, 0x80
	s_addc_u32 s101, s23, 0
	s_mov_b32 m0, s36
	s_nop 0
	global_load_lds_dwordx4 v210, s[100:101]
	s_waitcnt vmcnt(8)
	s_waitcnt lgkmcnt(0)
	s_setprio 1
	s_barrier
	v_mfma_f32_16x16x32_bf16 v[62:65], v[78:81], v[146:149], v[62:65]
	v_mfma_f32_16x16x32_bf16 v[58:61], v[94:97], v[146:149], v[58:61]
	v_mfma_f32_16x16x32_bf16 v[46:49], v[78:81], v[166:169], v[46:49]
	v_mfma_f32_16x16x32_bf16 v[42:45], v[94:97], v[166:169], v[42:45]
	v_mfma_f32_16x16x32_bf16 v[30:33], v[78:81], v[178:181], v[30:33]
	v_mfma_f32_16x16x32_bf16 v[26:29], v[94:97], v[178:181], v[26:29]
	v_mfma_f32_16x16x32_bf16 v[14:17], v[78:81], v[186:189], v[14:17]
	v_mfma_f32_16x16x32_bf16 v[10:13], v[94:97], v[186:189], v[10:13]
	v_mfma_f32_16x16x32_bf16 v[62:65], v[86:89], v[158:161], v[62:65]
	v_mfma_f32_16x16x32_bf16 v[58:61], v[98:101], v[158:161], v[58:61]
	v_mfma_f32_16x16x32_bf16 v[46:49], v[86:89], v[174:177], v[46:49]
	v_mfma_f32_16x16x32_bf16 v[42:45], v[98:101], v[174:177], v[42:45]
	v_mfma_f32_16x16x32_bf16 v[30:33], v[86:89], v[182:185], v[30:33]
	v_mfma_f32_16x16x32_bf16 v[26:29], v[98:101], v[182:185], v[26:29]
	v_mfma_f32_16x16x32_bf16 v[14:17], v[86:89], v[190:193], v[14:17]
	v_mfma_f32_16x16x32_bf16 v[10:13], v[98:101], v[190:193], v[10:13]
	v_mfma_f32_16x16x32_bf16 v[54:57], v[106:109], v[146:149], v[54:57]
	v_mfma_f32_16x16x32_bf16 v[50:53], v[126:129], v[146:149], v[50:53]
	v_mfma_f32_16x16x32_bf16 v[38:41], v[106:109], v[166:169], v[38:41]
	v_mfma_f32_16x16x32_bf16 v[34:37], v[126:129], v[166:169], v[34:37]
	v_mfma_f32_16x16x32_bf16 v[22:25], v[106:109], v[178:181], v[22:25]
	v_mfma_f32_16x16x32_bf16 v[18:21], v[126:129], v[178:181], v[18:21]
	v_mfma_f32_16x16x32_bf16 v[6:9], v[106:109], v[186:189], v[6:9]
	v_mfma_f32_16x16x32_bf16 v[2:5], v[126:129], v[186:189], v[2:5]
	v_mfma_f32_16x16x32_bf16 v[54:57], v[110:113], v[158:161], v[54:57]
	v_mfma_f32_16x16x32_bf16 v[50:53], v[134:137], v[158:161], v[50:53]
	v_mfma_f32_16x16x32_bf16 v[38:41], v[110:113], v[174:177], v[38:41]
	v_mfma_f32_16x16x32_bf16 v[34:37], v[134:137], v[174:177], v[34:37]
	v_mfma_f32_16x16x32_bf16 v[22:25], v[110:113], v[182:185], v[22:25]
	v_mfma_f32_16x16x32_bf16 v[18:21], v[134:137], v[182:185], v[18:21]
	v_mfma_f32_16x16x32_bf16 v[6:9], v[110:113], v[190:193], v[6:9]
	v_mfma_f32_16x16x32_bf16 v[2:5], v[134:137], v[190:193], v[2:5]
	s_barrier
	s_setprio 0
	s_add_i32 s61, s61, 2
	s_add_u32 s18, s18, 0x100
	s_addc_u32 s19, s19, 0
	s_add_u32 s59, s59, 0x100
	s_addc_u32 s60, s60, 0
	s_cmp_gt_u32 s61, 61
	s_cbranch_scc0 .LBB0_692
	s_and_b64 vcc, exec, s[6:7]
	s_cbranch_vccz .LBB0_695
	s_barrier

.LBB0_712:
	s_add_u32 s0, s18, 0xfff00080
	s_addc_u32 s1, s19, -1
	s_add_i32 s33, 0, 0x10000
	s_cmp_eq_u32 s49, 4
	s_cselect_b32 s23, s15, s1
	s_cselect_b32 s22, s14, s0
	s_cselect_b32 s21, s17, s11
	s_cselect_b32 s20, s16, s9
	s_add_i32 s55, 0, 0x14000
	ds_read_b128 v[140:143], v136
	ds_read_b128 v[144:147], v136 offset:1024
	ds_read_b128 v[148:151], v136 offset:2048
	ds_read_b128 v[152:155], v136 offset:3072
	ds_read_b128 v[156:159], v136 offset:16384
	ds_read_b128 v[160:163], v136 offset:17408
	ds_read_b128 v[164:167], v136 offset:18432
	ds_read_b128 v[168:171], v136 offset:19456
	s_add_i32 m0, s27, 0xc000
	ds_read_b128 v[172:175], v139
	ds_read_b128 v[176:179], v139 offset:1024
	ds_read_b128 v[180:183], v139 offset:2048
	ds_read_b128 v[184:187], v139 offset:3072
	ds_read_b128 v[188:191], v139 offset:4096
	ds_read_b128 v[192:195], v139 offset:5120
	ds_read_b128 v[196:199], v139 offset:6144
	ds_read_b128 v[208:211], v139 offset:7168
	global_load_lds_dwordx4 v132, s[18:19]
	s_add_i32 m0, s27, 0xe000
	s_nop 0
	global_load_lds_dwordx4 v134, s[18:19]
	s_waitcnt vmcnt(8)
	s_waitcnt lgkmcnt(0)
	s_setprio 1
	s_barrier
	v_mfma_f32_16x16x32_bf16 v[126:129], v[140:143], v[172:175], v[126:129]
	v_mfma_f32_16x16x32_bf16 v[122:125], v[148:151], v[172:175], v[122:125]
	v_mfma_f32_16x16x32_bf16 v[118:121], v[140:143], v[180:183], v[118:121]
	v_mfma_f32_16x16x32_bf16 v[114:117], v[148:151], v[180:183], v[114:117]
	v_mfma_f32_16x16x32_bf16 v[106:109], v[140:143], v[188:191], v[106:109]
	v_mfma_f32_16x16x32_bf16 v[98:101], v[148:151], v[188:191], v[98:101]
	v_mfma_f32_16x16x32_bf16 v[90:93], v[140:143], v[196:199], v[90:93]
	v_mfma_f32_16x16x32_bf16 v[82:85], v[148:151], v[196:199], v[82:85]
	v_mfma_f32_16x16x32_bf16 v[126:129], v[144:147], v[176:179], v[126:129]
	v_mfma_f32_16x16x32_bf16 v[122:125], v[152:155], v[176:179], v[122:125]
	v_mfma_f32_16x16x32_bf16 v[118:121], v[144:147], v[184:187], v[118:121]
	v_mfma_f32_16x16x32_bf16 v[114:117], v[152:155], v[184:187], v[114:117]
	v_mfma_f32_16x16x32_bf16 v[106:109], v[144:147], v[192:195], v[106:109]
	v_mfma_f32_16x16x32_bf16 v[98:101], v[152:155], v[192:195], v[98:101]
	v_mfma_f32_16x16x32_bf16 v[90:93], v[144:147], v[208:211], v[90:93]
	v_mfma_f32_16x16x32_bf16 v[82:85], v[152:155], v[208:211], v[82:85]
	v_mfma_f32_16x16x32_bf16 v[110:113], v[156:159], v[172:175], v[110:113]
	v_mfma_f32_16x16x32_bf16 v[102:105], v[164:167], v[172:175], v[102:105]
	v_mfma_f32_16x16x32_bf16 v[94:97], v[156:159], v[180:183], v[94:97]
	v_mfma_f32_16x16x32_bf16 v[86:89], v[164:167], v[180:183], v[86:89]
	v_mfma_f32_16x16x32_bf16 v[78:81], v[156:159], v[188:191], v[78:81]
	v_mfma_f32_16x16x32_bf16 v[74:77], v[164:167], v[188:191], v[74:77]
	v_mfma_f32_16x16x32_bf16 v[70:73], v[156:159], v[196:199], v[70:73]
	v_mfma_f32_16x16x32_bf16 v[66:69], v[164:167], v[196:199], v[66:69]
	v_mfma_f32_16x16x32_bf16 v[110:113], v[160:163], v[176:179], v[110:113]
	v_mfma_f32_16x16x32_bf16 v[102:105], v[168:171], v[176:179], v[102:105]
	v_mfma_f32_16x16x32_bf16 v[94:97], v[160:163], v[184:187], v[94:97]
	v_mfma_f32_16x16x32_bf16 v[86:89], v[168:171], v[184:187], v[86:89]
	v_mfma_f32_16x16x32_bf16 v[78:81], v[160:163], v[192:195], v[78:81]
	v_mfma_f32_16x16x32_bf16 v[74:77], v[168:171], v[192:195], v[74:77]
	v_mfma_f32_16x16x32_bf16 v[70:73], v[160:163], v[208:211], v[70:73]
	v_mfma_f32_16x16x32_bf16 v[66:69], v[168:171], v[208:211], v[66:69]
	s_barrier
	s_setprio 0
	s_add_i32 s0, s33, s26
	s_mov_b32 m0, s0
	ds_read_b128 v[172:175], v139 offset:16384
	ds_read_b128 v[176:179], v139 offset:17408
	ds_read_b128 v[180:183], v139 offset:18432
	ds_read_b128 v[184:187], v139 offset:19456
	ds_read_b128 v[188:191], v139 offset:20480
	ds_read_b128 v[192:195], v139 offset:21504
	ds_read_b128 v[196:199], v139 offset:22528
	ds_read_b128 v[208:211], v139 offset:23552
	global_load_lds_dwordx4 v202, s[20:21]
	s_add_i32 m0, s0, 0x2000
	s_add_u32 s0, s20, 0x100000
	s_addc_u32 s1, s21, 0
	s_add_i32 s33, s55, s26
	global_load_lds_dwordx4 v130, s[20:21]
	s_mov_b32 m0, s33
	s_nop 0
	global_load_lds_dwordx4 v202, s[0:1]
	s_add_i32 m0, s33, 0x2000
	s_nop 0
	global_load_lds_dwordx4 v130, s[0:1]
	s_mov_b32 m0, s27
	s_nop 0
	global_load_lds_dwordx4 v202, s[22:23]
	s_mov_b32 m0, s28
	s_nop 0
	global_load_lds_dwordx4 v130, s[22:23]
	s_waitcnt vmcnt(8)
	s_waitcnt lgkmcnt(0)
	s_setprio 1
	s_barrier
	v_mfma_f32_16x16x32_bf16 v[62:65], v[140:143], v[172:175], v[62:65]
	v_mfma_f32_16x16x32_bf16 v[58:61], v[148:151], v[172:175], v[58:61]
	v_mfma_f32_16x16x32_bf16 v[54:57], v[140:143], v[180:183], v[54:57]
	v_mfma_f32_16x16x32_bf16 v[50:53], v[148:151], v[180:183], v[50:53]
	v_mfma_f32_16x16x32_bf16 v[38:41], v[140:143], v[188:191], v[38:41]
	v_mfma_f32_16x16x32_bf16 v[34:37], v[148:151], v[188:191], v[34:37]
	v_mfma_f32_16x16x32_bf16 v[22:25], v[140:143], v[196:199], v[22:25]
	v_mfma_f32_16x16x32_bf16 v[18:21], v[148:151], v[196:199], v[18:21]
	v_mfma_f32_16x16x32_bf16 v[62:65], v[144:147], v[176:179], v[62:65]
	v_mfma_f32_16x16x32_bf16 v[58:61], v[152:155], v[176:179], v[58:61]
	v_mfma_f32_16x16x32_bf16 v[54:57], v[144:147], v[184:187], v[54:57]
	v_mfma_f32_16x16x32_bf16 v[50:53], v[152:155], v[184:187], v[50:53]
	v_mfma_f32_16x16x32_bf16 v[38:41], v[144:147], v[192:195], v[38:41]
	v_mfma_f32_16x16x32_bf16 v[34:37], v[152:155], v[192:195], v[34:37]
	v_mfma_f32_16x16x32_bf16 v[22:25], v[144:147], v[208:211], v[22:25]
	v_mfma_f32_16x16x32_bf16 v[18:21], v[152:155], v[208:211], v[18:21]
	v_mfma_f32_16x16x32_bf16 v[46:49], v[156:159], v[172:175], v[46:49]
	v_mfma_f32_16x16x32_bf16 v[42:45], v[164:167], v[172:175], v[42:45]
	v_mfma_f32_16x16x32_bf16 v[30:33], v[156:159], v[180:183], v[30:33]
	v_mfma_f32_16x16x32_bf16 v[26:29], v[164:167], v[180:183], v[26:29]
	v_mfma_f32_16x16x32_bf16 v[14:17], v[156:159], v[188:191], v[14:17]
	v_mfma_f32_16x16x32_bf16 v[10:13], v[164:167], v[188:191], v[10:13]
	v_mfma_f32_16x16x32_bf16 v[6:9], v[156:159], v[196:199], v[6:9]
	v_mfma_f32_16x16x32_bf16 v[2:5], v[164:167], v[196:199], v[2:5]
	v_mfma_f32_16x16x32_bf16 v[46:49], v[160:163], v[176:179], v[46:49]
	v_mfma_f32_16x16x32_bf16 v[42:45], v[168:171], v[176:179], v[42:45]
	v_mfma_f32_16x16x32_bf16 v[30:33], v[160:163], v[184:187], v[30:33]
	v_mfma_f32_16x16x32_bf16 v[26:29], v[168:171], v[184:187], v[26:29]
	v_mfma_f32_16x16x32_bf16 v[14:17], v[160:163], v[192:195], v[14:17]
	v_mfma_f32_16x16x32_bf16 v[10:13], v[168:171], v[192:195], v[10:13]
	v_mfma_f32_16x16x32_bf16 v[6:9], v[160:163], v[208:211], v[6:9]
	v_mfma_f32_16x16x32_bf16 v[2:5], v[168:171], v[208:211], v[2:5]
	s_barrier
	s_setprio 0
	s_add_i32 s33, 0, 0x18000
	s_add_i32 s55, 0, 0x1c000
	ds_read_b128 v[140:143], v136 offset:32768
	ds_read_b128 v[144:147], v136 offset:33792
	ds_read_b128 v[148:151], v136 offset:34816
	ds_read_b128 v[152:155], v136 offset:35840
	ds_read_b128 v[156:159], v136 offset:49152
	ds_read_b128 v[160:163], v136 offset:50176
	ds_read_b128 v[164:167], v136 offset:51200
	ds_read_b128 v[168:171], v136 offset:52224
	s_add_u32 s0, s22, 0x100000
	s_addc_u32 s1, s23, 0
	s_mov_b32 m0, s29
	ds_read_b128 v[172:175], v139 offset:32768
	ds_read_b128 v[176:179], v139 offset:33792
	ds_read_b128 v[180:183], v139 offset:34816
	ds_read_b128 v[184:187], v139 offset:35840
	ds_read_b128 v[188:191], v139 offset:36864
	ds_read_b128 v[192:195], v139 offset:37888
	ds_read_b128 v[196:199], v139 offset:38912
	ds_read_b128 v[208:211], v139 offset:39936
	global_load_lds_dwordx4 v202, s[0:1]
	s_mov_b32 m0, s30
	s_nop 0
	global_load_lds_dwordx4 v130, s[0:1]
	s_waitcnt vmcnt(8)
	s_waitcnt lgkmcnt(0)
	s_setprio 1
	s_barrier
	v_mfma_f32_16x16x32_bf16 v[126:129], v[140:143], v[172:175], v[126:129]
	v_mfma_f32_16x16x32_bf16 v[122:125], v[148:151], v[172:175], v[122:125]
	v_mfma_f32_16x16x32_bf16 v[118:121], v[140:143], v[180:183], v[118:121]
	v_mfma_f32_16x16x32_bf16 v[114:117], v[148:151], v[180:183], v[114:117]
	v_mfma_f32_16x16x32_bf16 v[106:109], v[140:143], v[188:191], v[106:109]
	v_mfma_f32_16x16x32_bf16 v[98:101], v[148:151], v[188:191], v[98:101]
	v_mfma_f32_16x16x32_bf16 v[90:93], v[140:143], v[196:199], v[90:93]
	v_mfma_f32_16x16x32_bf16 v[82:85], v[148:151], v[196:199], v[82:85]
	v_mfma_f32_16x16x32_bf16 v[126:129], v[144:147], v[176:179], v[126:129]
	v_mfma_f32_16x16x32_bf16 v[122:125], v[152:155], v[176:179], v[122:125]
	v_mfma_f32_16x16x32_bf16 v[118:121], v[144:147], v[184:187], v[118:121]
	v_mfma_f32_16x16x32_bf16 v[114:117], v[152:155], v[184:187], v[114:117]
	v_mfma_f32_16x16x32_bf16 v[106:109], v[144:147], v[192:195], v[106:109]
	v_mfma_f32_16x16x32_bf16 v[98:101], v[152:155], v[192:195], v[98:101]
	v_mfma_f32_16x16x32_bf16 v[90:93], v[144:147], v[208:211], v[90:93]
	v_mfma_f32_16x16x32_bf16 v[82:85], v[152:155], v[208:211], v[82:85]
	v_mfma_f32_16x16x32_bf16 v[110:113], v[156:159], v[172:175], v[110:113]
	v_mfma_f32_16x16x32_bf16 v[102:105], v[164:167], v[172:175], v[102:105]
	v_mfma_f32_16x16x32_bf16 v[94:97], v[156:159], v[180:183], v[94:97]
	v_mfma_f32_16x16x32_bf16 v[86:89], v[164:167], v[180:183], v[86:89]
	v_mfma_f32_16x16x32_bf16 v[78:81], v[156:159], v[188:191], v[78:81]
	v_mfma_f32_16x16x32_bf16 v[74:77], v[164:167], v[188:191], v[74:77]
	v_mfma_f32_16x16x32_bf16 v[70:73], v[156:159], v[196:199], v[70:73]
	v_mfma_f32_16x16x32_bf16 v[66:69], v[164:167], v[196:199], v[66:69]
	v_mfma_f32_16x16x32_bf16 v[110:113], v[160:163], v[176:179], v[110:113]
	v_mfma_f32_16x16x32_bf16 v[102:105], v[168:171], v[176:179], v[102:105]
	v_mfma_f32_16x16x32_bf16 v[94:97], v[160:163], v[184:187], v[94:97]
	v_mfma_f32_16x16x32_bf16 v[86:89], v[168:171], v[184:187], v[86:89]
	v_mfma_f32_16x16x32_bf16 v[78:81], v[160:163], v[192:195], v[78:81]
	v_mfma_f32_16x16x32_bf16 v[74:77], v[168:171], v[192:195], v[74:77]
	v_mfma_f32_16x16x32_bf16 v[70:73], v[160:163], v[208:211], v[70:73]
	v_mfma_f32_16x16x32_bf16 v[66:69], v[168:171], v[208:211], v[66:69]
	s_barrier
	s_setprio 0
	s_add_i32 s0, s33, s26
	s_add_u32 s100, s20, 0x80
	s_addc_u32 s101, s21, 0
	s_mov_b32 m0, s0
	ds_read_b128 v[172:175], v139 offset:49152
	ds_read_b128 v[176:179], v139 offset:50176
	ds_read_b128 v[180:183], v139 offset:51200
	ds_read_b128 v[184:187], v139 offset:52224
	ds_read_b128 v[188:191], v139 offset:53248
	ds_read_b128 v[192:195], v139 offset:54272
	ds_read_b128 v[196:199], v139 offset:55296
	ds_read_b128 v[208:211], v139 offset:56320
	global_load_lds_dwordx4 v202, s[100:101]
	s_add_i32 m0, s0, 0x2000
	s_add_u32 s100, s20, 0x80
	s_addc_u32 s101, s21, 0
	s_add_u32 s0, s20, 0x100080
	s_addc_u32 s1, s21, 0
	s_add_i32 s20, s55, s26
	global_load_lds_dwordx4 v130, s[100:101]
	s_mov_b32 m0, s20
	s_nop 0
	global_load_lds_dwordx4 v202, s[0:1]
	s_add_i32 m0, s20, 0x2000
	s_nop 0
	global_load_lds_dwordx4 v130, s[0:1]
	s_add_u32 s100, s22, 0x80
	s_addc_u32 s101, s23, 0
	s_mov_b32 m0, s31
	s_nop 0
	global_load_lds_dwordx4 v202, s[100:101]
	s_add_u32 s100, s22, 0x80
	s_addc_u32 s101, s23, 0
	s_mov_b32 m0, s34
	s_nop 0
	global_load_lds_dwordx4 v130, s[100:101]
	s_waitcnt vmcnt(8)
	s_waitcnt lgkmcnt(0)
	s_setprio 1
	s_barrier
	v_mfma_f32_16x16x32_bf16 v[62:65], v[140:143], v[172:175], v[62:65]
	v_mfma_f32_16x16x32_bf16 v[58:61], v[148:151], v[172:175], v[58:61]
	v_mfma_f32_16x16x32_bf16 v[54:57], v[140:143], v[180:183], v[54:57]
	v_mfma_f32_16x16x32_bf16 v[50:53], v[148:151], v[180:183], v[50:53]
	v_mfma_f32_16x16x32_bf16 v[38:41], v[140:143], v[188:191], v[38:41]
	v_mfma_f32_16x16x32_bf16 v[34:37], v[148:151], v[188:191], v[34:37]
	v_mfma_f32_16x16x32_bf16 v[22:25], v[140:143], v[196:199], v[22:25]
	v_mfma_f32_16x16x32_bf16 v[18:21], v[148:151], v[196:199], v[18:21]
	v_mfma_f32_16x16x32_bf16 v[62:65], v[144:147], v[176:179], v[62:65]
	v_mfma_f32_16x16x32_bf16 v[58:61], v[152:155], v[176:179], v[58:61]
	v_mfma_f32_16x16x32_bf16 v[54:57], v[144:147], v[184:187], v[54:57]
	v_mfma_f32_16x16x32_bf16 v[50:53], v[152:155], v[184:187], v[50:53]
	v_mfma_f32_16x16x32_bf16 v[38:41], v[144:147], v[192:195], v[38:41]
	v_mfma_f32_16x16x32_bf16 v[34:37], v[152:155], v[192:195], v[34:37]
	v_mfma_f32_16x16x32_bf16 v[22:25], v[144:147], v[208:211], v[22:25]
	v_mfma_f32_16x16x32_bf16 v[18:21], v[152:155], v[208:211], v[18:21]
	v_mfma_f32_16x16x32_bf16 v[46:49], v[156:159], v[172:175], v[46:49]
	v_mfma_f32_16x16x32_bf16 v[42:45], v[164:167], v[172:175], v[42:45]
	v_mfma_f32_16x16x32_bf16 v[30:33], v[156:159], v[180:183], v[30:33]
	v_mfma_f32_16x16x32_bf16 v[26:29], v[164:167], v[180:183], v[26:29]
	v_mfma_f32_16x16x32_bf16 v[14:17], v[156:159], v[188:191], v[14:17]
	v_mfma_f32_16x16x32_bf16 v[10:13], v[164:167], v[188:191], v[10:13]
	v_mfma_f32_16x16x32_bf16 v[6:9], v[156:159], v[196:199], v[6:9]
	v_mfma_f32_16x16x32_bf16 v[2:5], v[164:167], v[196:199], v[2:5]
	v_mfma_f32_16x16x32_bf16 v[46:49], v[160:163], v[176:179], v[46:49]
	v_mfma_f32_16x16x32_bf16 v[42:45], v[168:171], v[176:179], v[42:45]
	v_mfma_f32_16x16x32_bf16 v[30:33], v[160:163], v[184:187], v[30:33]
	v_mfma_f32_16x16x32_bf16 v[26:29], v[168:171], v[184:187], v[26:29]
	v_mfma_f32_16x16x32_bf16 v[14:17], v[160:163], v[192:195], v[14:17]
	v_mfma_f32_16x16x32_bf16 v[10:13], v[168:171], v[192:195], v[10:13]
	v_mfma_f32_16x16x32_bf16 v[6:9], v[160:163], v[208:211], v[6:9]
	v_mfma_f32_16x16x32_bf16 v[2:5], v[168:171], v[208:211], v[2:5]
	s_barrier
	s_setprio 0
	s_add_i32 s49, s49, 2
	s_add_u32 s18, s18, 0x100
	s_addc_u32 s19, s19, 0
	s_add_u32 s9, s9, 0x100
	s_addc_u32 s11, s11, 0
	s_cmp_gt_u32 s49, 5
	s_cbranch_scc0 .LBB0_712
	s_and_b64 vcc, exec, s[6:7]
	s_cbranch_vccz .LBB0_715
	s_barrier

.LBB0_837:
	s_add_u32 s0, s18, 0xfff80080
	s_addc_u32 s1, s19, -1
	s_add_i32 s33, 0, 0x10000
	s_cmp_eq_u32 s59, 28
	s_cselect_b32 s23, s11, s1
	s_cselect_b32 s22, s38, s0
	s_cselect_b32 s21, s9, s58
	s_cselect_b32 s20, s39, s49
	s_add_i32 s55, 0, 0x14000
	ds_read_b128 v[146:149], v143
	ds_read_b128 v[150:153], v143 offset:1024
	ds_read_b128 v[154:157], v143 offset:2048
	ds_read_b128 v[158:161], v143 offset:3072
	ds_read_b128 v[162:165], v143 offset:16384
	ds_read_b128 v[166:169], v143 offset:17408
	ds_read_b128 v[170:173], v143 offset:18432
	ds_read_b128 v[174:177], v143 offset:19456
	s_add_i32 m0, s27, 0xc000
	ds_read_b128 v[178:181], v145
	ds_read_b128 v[182:185], v145 offset:1024
	ds_read_b128 v[186:189], v145 offset:2048
	ds_read_b128 v[190:193], v145 offset:3072
	ds_read_b128 v[194:197], v145 offset:4096
	ds_read_b128 v[198:201], v145 offset:5120
	ds_read_b128 v[208:211], v145 offset:6144
	ds_read_b128 v[212:215], v145 offset:7168
	global_load_lds_dwordx4 v136, s[18:19]
	s_add_i32 m0, s27, 0xe000
	s_nop 0
	global_load_lds_dwordx4 v138, s[18:19]
	s_waitcnt vmcnt(8)
	s_waitcnt lgkmcnt(0)
	s_setprio 1
	s_barrier
	v_mfma_f32_16x16x32_bf16 v[126:129], v[146:149], v[178:181], v[126:129]
	v_mfma_f32_16x16x32_bf16 v[118:121], v[154:157], v[178:181], v[118:121]
	v_mfma_f32_16x16x32_bf16 v[110:113], v[146:149], v[186:189], v[110:113]
	v_mfma_f32_16x16x32_bf16 v[102:105], v[154:157], v[186:189], v[102:105]
	v_mfma_f32_16x16x32_bf16 v[94:97], v[146:149], v[194:197], v[94:97]
	v_mfma_f32_16x16x32_bf16 v[86:89], v[154:157], v[194:197], v[86:89]
	v_mfma_f32_16x16x32_bf16 v[78:81], v[146:149], v[208:211], v[78:81]
	v_mfma_f32_16x16x32_bf16 v[70:73], v[154:157], v[208:211], v[70:73]
	v_mfma_f32_16x16x32_bf16 v[126:129], v[150:153], v[182:185], v[126:129]
	v_mfma_f32_16x16x32_bf16 v[118:121], v[158:161], v[182:185], v[118:121]
	v_mfma_f32_16x16x32_bf16 v[110:113], v[150:153], v[190:193], v[110:113]
	v_mfma_f32_16x16x32_bf16 v[102:105], v[158:161], v[190:193], v[102:105]
	v_mfma_f32_16x16x32_bf16 v[94:97], v[150:153], v[198:201], v[94:97]
	v_mfma_f32_16x16x32_bf16 v[86:89], v[158:161], v[198:201], v[86:89]
	v_mfma_f32_16x16x32_bf16 v[78:81], v[150:153], v[212:215], v[78:81]
	v_mfma_f32_16x16x32_bf16 v[70:73], v[158:161], v[212:215], v[70:73]
	v_mfma_f32_16x16x32_bf16 v[122:125], v[162:165], v[178:181], v[122:125]
	v_mfma_f32_16x16x32_bf16 v[114:117], v[170:173], v[178:181], v[114:117]
	v_mfma_f32_16x16x32_bf16 v[106:109], v[162:165], v[186:189], v[106:109]
	v_mfma_f32_16x16x32_bf16 v[98:101], v[170:173], v[186:189], v[98:101]
	v_mfma_f32_16x16x32_bf16 v[90:93], v[162:165], v[194:197], v[90:93]
	v_mfma_f32_16x16x32_bf16 v[82:85], v[170:173], v[194:197], v[82:85]
	v_mfma_f32_16x16x32_bf16 v[74:77], v[162:165], v[208:211], v[74:77]
	v_mfma_f32_16x16x32_bf16 v[66:69], v[170:173], v[208:211], v[66:69]
	v_mfma_f32_16x16x32_bf16 v[122:125], v[166:169], v[182:185], v[122:125]
	v_mfma_f32_16x16x32_bf16 v[114:117], v[174:177], v[182:185], v[114:117]
	v_mfma_f32_16x16x32_bf16 v[106:109], v[166:169], v[190:193], v[106:109]
	v_mfma_f32_16x16x32_bf16 v[98:101], v[174:177], v[190:193], v[98:101]
	v_mfma_f32_16x16x32_bf16 v[90:93], v[166:169], v[198:201], v[90:93]
	v_mfma_f32_16x16x32_bf16 v[82:85], v[174:177], v[198:201], v[82:85]
	v_mfma_f32_16x16x32_bf16 v[74:77], v[166:169], v[212:215], v[74:77]
	v_mfma_f32_16x16x32_bf16 v[66:69], v[174:177], v[212:215], v[66:69]
	s_barrier
	s_setprio 0
	s_add_i32 s0, s33, s26
	s_mov_b32 m0, s0
	ds_read_b128 v[178:181], v145 offset:16384
	ds_read_b128 v[182:185], v145 offset:17408
	ds_read_b128 v[186:189], v145 offset:18432
	ds_read_b128 v[190:193], v145 offset:19456
	ds_read_b128 v[194:197], v145 offset:20480
	ds_read_b128 v[198:201], v145 offset:21504
	ds_read_b128 v[208:211], v145 offset:22528
	ds_read_b128 v[212:215], v145 offset:23552
	global_load_lds_dwordx4 v202, s[20:21]
	s_add_i32 m0, s0, 0x2000
	s_add_u32 s0, s20, 0x80000
	s_addc_u32 s1, s21, 0
	s_add_i32 s33, s55, s26
	global_load_lds_dwordx4 v130, s[20:21]
	s_mov_b32 m0, s33
	s_nop 0
	global_load_lds_dwordx4 v202, s[0:1]
	s_add_i32 m0, s33, 0x2000
	s_nop 0
	global_load_lds_dwordx4 v130, s[0:1]
	s_mov_b32 m0, s27
	s_nop 0
	global_load_lds_dwordx4 v134, s[22:23]
	s_mov_b32 m0, s28
	s_nop 0
	global_load_lds_dwordx4 v132, s[22:23]
	s_waitcnt vmcnt(8)
	s_waitcnt lgkmcnt(0)
	s_setprio 1
	s_barrier
	v_mfma_f32_16x16x32_bf16 v[62:65], v[146:149], v[178:181], v[62:65]
	v_mfma_f32_16x16x32_bf16 v[54:57], v[154:157], v[178:181], v[54:57]
	v_mfma_f32_16x16x32_bf16 v[46:49], v[146:149], v[186:189], v[46:49]
	v_mfma_f32_16x16x32_bf16 v[38:41], v[154:157], v[186:189], v[38:41]
	v_mfma_f32_16x16x32_bf16 v[30:33], v[146:149], v[194:197], v[30:33]
	v_mfma_f32_16x16x32_bf16 v[22:25], v[154:157], v[194:197], v[22:25]
	v_mfma_f32_16x16x32_bf16 v[14:17], v[146:149], v[208:211], v[14:17]
	v_mfma_f32_16x16x32_bf16 v[6:9], v[154:157], v[208:211], v[6:9]
	v_mfma_f32_16x16x32_bf16 v[62:65], v[150:153], v[182:185], v[62:65]
	v_mfma_f32_16x16x32_bf16 v[54:57], v[158:161], v[182:185], v[54:57]
	v_mfma_f32_16x16x32_bf16 v[46:49], v[150:153], v[190:193], v[46:49]
	v_mfma_f32_16x16x32_bf16 v[38:41], v[158:161], v[190:193], v[38:41]
	v_mfma_f32_16x16x32_bf16 v[30:33], v[150:153], v[198:201], v[30:33]
	v_mfma_f32_16x16x32_bf16 v[22:25], v[158:161], v[198:201], v[22:25]
	v_mfma_f32_16x16x32_bf16 v[14:17], v[150:153], v[212:215], v[14:17]
	v_mfma_f32_16x16x32_bf16 v[6:9], v[158:161], v[212:215], v[6:9]
	v_mfma_f32_16x16x32_bf16 v[58:61], v[162:165], v[178:181], v[58:61]
	v_mfma_f32_16x16x32_bf16 v[50:53], v[170:173], v[178:181], v[50:53]
	v_mfma_f32_16x16x32_bf16 v[42:45], v[162:165], v[186:189], v[42:45]
	v_mfma_f32_16x16x32_bf16 v[34:37], v[170:173], v[186:189], v[34:37]
	v_mfma_f32_16x16x32_bf16 v[26:29], v[162:165], v[194:197], v[26:29]
	v_mfma_f32_16x16x32_bf16 v[18:21], v[170:173], v[194:197], v[18:21]
	v_mfma_f32_16x16x32_bf16 v[10:13], v[162:165], v[208:211], v[10:13]
	v_mfma_f32_16x16x32_bf16 v[2:5], v[170:173], v[208:211], v[2:5]
	v_mfma_f32_16x16x32_bf16 v[58:61], v[166:169], v[182:185], v[58:61]
	v_mfma_f32_16x16x32_bf16 v[50:53], v[174:177], v[182:185], v[50:53]
	v_mfma_f32_16x16x32_bf16 v[42:45], v[166:169], v[190:193], v[42:45]
	v_mfma_f32_16x16x32_bf16 v[34:37], v[174:177], v[190:193], v[34:37]
	v_mfma_f32_16x16x32_bf16 v[26:29], v[166:169], v[198:201], v[26:29]
	v_mfma_f32_16x16x32_bf16 v[18:21], v[174:177], v[198:201], v[18:21]
	v_mfma_f32_16x16x32_bf16 v[10:13], v[166:169], v[212:215], v[10:13]
	v_mfma_f32_16x16x32_bf16 v[2:5], v[174:177], v[212:215], v[2:5]
	s_barrier
	s_setprio 0
	s_add_i32 s33, 0, 0x18000
	s_add_i32 s55, 0, 0x1c000
	ds_read_b128 v[146:149], v143 offset:32768
	ds_read_b128 v[150:153], v143 offset:33792
	ds_read_b128 v[154:157], v143 offset:34816
	ds_read_b128 v[158:161], v143 offset:35840
	ds_read_b128 v[162:165], v143 offset:49152
	ds_read_b128 v[166:169], v143 offset:50176
	ds_read_b128 v[170:173], v143 offset:51200
	ds_read_b128 v[174:177], v143 offset:52224
	s_add_u32 s0, s22, 0x80000
	s_addc_u32 s1, s23, 0
	s_mov_b32 m0, s29
	ds_read_b128 v[178:181], v145 offset:32768
	ds_read_b128 v[182:185], v145 offset:33792
	ds_read_b128 v[186:189], v145 offset:34816
	ds_read_b128 v[190:193], v145 offset:35840
	ds_read_b128 v[194:197], v145 offset:36864
	ds_read_b128 v[198:201], v145 offset:37888
	ds_read_b128 v[208:211], v145 offset:38912
	ds_read_b128 v[212:215], v145 offset:39936
	global_load_lds_dwordx4 v134, s[0:1]
	s_mov_b32 m0, s30
	s_nop 0
	global_load_lds_dwordx4 v132, s[0:1]
	s_waitcnt vmcnt(8)
	s_waitcnt lgkmcnt(0)
	s_setprio 1
	s_barrier
	v_mfma_f32_16x16x32_bf16 v[126:129], v[146:149], v[178:181], v[126:129]
	v_mfma_f32_16x16x32_bf16 v[118:121], v[154:157], v[178:181], v[118:121]
	v_mfma_f32_16x16x32_bf16 v[110:113], v[146:149], v[186:189], v[110:113]
	v_mfma_f32_16x16x32_bf16 v[102:105], v[154:157], v[186:189], v[102:105]
	v_mfma_f32_16x16x32_bf16 v[94:97], v[146:149], v[194:197], v[94:97]
	v_mfma_f32_16x16x32_bf16 v[86:89], v[154:157], v[194:197], v[86:89]
	v_mfma_f32_16x16x32_bf16 v[78:81], v[146:149], v[208:211], v[78:81]
	v_mfma_f32_16x16x32_bf16 v[70:73], v[154:157], v[208:211], v[70:73]
	v_mfma_f32_16x16x32_bf16 v[126:129], v[150:153], v[182:185], v[126:129]
	v_mfma_f32_16x16x32_bf16 v[118:121], v[158:161], v[182:185], v[118:121]
	v_mfma_f32_16x16x32_bf16 v[110:113], v[150:153], v[190:193], v[110:113]
	v_mfma_f32_16x16x32_bf16 v[102:105], v[158:161], v[190:193], v[102:105]
	v_mfma_f32_16x16x32_bf16 v[94:97], v[150:153], v[198:201], v[94:97]
	v_mfma_f32_16x16x32_bf16 v[86:89], v[158:161], v[198:201], v[86:89]
	v_mfma_f32_16x16x32_bf16 v[78:81], v[150:153], v[212:215], v[78:81]
	v_mfma_f32_16x16x32_bf16 v[70:73], v[158:161], v[212:215], v[70:73]
	v_mfma_f32_16x16x32_bf16 v[122:125], v[162:165], v[178:181], v[122:125]
	v_mfma_f32_16x16x32_bf16 v[114:117], v[170:173], v[178:181], v[114:117]
	v_mfma_f32_16x16x32_bf16 v[106:109], v[162:165], v[186:189], v[106:109]
	v_mfma_f32_16x16x32_bf16 v[98:101], v[170:173], v[186:189], v[98:101]
	v_mfma_f32_16x16x32_bf16 v[90:93], v[162:165], v[194:197], v[90:93]
	v_mfma_f32_16x16x32_bf16 v[82:85], v[170:173], v[194:197], v[82:85]
	v_mfma_f32_16x16x32_bf16 v[74:77], v[162:165], v[208:211], v[74:77]
	v_mfma_f32_16x16x32_bf16 v[66:69], v[170:173], v[208:211], v[66:69]
	v_mfma_f32_16x16x32_bf16 v[122:125], v[166:169], v[182:185], v[122:125]
	v_mfma_f32_16x16x32_bf16 v[114:117], v[174:177], v[182:185], v[114:117]
	v_mfma_f32_16x16x32_bf16 v[106:109], v[166:169], v[190:193], v[106:109]
	v_mfma_f32_16x16x32_bf16 v[98:101], v[174:177], v[190:193], v[98:101]
	v_mfma_f32_16x16x32_bf16 v[90:93], v[166:169], v[198:201], v[90:93]
	v_mfma_f32_16x16x32_bf16 v[82:85], v[174:177], v[198:201], v[82:85]
	v_mfma_f32_16x16x32_bf16 v[74:77], v[166:169], v[212:215], v[74:77]
	v_mfma_f32_16x16x32_bf16 v[66:69], v[174:177], v[212:215], v[66:69]
	s_barrier
	s_setprio 0
	s_add_i32 s0, s33, s26
	s_add_u32 s100, s20, 0x80
	s_addc_u32 s101, s21, 0
	s_mov_b32 m0, s0
	ds_read_b128 v[178:181], v145 offset:49152
	ds_read_b128 v[182:185], v145 offset:50176
	ds_read_b128 v[186:189], v145 offset:51200
	ds_read_b128 v[190:193], v145 offset:52224
	ds_read_b128 v[194:197], v145 offset:53248
	ds_read_b128 v[198:201], v145 offset:54272
	ds_read_b128 v[208:211], v145 offset:55296
	ds_read_b128 v[212:215], v145 offset:56320
	global_load_lds_dwordx4 v202, s[100:101]
	s_add_i32 m0, s0, 0x2000
	s_add_u32 s100, s20, 0x80
	s_addc_u32 s101, s21, 0
	s_add_u32 s0, s20, 0x80080
	s_addc_u32 s1, s21, 0
	s_add_i32 s20, s55, s26
	global_load_lds_dwordx4 v130, s[100:101]
	s_mov_b32 m0, s20
	s_nop 0
	global_load_lds_dwordx4 v202, s[0:1]
	s_add_i32 m0, s20, 0x2000
	s_nop 0
	global_load_lds_dwordx4 v130, s[0:1]
	s_add_u32 s100, s22, 0x80
	s_addc_u32 s101, s23, 0
	s_mov_b32 m0, s31
	s_nop 0
	global_load_lds_dwordx4 v134, s[100:101]
	s_add_u32 s100, s22, 0x80
	s_addc_u32 s101, s23, 0
	s_mov_b32 m0, s34
	s_nop 0
	global_load_lds_dwordx4 v132, s[100:101]
	s_waitcnt vmcnt(8)
	s_waitcnt lgkmcnt(0)
	s_setprio 1
	s_barrier
	v_mfma_f32_16x16x32_bf16 v[62:65], v[146:149], v[178:181], v[62:65]
	v_mfma_f32_16x16x32_bf16 v[54:57], v[154:157], v[178:181], v[54:57]
	v_mfma_f32_16x16x32_bf16 v[46:49], v[146:149], v[186:189], v[46:49]
	v_mfma_f32_16x16x32_bf16 v[38:41], v[154:157], v[186:189], v[38:41]
	v_mfma_f32_16x16x32_bf16 v[30:33], v[146:149], v[194:197], v[30:33]
	v_mfma_f32_16x16x32_bf16 v[22:25], v[154:157], v[194:197], v[22:25]
	v_mfma_f32_16x16x32_bf16 v[14:17], v[146:149], v[208:211], v[14:17]
	v_mfma_f32_16x16x32_bf16 v[6:9], v[154:157], v[208:211], v[6:9]
	v_mfma_f32_16x16x32_bf16 v[62:65], v[150:153], v[182:185], v[62:65]
	v_mfma_f32_16x16x32_bf16 v[54:57], v[158:161], v[182:185], v[54:57]
	v_mfma_f32_16x16x32_bf16 v[46:49], v[150:153], v[190:193], v[46:49]
	v_mfma_f32_16x16x32_bf16 v[38:41], v[158:161], v[190:193], v[38:41]
	v_mfma_f32_16x16x32_bf16 v[30:33], v[150:153], v[198:201], v[30:33]
	v_mfma_f32_16x16x32_bf16 v[22:25], v[158:161], v[198:201], v[22:25]
	v_mfma_f32_16x16x32_bf16 v[14:17], v[150:153], v[212:215], v[14:17]
	v_mfma_f32_16x16x32_bf16 v[6:9], v[158:161], v[212:215], v[6:9]
	v_mfma_f32_16x16x32_bf16 v[58:61], v[162:165], v[178:181], v[58:61]
	v_mfma_f32_16x16x32_bf16 v[50:53], v[170:173], v[178:181], v[50:53]
	v_mfma_f32_16x16x32_bf16 v[42:45], v[162:165], v[186:189], v[42:45]
	v_mfma_f32_16x16x32_bf16 v[34:37], v[170:173], v[186:189], v[34:37]
	v_mfma_f32_16x16x32_bf16 v[26:29], v[162:165], v[194:197], v[26:29]
	v_mfma_f32_16x16x32_bf16 v[18:21], v[170:173], v[194:197], v[18:21]
	v_mfma_f32_16x16x32_bf16 v[10:13], v[162:165], v[208:211], v[10:13]
	v_mfma_f32_16x16x32_bf16 v[2:5], v[170:173], v[208:211], v[2:5]
	v_mfma_f32_16x16x32_bf16 v[58:61], v[166:169], v[182:185], v[58:61]
	v_mfma_f32_16x16x32_bf16 v[50:53], v[174:177], v[182:185], v[50:53]
	v_mfma_f32_16x16x32_bf16 v[42:45], v[166:169], v[190:193], v[42:45]
	v_mfma_f32_16x16x32_bf16 v[34:37], v[174:177], v[190:193], v[34:37]
	v_mfma_f32_16x16x32_bf16 v[26:29], v[166:169], v[198:201], v[26:29]
	v_mfma_f32_16x16x32_bf16 v[18:21], v[174:177], v[198:201], v[18:21]
	v_mfma_f32_16x16x32_bf16 v[10:13], v[166:169], v[212:215], v[10:13]
	v_mfma_f32_16x16x32_bf16 v[2:5], v[174:177], v[212:215], v[2:5]
	s_barrier
	s_setprio 0
	s_add_i32 s59, s59, 2
	s_add_u32 s18, s18, 0x100
	s_addc_u32 s19, s19, 0
	s_add_u32 s49, s49, 0x100
	s_addc_u32 s58, s58, 0
	s_cmp_gt_u32 s59, 29
	s_cbranch_scc0 .LBB0_837
	s_and_b64 vcc, exec, s[6:7]
	s_cbranch_vccz .LBB0_840
	s_barrier

.LBB0_970:
	s_add_u32 s16, s2, 0x100
	s_addc_u32 s17, s3, 0
	s_add_i32 s0, 0, 0x10000
	s_cmpk_eq_i32 s59, 0x54
	s_cselect_b32 s21, s7, s17
	s_cselect_b32 s20, s6, s16
	s_cselect_b32 s19, s15, s58
	s_cselect_b32 s18, s14, s49
	s_add_i32 s33, 0, 0x14000
	ds_read_b128 v[78:81], v205
	ds_read_b128 v[82:85], v205 offset:1024
	ds_read_b128 v[94:97], v205 offset:2048
	ds_read_b128 v[98:101], v205 offset:3072
	ds_read_b128 v[106:109], v205 offset:16384
	ds_read_b128 v[110:113], v205 offset:17408
	ds_read_b128 v[126:129], v205 offset:18432
	ds_read_b128 v[134:137], v205 offset:19456
	s_add_i32 m0, s25, 0xc000
	ds_read_b128 v[146:149], v239
	ds_read_b128 v[158:161], v239 offset:1024
	ds_read_b128 v[166:169], v239 offset:2048
	ds_read_b128 v[174:177], v239 offset:3072
	ds_read_b128 v[178:181], v239 offset:4096
	ds_read_b128 v[182:185], v239 offset:5120
	ds_read_b128 v[186:189], v239 offset:6144
	ds_read_b128 v[190:193], v239 offset:7168
	global_load_lds_dwordx4 v214, s[2:3]
	s_add_i32 m0, s25, 0xe000
	s_nop 0
	global_load_lds_dwordx4 v216, s[2:3]
	s_waitcnt vmcnt(8)
	s_waitcnt lgkmcnt(0)
	s_setprio 1
	s_barrier
	v_mfma_f32_16x16x32_bf16 v[170:173], v[78:81], v[146:149], v[170:173]
	v_mfma_f32_16x16x32_bf16 v[162:165], v[94:97], v[146:149], v[162:165]
	v_mfma_f32_16x16x32_bf16 v[142:145], v[78:81], v[166:169], v[142:145]
	v_mfma_f32_16x16x32_bf16 v[138:141], v[94:97], v[166:169], v[138:141]
	v_mfma_f32_16x16x32_bf16 v[118:121], v[78:81], v[178:181], v[118:121]
	v_mfma_f32_16x16x32_bf16 v[114:117], v[94:97], v[178:181], v[114:117]
	v_mfma_f32_16x16x32_bf16 v[86:89], v[78:81], v[186:189], v[86:89]
	v_mfma_f32_16x16x32_bf16 v[74:77], v[94:97], v[186:189], v[74:77]
	v_mfma_f32_16x16x32_bf16 v[170:173], v[82:85], v[158:161], v[170:173]
	v_mfma_f32_16x16x32_bf16 v[162:165], v[98:101], v[158:161], v[162:165]
	v_mfma_f32_16x16x32_bf16 v[142:145], v[82:85], v[174:177], v[142:145]
	v_mfma_f32_16x16x32_bf16 v[138:141], v[98:101], v[174:177], v[138:141]
	v_mfma_f32_16x16x32_bf16 v[118:121], v[82:85], v[182:185], v[118:121]
	v_mfma_f32_16x16x32_bf16 v[114:117], v[98:101], v[182:185], v[114:117]
	v_mfma_f32_16x16x32_bf16 v[86:89], v[82:85], v[190:193], v[86:89]
	v_mfma_f32_16x16x32_bf16 v[74:77], v[98:101], v[190:193], v[74:77]
	v_mfma_f32_16x16x32_bf16 v[154:157], v[106:109], v[146:149], v[154:157]
	v_mfma_f32_16x16x32_bf16 v[130:133], v[106:109], v[166:169], v[130:133]
	v_mfma_f32_16x16x32_bf16 v[122:125], v[126:129], v[166:169], v[122:125]
	v_mfma_f32_16x16x32_bf16 v[102:105], v[106:109], v[178:181], v[102:105]
	v_mfma_f32_16x16x32_bf16 v[90:93], v[126:129], v[178:181], v[90:93]
	v_mfma_f32_16x16x32_bf16 v[70:73], v[106:109], v[186:189], v[70:73]
	v_mfma_f32_16x16x32_bf16 v[66:69], v[126:129], v[186:189], v[66:69]
	v_mfma_f32_16x16x32_bf16 v[154:157], v[110:113], v[158:161], v[154:157]
	v_mfma_f32_16x16x32_bf16 v[146:149], v[126:129], v[146:149], v[150:153]
	v_mfma_f32_16x16x32_bf16 v[130:133], v[110:113], v[174:177], v[130:133]
	v_mfma_f32_16x16x32_bf16 v[122:125], v[134:137], v[174:177], v[122:125]
	v_mfma_f32_16x16x32_bf16 v[102:105], v[110:113], v[182:185], v[102:105]
	v_mfma_f32_16x16x32_bf16 v[90:93], v[134:137], v[182:185], v[90:93]
	v_mfma_f32_16x16x32_bf16 v[70:73], v[110:113], v[190:193], v[70:73]
	v_mfma_f32_16x16x32_bf16 v[66:69], v[134:137], v[190:193], v[66:69]
	v_mfma_f32_16x16x32_bf16 v[146:149], v[134:137], v[158:161], v[146:149]
	s_barrier
	s_setprio 0
	s_add_i32 s0, s0, s24
	s_mov_b32 m0, s0
	ds_read_b128 v[150:153], v239 offset:16384
	ds_read_b128 v[158:161], v239 offset:17408
	ds_read_b128 v[166:169], v239 offset:18432
	ds_read_b128 v[174:177], v239 offset:19456
	ds_read_b128 v[178:181], v239 offset:20480
	ds_read_b128 v[182:185], v239 offset:21504
	ds_read_b128 v[186:189], v239 offset:22528
	ds_read_b128 v[190:193], v239 offset:23552
	global_load_lds_dwordx4 v202, s[18:19]
	s_add_i32 m0, s0, 0x2000
	s_add_u32 s0, s18, 0x160000
	s_addc_u32 s1, s19, 0
	s_add_i32 s2, s33, s24
	global_load_lds_dwordx4 v208, s[18:19]
	s_mov_b32 m0, s2
	s_nop 0
	global_load_lds_dwordx4 v202, s[0:1]
	s_add_i32 m0, s2, 0x2000
	s_nop 0
	global_load_lds_dwordx4 v208, s[0:1]
	s_mov_b32 m0, s25
	s_nop 0
	global_load_lds_dwordx4 v212, s[20:21]
	s_mov_b32 m0, s26
	s_nop 0
	global_load_lds_dwordx4 v210, s[20:21]
	s_waitcnt vmcnt(8)
	s_waitcnt lgkmcnt(0)
	s_setprio 1
	s_barrier
	v_mfma_f32_16x16x32_bf16 v[62:65], v[78:81], v[150:153], v[62:65]
	v_mfma_f32_16x16x32_bf16 v[58:61], v[94:97], v[150:153], v[58:61]
	v_mfma_f32_16x16x32_bf16 v[46:49], v[78:81], v[166:169], v[46:49]
	v_mfma_f32_16x16x32_bf16 v[42:45], v[94:97], v[166:169], v[42:45]
	v_mfma_f32_16x16x32_bf16 v[30:33], v[78:81], v[178:181], v[30:33]
	v_mfma_f32_16x16x32_bf16 v[26:29], v[94:97], v[178:181], v[26:29]
	v_mfma_f32_16x16x32_bf16 v[14:17], v[78:81], v[186:189], v[14:17]
	v_mfma_f32_16x16x32_bf16 v[10:13], v[94:97], v[186:189], v[10:13]
	v_mfma_f32_16x16x32_bf16 v[62:65], v[82:85], v[158:161], v[62:65]
	v_mfma_f32_16x16x32_bf16 v[58:61], v[98:101], v[158:161], v[58:61]
	v_mfma_f32_16x16x32_bf16 v[46:49], v[82:85], v[174:177], v[46:49]
	v_mfma_f32_16x16x32_bf16 v[42:45], v[98:101], v[174:177], v[42:45]
	v_mfma_f32_16x16x32_bf16 v[30:33], v[82:85], v[182:185], v[30:33]
	v_mfma_f32_16x16x32_bf16 v[26:29], v[98:101], v[182:185], v[26:29]
	v_mfma_f32_16x16x32_bf16 v[14:17], v[82:85], v[190:193], v[14:17]
	v_mfma_f32_16x16x32_bf16 v[10:13], v[98:101], v[190:193], v[10:13]
	v_mfma_f32_16x16x32_bf16 v[54:57], v[106:109], v[150:153], v[54:57]
	v_mfma_f32_16x16x32_bf16 v[50:53], v[126:129], v[150:153], v[50:53]
	v_mfma_f32_16x16x32_bf16 v[38:41], v[106:109], v[166:169], v[38:41]
	v_mfma_f32_16x16x32_bf16 v[34:37], v[126:129], v[166:169], v[34:37]
	v_mfma_f32_16x16x32_bf16 v[22:25], v[106:109], v[178:181], v[22:25]
	v_mfma_f32_16x16x32_bf16 v[18:21], v[126:129], v[178:181], v[18:21]
	v_mfma_f32_16x16x32_bf16 v[6:9], v[106:109], v[186:189], v[6:9]
	v_mfma_f32_16x16x32_bf16 v[2:5], v[126:129], v[186:189], v[2:5]
	v_mfma_f32_16x16x32_bf16 v[54:57], v[110:113], v[158:161], v[54:57]
	v_mfma_f32_16x16x32_bf16 v[50:53], v[134:137], v[158:161], v[50:53]
	v_mfma_f32_16x16x32_bf16 v[38:41], v[110:113], v[174:177], v[38:41]
	v_mfma_f32_16x16x32_bf16 v[34:37], v[134:137], v[174:177], v[34:37]
	v_mfma_f32_16x16x32_bf16 v[22:25], v[110:113], v[182:185], v[22:25]
	v_mfma_f32_16x16x32_bf16 v[18:21], v[134:137], v[182:185], v[18:21]
	v_mfma_f32_16x16x32_bf16 v[6:9], v[110:113], v[190:193], v[6:9]
	v_mfma_f32_16x16x32_bf16 v[2:5], v[134:137], v[190:193], v[2:5]
	s_barrier
	s_setprio 0
	s_add_i32 s2, 0, 0x18000
	s_add_i32 s3, 0, 0x1c000
	ds_read_b128 v[78:81], v205 offset:32768
	ds_read_b128 v[82:85], v205 offset:33792
	ds_read_b128 v[94:97], v205 offset:34816
	ds_read_b128 v[98:101], v205 offset:35840
	ds_read_b128 v[106:109], v205 offset:49152
	ds_read_b128 v[110:113], v205 offset:50176
	ds_read_b128 v[126:129], v205 offset:51200
	ds_read_b128 v[134:137], v205 offset:52224
	s_add_u32 s0, s20, 0x160000
	s_addc_u32 s1, s21, 0
	s_mov_b32 m0, s27
	ds_read_b128 v[150:153], v239 offset:32768
	ds_read_b128 v[158:161], v239 offset:33792
	ds_read_b128 v[166:169], v239 offset:34816
	ds_read_b128 v[174:177], v239 offset:35840
	ds_read_b128 v[178:181], v239 offset:36864
	ds_read_b128 v[182:185], v239 offset:37888
	ds_read_b128 v[186:189], v239 offset:38912
	ds_read_b128 v[190:193], v239 offset:39936
	global_load_lds_dwordx4 v212, s[0:1]
	s_mov_b32 m0, s28
	s_nop 0
	global_load_lds_dwordx4 v210, s[0:1]
	s_waitcnt vmcnt(8)
	s_waitcnt lgkmcnt(0)
	s_setprio 1
	s_barrier
	v_mfma_f32_16x16x32_bf16 v[170:173], v[78:81], v[150:153], v[170:173]
	v_mfma_f32_16x16x32_bf16 v[162:165], v[94:97], v[150:153], v[162:165]
	v_mfma_f32_16x16x32_bf16 v[142:145], v[78:81], v[166:169], v[142:145]
	v_mfma_f32_16x16x32_bf16 v[138:141], v[94:97], v[166:169], v[138:141]
	v_mfma_f32_16x16x32_bf16 v[118:121], v[78:81], v[178:181], v[118:121]
	v_mfma_f32_16x16x32_bf16 v[114:117], v[94:97], v[178:181], v[114:117]
	v_mfma_f32_16x16x32_bf16 v[86:89], v[78:81], v[186:189], v[86:89]
	v_mfma_f32_16x16x32_bf16 v[74:77], v[94:97], v[186:189], v[74:77]
	v_mfma_f32_16x16x32_bf16 v[170:173], v[82:85], v[158:161], v[170:173]
	v_mfma_f32_16x16x32_bf16 v[162:165], v[98:101], v[158:161], v[162:165]
	v_mfma_f32_16x16x32_bf16 v[142:145], v[82:85], v[174:177], v[142:145]
	v_mfma_f32_16x16x32_bf16 v[138:141], v[98:101], v[174:177], v[138:141]
	v_mfma_f32_16x16x32_bf16 v[118:121], v[82:85], v[182:185], v[118:121]
	v_mfma_f32_16x16x32_bf16 v[114:117], v[98:101], v[182:185], v[114:117]
	v_mfma_f32_16x16x32_bf16 v[86:89], v[82:85], v[190:193], v[86:89]
	v_mfma_f32_16x16x32_bf16 v[74:77], v[98:101], v[190:193], v[74:77]
	v_mfma_f32_16x16x32_bf16 v[154:157], v[106:109], v[150:153], v[154:157]
	v_mfma_f32_16x16x32_bf16 v[146:149], v[126:129], v[150:153], v[146:149]
	v_mfma_f32_16x16x32_bf16 v[130:133], v[106:109], v[166:169], v[130:133]
	v_mfma_f32_16x16x32_bf16 v[122:125], v[126:129], v[166:169], v[122:125]
	v_mfma_f32_16x16x32_bf16 v[102:105], v[106:109], v[178:181], v[102:105]
	v_mfma_f32_16x16x32_bf16 v[90:93], v[126:129], v[178:181], v[90:93]
	v_mfma_f32_16x16x32_bf16 v[70:73], v[106:109], v[186:189], v[70:73]
	v_mfma_f32_16x16x32_bf16 v[66:69], v[126:129], v[186:189], v[66:69]
	v_mfma_f32_16x16x32_bf16 v[154:157], v[110:113], v[158:161], v[154:157]
	v_mfma_f32_16x16x32_bf16 v[150:153], v[134:137], v[158:161], v[146:149]
	v_mfma_f32_16x16x32_bf16 v[130:133], v[110:113], v[174:177], v[130:133]
	v_mfma_f32_16x16x32_bf16 v[122:125], v[134:137], v[174:177], v[122:125]
	v_mfma_f32_16x16x32_bf16 v[102:105], v[110:113], v[182:185], v[102:105]
	v_mfma_f32_16x16x32_bf16 v[90:93], v[134:137], v[182:185], v[90:93]
	v_mfma_f32_16x16x32_bf16 v[70:73], v[110:113], v[190:193], v[70:73]
	v_mfma_f32_16x16x32_bf16 v[66:69], v[134:137], v[190:193], v[66:69]
	s_barrier
	s_setprio 0
	s_add_i32 s0, s2, s24
	s_add_u32 s100, s18, 0x80
	s_addc_u32 s101, s19, 0
	s_mov_b32 m0, s0
	ds_read_b128 v[146:149], v239 offset:49152
	ds_read_b128 v[158:161], v239 offset:50176
	ds_read_b128 v[166:169], v239 offset:51200
	ds_read_b128 v[174:177], v239 offset:52224
	ds_read_b128 v[178:181], v239 offset:53248
	ds_read_b128 v[182:185], v239 offset:54272
	ds_read_b128 v[186:189], v239 offset:55296
	ds_read_b128 v[190:193], v239 offset:56320
	global_load_lds_dwordx4 v202, s[100:101]
	s_add_i32 m0, s0, 0x2000
	s_add_u32 s100, s18, 0x80
	s_addc_u32 s101, s19, 0
	s_add_u32 s0, s18, 0x160080
	s_addc_u32 s1, s19, 0
	s_add_i32 s2, s3, s24
	global_load_lds_dwordx4 v208, s[100:101]
	s_mov_b32 m0, s2
	s_nop 0
	global_load_lds_dwordx4 v202, s[0:1]
	s_add_i32 m0, s2, 0x2000
	s_nop 0
	global_load_lds_dwordx4 v208, s[0:1]
	s_add_u32 s100, s20, 0x80
	s_addc_u32 s101, s21, 0
	s_mov_b32 m0, s31
	s_nop 0
	global_load_lds_dwordx4 v212, s[100:101]
	s_add_u32 s100, s20, 0x80
	s_addc_u32 s101, s21, 0
	s_mov_b32 m0, s34
	s_nop 0
	global_load_lds_dwordx4 v210, s[100:101]
	s_waitcnt vmcnt(8)
	s_waitcnt lgkmcnt(0)
	s_setprio 1
	s_barrier
	v_mfma_f32_16x16x32_bf16 v[62:65], v[78:81], v[146:149], v[62:65]
	v_mfma_f32_16x16x32_bf16 v[58:61], v[94:97], v[146:149], v[58:61]
	v_mfma_f32_16x16x32_bf16 v[46:49], v[78:81], v[166:169], v[46:49]
	v_mfma_f32_16x16x32_bf16 v[42:45], v[94:97], v[166:169], v[42:45]
	v_mfma_f32_16x16x32_bf16 v[30:33], v[78:81], v[178:181], v[30:33]
	v_mfma_f32_16x16x32_bf16 v[26:29], v[94:97], v[178:181], v[26:29]
	v_mfma_f32_16x16x32_bf16 v[14:17], v[78:81], v[186:189], v[14:17]
	v_mfma_f32_16x16x32_bf16 v[10:13], v[94:97], v[186:189], v[10:13]
	v_mfma_f32_16x16x32_bf16 v[62:65], v[82:85], v[158:161], v[62:65]
	v_mfma_f32_16x16x32_bf16 v[58:61], v[98:101], v[158:161], v[58:61]
	v_mfma_f32_16x16x32_bf16 v[46:49], v[82:85], v[174:177], v[46:49]
	v_mfma_f32_16x16x32_bf16 v[42:45], v[98:101], v[174:177], v[42:45]
	v_mfma_f32_16x16x32_bf16 v[30:33], v[82:85], v[182:185], v[30:33]
	v_mfma_f32_16x16x32_bf16 v[26:29], v[98:101], v[182:185], v[26:29]
	v_mfma_f32_16x16x32_bf16 v[14:17], v[82:85], v[190:193], v[14:17]
	v_mfma_f32_16x16x32_bf16 v[10:13], v[98:101], v[190:193], v[10:13]
	v_mfma_f32_16x16x32_bf16 v[54:57], v[106:109], v[146:149], v[54:57]
	v_mfma_f32_16x16x32_bf16 v[50:53], v[126:129], v[146:149], v[50:53]
	v_mfma_f32_16x16x32_bf16 v[38:41], v[106:109], v[166:169], v[38:41]
	v_mfma_f32_16x16x32_bf16 v[34:37], v[126:129], v[166:169], v[34:37]
	v_mfma_f32_16x16x32_bf16 v[22:25], v[106:109], v[178:181], v[22:25]
	v_mfma_f32_16x16x32_bf16 v[18:21], v[126:129], v[178:181], v[18:21]
	v_mfma_f32_16x16x32_bf16 v[6:9], v[106:109], v[186:189], v[6:9]
	v_mfma_f32_16x16x32_bf16 v[2:5], v[126:129], v[186:189], v[2:5]
	v_mfma_f32_16x16x32_bf16 v[54:57], v[110:113], v[158:161], v[54:57]
	v_mfma_f32_16x16x32_bf16 v[50:53], v[134:137], v[158:161], v[50:53]
	v_mfma_f32_16x16x32_bf16 v[38:41], v[110:113], v[174:177], v[38:41]
	v_mfma_f32_16x16x32_bf16 v[34:37], v[134:137], v[174:177], v[34:37]
	v_mfma_f32_16x16x32_bf16 v[22:25], v[110:113], v[182:185], v[22:25]
	v_mfma_f32_16x16x32_bf16 v[18:21], v[134:137], v[182:185], v[18:21]
	v_mfma_f32_16x16x32_bf16 v[6:9], v[110:113], v[190:193], v[6:9]
	v_mfma_f32_16x16x32_bf16 v[2:5], v[134:137], v[190:193], v[2:5]
	s_barrier
	s_setprio 0
	s_add_i32 s59, s59, 2
	s_add_u32 s49, s49, 0x100
	s_addc_u32 s58, s58, 0
	s_cmpk_gt_u32 s59, 0x55
	s_mov_b64 s[2:3], s[16:17]
	s_cbranch_scc0 .LBB0_970
	s_and_b64 vcc, exec, s[10:11]
	s_cbranch_vccz .LBB0_973
	s_barrier

.LBB0_990:
	s_add_u32 s4, s2, 0x100
	s_addc_u32 s5, s3, 0
	s_add_i32 s0, 0, 0x10000
	s_cmp_eq_u32 s59, 4
	s_cselect_b32 s21, s15, s5
	s_cselect_b32 s20, s14, s4
	s_cselect_b32 s19, s17, s58
	s_cselect_b32 s18, s16, s49
	s_add_i32 s33, 0, 0x14000
	ds_read_b128 v[140:143], v136
	ds_read_b128 v[144:147], v136 offset:1024
	ds_read_b128 v[148:151], v136 offset:2048
	ds_read_b128 v[152:155], v136 offset:3072
	ds_read_b128 v[156:159], v136 offset:16384
	ds_read_b128 v[160:163], v136 offset:17408
	ds_read_b128 v[164:167], v136 offset:18432
	ds_read_b128 v[168:171], v136 offset:19456
	s_add_i32 m0, s25, 0xc000
	ds_read_b128 v[172:175], v139
	ds_read_b128 v[176:179], v139 offset:1024
	ds_read_b128 v[180:183], v139 offset:2048
	ds_read_b128 v[184:187], v139 offset:3072
	ds_read_b128 v[188:191], v139 offset:4096
	ds_read_b128 v[192:195], v139 offset:5120
	ds_read_b128 v[196:199], v139 offset:6144
	ds_read_b128 v[208:211], v139 offset:7168
	global_load_lds_dwordx4 v132, s[2:3]
	s_add_i32 m0, s25, 0xe000
	s_nop 0
	global_load_lds_dwordx4 v134, s[2:3]
	s_waitcnt vmcnt(8)
	s_waitcnt lgkmcnt(0)
	s_setprio 1
	s_barrier
	v_mfma_f32_16x16x32_bf16 v[126:129], v[140:143], v[172:175], v[126:129]
	v_mfma_f32_16x16x32_bf16 v[122:125], v[148:151], v[172:175], v[122:125]
	v_mfma_f32_16x16x32_bf16 v[118:121], v[140:143], v[180:183], v[118:121]
	v_mfma_f32_16x16x32_bf16 v[114:117], v[148:151], v[180:183], v[114:117]
	v_mfma_f32_16x16x32_bf16 v[106:109], v[140:143], v[188:191], v[106:109]
	v_mfma_f32_16x16x32_bf16 v[98:101], v[148:151], v[188:191], v[98:101]
	v_mfma_f32_16x16x32_bf16 v[90:93], v[140:143], v[196:199], v[90:93]
	v_mfma_f32_16x16x32_bf16 v[82:85], v[148:151], v[196:199], v[82:85]
	v_mfma_f32_16x16x32_bf16 v[126:129], v[144:147], v[176:179], v[126:129]
	v_mfma_f32_16x16x32_bf16 v[122:125], v[152:155], v[176:179], v[122:125]
	v_mfma_f32_16x16x32_bf16 v[118:121], v[144:147], v[184:187], v[118:121]
	v_mfma_f32_16x16x32_bf16 v[114:117], v[152:155], v[184:187], v[114:117]
	v_mfma_f32_16x16x32_bf16 v[106:109], v[144:147], v[192:195], v[106:109]
	v_mfma_f32_16x16x32_bf16 v[98:101], v[152:155], v[192:195], v[98:101]
	v_mfma_f32_16x16x32_bf16 v[90:93], v[144:147], v[208:211], v[90:93]
	v_mfma_f32_16x16x32_bf16 v[82:85], v[152:155], v[208:211], v[82:85]
	v_mfma_f32_16x16x32_bf16 v[110:113], v[156:159], v[172:175], v[110:113]
	v_mfma_f32_16x16x32_bf16 v[102:105], v[164:167], v[172:175], v[102:105]
	v_mfma_f32_16x16x32_bf16 v[94:97], v[156:159], v[180:183], v[94:97]
	v_mfma_f32_16x16x32_bf16 v[86:89], v[164:167], v[180:183], v[86:89]
	v_mfma_f32_16x16x32_bf16 v[78:81], v[156:159], v[188:191], v[78:81]
	v_mfma_f32_16x16x32_bf16 v[74:77], v[164:167], v[188:191], v[74:77]
	v_mfma_f32_16x16x32_bf16 v[70:73], v[156:159], v[196:199], v[70:73]
	v_mfma_f32_16x16x32_bf16 v[66:69], v[164:167], v[196:199], v[66:69]
	v_mfma_f32_16x16x32_bf16 v[110:113], v[160:163], v[176:179], v[110:113]
	v_mfma_f32_16x16x32_bf16 v[102:105], v[168:171], v[176:179], v[102:105]
	v_mfma_f32_16x16x32_bf16 v[94:97], v[160:163], v[184:187], v[94:97]
	v_mfma_f32_16x16x32_bf16 v[86:89], v[168:171], v[184:187], v[86:89]
	v_mfma_f32_16x16x32_bf16 v[78:81], v[160:163], v[192:195], v[78:81]
	v_mfma_f32_16x16x32_bf16 v[74:77], v[168:171], v[192:195], v[74:77]
	v_mfma_f32_16x16x32_bf16 v[70:73], v[160:163], v[208:211], v[70:73]
	v_mfma_f32_16x16x32_bf16 v[66:69], v[168:171], v[208:211], v[66:69]
	s_barrier
	s_setprio 0
	s_add_i32 s0, s0, s24
	s_mov_b32 m0, s0
	ds_read_b128 v[172:175], v139 offset:16384
	ds_read_b128 v[176:179], v139 offset:17408
	ds_read_b128 v[180:183], v139 offset:18432
	ds_read_b128 v[184:187], v139 offset:19456
	ds_read_b128 v[188:191], v139 offset:20480
	ds_read_b128 v[192:195], v139 offset:21504
	ds_read_b128 v[196:199], v139 offset:22528
	ds_read_b128 v[208:211], v139 offset:23552
	global_load_lds_dwordx4 v202, s[18:19]
	s_add_i32 m0, s0, 0x2000
	s_add_u32 s0, s18, 0x160000
	s_addc_u32 s1, s19, 0
	s_add_i32 s2, s33, s24
	global_load_lds_dwordx4 v130, s[18:19]
	s_mov_b32 m0, s2
	s_nop 0
	global_load_lds_dwordx4 v202, s[0:1]
	s_add_i32 m0, s2, 0x2000
	s_nop 0
	global_load_lds_dwordx4 v130, s[0:1]
	s_mov_b32 m0, s25
	s_nop 0
	global_load_lds_dwordx4 v202, s[20:21]
	s_mov_b32 m0, s26
	s_nop 0
	global_load_lds_dwordx4 v130, s[20:21]
	s_waitcnt vmcnt(8)
	s_waitcnt lgkmcnt(0)
	s_setprio 1
	s_barrier
	v_mfma_f32_16x16x32_bf16 v[62:65], v[140:143], v[172:175], v[62:65]
	v_mfma_f32_16x16x32_bf16 v[58:61], v[148:151], v[172:175], v[58:61]
	v_mfma_f32_16x16x32_bf16 v[54:57], v[140:143], v[180:183], v[54:57]
	v_mfma_f32_16x16x32_bf16 v[50:53], v[148:151], v[180:183], v[50:53]
	v_mfma_f32_16x16x32_bf16 v[38:41], v[140:143], v[188:191], v[38:41]
	v_mfma_f32_16x16x32_bf16 v[34:37], v[148:151], v[188:191], v[34:37]
	v_mfma_f32_16x16x32_bf16 v[22:25], v[140:143], v[196:199], v[22:25]
	v_mfma_f32_16x16x32_bf16 v[18:21], v[148:151], v[196:199], v[18:21]
	v_mfma_f32_16x16x32_bf16 v[62:65], v[144:147], v[176:179], v[62:65]
	v_mfma_f32_16x16x32_bf16 v[58:61], v[152:155], v[176:179], v[58:61]
	v_mfma_f32_16x16x32_bf16 v[54:57], v[144:147], v[184:187], v[54:57]
	v_mfma_f32_16x16x32_bf16 v[50:53], v[152:155], v[184:187], v[50:53]
	v_mfma_f32_16x16x32_bf16 v[38:41], v[144:147], v[192:195], v[38:41]
	v_mfma_f32_16x16x32_bf16 v[34:37], v[152:155], v[192:195], v[34:37]
	v_mfma_f32_16x16x32_bf16 v[22:25], v[144:147], v[208:211], v[22:25]
	v_mfma_f32_16x16x32_bf16 v[18:21], v[152:155], v[208:211], v[18:21]
	v_mfma_f32_16x16x32_bf16 v[46:49], v[156:159], v[172:175], v[46:49]
	v_mfma_f32_16x16x32_bf16 v[42:45], v[164:167], v[172:175], v[42:45]
	v_mfma_f32_16x16x32_bf16 v[30:33], v[156:159], v[180:183], v[30:33]
	v_mfma_f32_16x16x32_bf16 v[26:29], v[164:167], v[180:183], v[26:29]
	v_mfma_f32_16x16x32_bf16 v[14:17], v[156:159], v[188:191], v[14:17]
	v_mfma_f32_16x16x32_bf16 v[10:13], v[164:167], v[188:191], v[10:13]
	v_mfma_f32_16x16x32_bf16 v[6:9], v[156:159], v[196:199], v[6:9]
	v_mfma_f32_16x16x32_bf16 v[2:5], v[164:167], v[196:199], v[2:5]
	v_mfma_f32_16x16x32_bf16 v[46:49], v[160:163], v[176:179], v[46:49]
	v_mfma_f32_16x16x32_bf16 v[42:45], v[168:171], v[176:179], v[42:45]
	v_mfma_f32_16x16x32_bf16 v[30:33], v[160:163], v[184:187], v[30:33]
	v_mfma_f32_16x16x32_bf16 v[26:29], v[168:171], v[184:187], v[26:29]
	v_mfma_f32_16x16x32_bf16 v[14:17], v[160:163], v[192:195], v[14:17]
	v_mfma_f32_16x16x32_bf16 v[10:13], v[168:171], v[192:195], v[10:13]
	v_mfma_f32_16x16x32_bf16 v[6:9], v[160:163], v[208:211], v[6:9]
	v_mfma_f32_16x16x32_bf16 v[2:5], v[168:171], v[208:211], v[2:5]
	s_barrier
	s_setprio 0
	s_add_i32 s2, 0, 0x18000
	s_add_i32 s3, 0, 0x1c000
	ds_read_b128 v[140:143], v136 offset:32768
	ds_read_b128 v[144:147], v136 offset:33792
	ds_read_b128 v[148:151], v136 offset:34816
	ds_read_b128 v[152:155], v136 offset:35840
	ds_read_b128 v[156:159], v136 offset:49152
	ds_read_b128 v[160:163], v136 offset:50176
	ds_read_b128 v[164:167], v136 offset:51200
	ds_read_b128 v[168:171], v136 offset:52224
	s_add_u32 s0, s20, 0x160000
	s_addc_u32 s1, s21, 0
	s_mov_b32 m0, s27
	ds_read_b128 v[172:175], v139 offset:32768
	ds_read_b128 v[176:179], v139 offset:33792
	ds_read_b128 v[180:183], v139 offset:34816
	ds_read_b128 v[184:187], v139 offset:35840
	ds_read_b128 v[188:191], v139 offset:36864
	ds_read_b128 v[192:195], v139 offset:37888
	ds_read_b128 v[196:199], v139 offset:38912
	ds_read_b128 v[208:211], v139 offset:39936
	global_load_lds_dwordx4 v202, s[0:1]
	s_mov_b32 m0, s28
	s_nop 0
	global_load_lds_dwordx4 v130, s[0:1]
	s_waitcnt vmcnt(8)
	s_waitcnt lgkmcnt(0)
	s_setprio 1
	s_barrier
	v_mfma_f32_16x16x32_bf16 v[126:129], v[140:143], v[172:175], v[126:129]
	v_mfma_f32_16x16x32_bf16 v[122:125], v[148:151], v[172:175], v[122:125]
	v_mfma_f32_16x16x32_bf16 v[118:121], v[140:143], v[180:183], v[118:121]
	v_mfma_f32_16x16x32_bf16 v[114:117], v[148:151], v[180:183], v[114:117]
	v_mfma_f32_16x16x32_bf16 v[106:109], v[140:143], v[188:191], v[106:109]
	v_mfma_f32_16x16x32_bf16 v[98:101], v[148:151], v[188:191], v[98:101]
	v_mfma_f32_16x16x32_bf16 v[90:93], v[140:143], v[196:199], v[90:93]
	v_mfma_f32_16x16x32_bf16 v[82:85], v[148:151], v[196:199], v[82:85]
	v_mfma_f32_16x16x32_bf16 v[126:129], v[144:147], v[176:179], v[126:129]
	v_mfma_f32_16x16x32_bf16 v[122:125], v[152:155], v[176:179], v[122:125]
	v_mfma_f32_16x16x32_bf16 v[118:121], v[144:147], v[184:187], v[118:121]
	v_mfma_f32_16x16x32_bf16 v[114:117], v[152:155], v[184:187], v[114:117]
	v_mfma_f32_16x16x32_bf16 v[106:109], v[144:147], v[192:195], v[106:109]
	v_mfma_f32_16x16x32_bf16 v[98:101], v[152:155], v[192:195], v[98:101]
	v_mfma_f32_16x16x32_bf16 v[90:93], v[144:147], v[208:211], v[90:93]
	v_mfma_f32_16x16x32_bf16 v[82:85], v[152:155], v[208:211], v[82:85]
	v_mfma_f32_16x16x32_bf16 v[110:113], v[156:159], v[172:175], v[110:113]
	v_mfma_f32_16x16x32_bf16 v[102:105], v[164:167], v[172:175], v[102:105]
	v_mfma_f32_16x16x32_bf16 v[94:97], v[156:159], v[180:183], v[94:97]
	v_mfma_f32_16x16x32_bf16 v[86:89], v[164:167], v[180:183], v[86:89]
	v_mfma_f32_16x16x32_bf16 v[78:81], v[156:159], v[188:191], v[78:81]
	v_mfma_f32_16x16x32_bf16 v[74:77], v[164:167], v[188:191], v[74:77]
	v_mfma_f32_16x16x32_bf16 v[70:73], v[156:159], v[196:199], v[70:73]
	v_mfma_f32_16x16x32_bf16 v[66:69], v[164:167], v[196:199], v[66:69]
	v_mfma_f32_16x16x32_bf16 v[110:113], v[160:163], v[176:179], v[110:113]
	v_mfma_f32_16x16x32_bf16 v[102:105], v[168:171], v[176:179], v[102:105]
	v_mfma_f32_16x16x32_bf16 v[94:97], v[160:163], v[184:187], v[94:97]
	v_mfma_f32_16x16x32_bf16 v[86:89], v[168:171], v[184:187], v[86:89]
	v_mfma_f32_16x16x32_bf16 v[78:81], v[160:163], v[192:195], v[78:81]
	v_mfma_f32_16x16x32_bf16 v[74:77], v[168:171], v[192:195], v[74:77]
	v_mfma_f32_16x16x32_bf16 v[70:73], v[160:163], v[208:211], v[70:73]
	v_mfma_f32_16x16x32_bf16 v[66:69], v[168:171], v[208:211], v[66:69]
	s_barrier
	s_setprio 0
	s_add_i32 s0, s2, s24
	s_add_u32 s100, s18, 0x80
	s_addc_u32 s101, s19, 0
	s_mov_b32 m0, s0
	ds_read_b128 v[172:175], v139 offset:49152
	ds_read_b128 v[176:179], v139 offset:50176
	ds_read_b128 v[180:183], v139 offset:51200
	ds_read_b128 v[184:187], v139 offset:52224
	ds_read_b128 v[188:191], v139 offset:53248
	ds_read_b128 v[192:195], v139 offset:54272
	ds_read_b128 v[196:199], v139 offset:55296
	ds_read_b128 v[208:211], v139 offset:56320
	global_load_lds_dwordx4 v202, s[100:101]
	s_add_i32 m0, s0, 0x2000
	s_add_u32 s100, s18, 0x80
	s_addc_u32 s101, s19, 0
	s_add_u32 s0, s18, 0x160080
	s_addc_u32 s1, s19, 0
	s_add_i32 s2, s3, s24
	global_load_lds_dwordx4 v130, s[100:101]
	s_mov_b32 m0, s2
	s_nop 0
	global_load_lds_dwordx4 v202, s[0:1]
	s_add_i32 m0, s2, 0x2000
	s_nop 0
	global_load_lds_dwordx4 v130, s[0:1]
	s_add_u32 s100, s20, 0x80
	s_addc_u32 s101, s21, 0
	s_mov_b32 m0, s29
	s_nop 0
	global_load_lds_dwordx4 v202, s[100:101]
	s_add_u32 s100, s20, 0x80
	s_addc_u32 s101, s21, 0
	s_mov_b32 m0, s30
	s_nop 0
	global_load_lds_dwordx4 v130, s[100:101]
	s_waitcnt vmcnt(8)
	s_waitcnt lgkmcnt(0)
	s_setprio 1
	s_barrier
	v_mfma_f32_16x16x32_bf16 v[62:65], v[140:143], v[172:175], v[62:65]
	v_mfma_f32_16x16x32_bf16 v[58:61], v[148:151], v[172:175], v[58:61]
	v_mfma_f32_16x16x32_bf16 v[54:57], v[140:143], v[180:183], v[54:57]
	v_mfma_f32_16x16x32_bf16 v[50:53], v[148:151], v[180:183], v[50:53]
	v_mfma_f32_16x16x32_bf16 v[38:41], v[140:143], v[188:191], v[38:41]
	v_mfma_f32_16x16x32_bf16 v[34:37], v[148:151], v[188:191], v[34:37]
	v_mfma_f32_16x16x32_bf16 v[22:25], v[140:143], v[196:199], v[22:25]
	v_mfma_f32_16x16x32_bf16 v[18:21], v[148:151], v[196:199], v[18:21]
	v_mfma_f32_16x16x32_bf16 v[62:65], v[144:147], v[176:179], v[62:65]
	v_mfma_f32_16x16x32_bf16 v[58:61], v[152:155], v[176:179], v[58:61]
	v_mfma_f32_16x16x32_bf16 v[54:57], v[144:147], v[184:187], v[54:57]
	v_mfma_f32_16x16x32_bf16 v[50:53], v[152:155], v[184:187], v[50:53]
	v_mfma_f32_16x16x32_bf16 v[38:41], v[144:147], v[192:195], v[38:41]
	v_mfma_f32_16x16x32_bf16 v[34:37], v[152:155], v[192:195], v[34:37]
	v_mfma_f32_16x16x32_bf16 v[22:25], v[144:147], v[208:211], v[22:25]
	v_mfma_f32_16x16x32_bf16 v[18:21], v[152:155], v[208:211], v[18:21]
	v_mfma_f32_16x16x32_bf16 v[46:49], v[156:159], v[172:175], v[46:49]
	v_mfma_f32_16x16x32_bf16 v[42:45], v[164:167], v[172:175], v[42:45]
	v_mfma_f32_16x16x32_bf16 v[30:33], v[156:159], v[180:183], v[30:33]
	v_mfma_f32_16x16x32_bf16 v[26:29], v[164:167], v[180:183], v[26:29]
	v_mfma_f32_16x16x32_bf16 v[14:17], v[156:159], v[188:191], v[14:17]
	v_mfma_f32_16x16x32_bf16 v[10:13], v[164:167], v[188:191], v[10:13]
	v_mfma_f32_16x16x32_bf16 v[6:9], v[156:159], v[196:199], v[6:9]
	v_mfma_f32_16x16x32_bf16 v[2:5], v[164:167], v[196:199], v[2:5]
	v_mfma_f32_16x16x32_bf16 v[46:49], v[160:163], v[176:179], v[46:49]
	v_mfma_f32_16x16x32_bf16 v[42:45], v[168:171], v[176:179], v[42:45]
	v_mfma_f32_16x16x32_bf16 v[30:33], v[160:163], v[184:187], v[30:33]
	v_mfma_f32_16x16x32_bf16 v[26:29], v[168:171], v[184:187], v[26:29]
	v_mfma_f32_16x16x32_bf16 v[14:17], v[160:163], v[192:195], v[14:17]
	v_mfma_f32_16x16x32_bf16 v[10:13], v[168:171], v[192:195], v[10:13]
	v_mfma_f32_16x16x32_bf16 v[6:9], v[160:163], v[208:211], v[6:9]
	v_mfma_f32_16x16x32_bf16 v[2:5], v[168:171], v[208:211], v[2:5]
	s_barrier
	s_setprio 0
	s_add_i32 s59, s59, 2
	s_add_u32 s49, s49, 0x100
	s_addc_u32 s58, s58, 0
	s_cmp_gt_u32 s59, 5
	s_mov_b64 s[2:3], s[4:5]
	s_cbranch_scc0 .LBB0_990
	s_and_b64 vcc, exec, s[10:11]
	s_cbranch_vccz .LBB0_993
	s_barrier

.LBB0_1115:
	s_add_u32 s0, s22, 0xfff80080
	s_addc_u32 s1, s23, -1
	s_add_i32 s33, 0, 0x10000
	s_cmp_eq_u32 s58, 28
	s_cselect_b32 s5, s17, s1
	s_cselect_b32 s4, s39, s0
	s_cselect_b32 s3, s15, s49
	s_cselect_b32 s2, s40, s41
	s_add_i32 s55, 0, 0x14000
	ds_read_b128 v[148:151], v145
	ds_read_b128 v[152:155], v145 offset:1024
	ds_read_b128 v[156:159], v145 offset:2048
	ds_read_b128 v[160:163], v145 offset:3072
	ds_read_b128 v[164:167], v145 offset:16384
	ds_read_b128 v[168:171], v145 offset:17408
	ds_read_b128 v[172:175], v145 offset:18432
	ds_read_b128 v[176:179], v145 offset:19456
	s_add_i32 m0, s27, 0xc000
	ds_read_b128 v[180:183], v147
	ds_read_b128 v[184:187], v147 offset:1024
	ds_read_b128 v[188:191], v147 offset:2048
	ds_read_b128 v[192:195], v147 offset:3072
	ds_read_b128 v[196:199], v147 offset:4096
	ds_read_b128 v[208:211], v147 offset:5120
	ds_read_b128 v[212:215], v147 offset:6144
	ds_read_b128 v[216:219], v147 offset:7168
	global_load_lds_dwordx4 v138, s[22:23]
	s_add_i32 m0, s27, 0xe000
	s_nop 0
	global_load_lds_dwordx4 v140, s[22:23]
	s_waitcnt vmcnt(8)
	s_waitcnt lgkmcnt(0)
	s_setprio 1
	s_barrier
	v_mfma_f32_16x16x32_bf16 v[126:129], v[148:151], v[180:183], v[126:129]
	v_mfma_f32_16x16x32_bf16 v[122:125], v[156:159], v[180:183], v[122:125]
	v_mfma_f32_16x16x32_bf16 v[110:113], v[148:151], v[188:191], v[110:113]
	v_mfma_f32_16x16x32_bf16 v[106:109], v[156:159], v[188:191], v[106:109]
	v_mfma_f32_16x16x32_bf16 v[94:97], v[148:151], v[196:199], v[94:97]
	v_mfma_f32_16x16x32_bf16 v[90:93], v[156:159], v[196:199], v[90:93]
	v_mfma_f32_16x16x32_bf16 v[78:81], v[148:151], v[212:215], v[78:81]
	v_mfma_f32_16x16x32_bf16 v[74:77], v[156:159], v[212:215], v[74:77]
	v_mfma_f32_16x16x32_bf16 v[126:129], v[152:155], v[184:187], v[126:129]
	v_mfma_f32_16x16x32_bf16 v[122:125], v[160:163], v[184:187], v[122:125]
	v_mfma_f32_16x16x32_bf16 v[110:113], v[152:155], v[192:195], v[110:113]
	v_mfma_f32_16x16x32_bf16 v[106:109], v[160:163], v[192:195], v[106:109]
	v_mfma_f32_16x16x32_bf16 v[94:97], v[152:155], v[208:211], v[94:97]
	v_mfma_f32_16x16x32_bf16 v[90:93], v[160:163], v[208:211], v[90:93]
	v_mfma_f32_16x16x32_bf16 v[78:81], v[152:155], v[216:219], v[78:81]
	v_mfma_f32_16x16x32_bf16 v[74:77], v[160:163], v[216:219], v[74:77]
	v_mfma_f32_16x16x32_bf16 v[118:121], v[164:167], v[180:183], v[118:121]
	v_mfma_f32_16x16x32_bf16 v[114:117], v[172:175], v[180:183], v[114:117]
	v_mfma_f32_16x16x32_bf16 v[102:105], v[164:167], v[188:191], v[102:105]
	v_mfma_f32_16x16x32_bf16 v[98:101], v[172:175], v[188:191], v[98:101]
	v_mfma_f32_16x16x32_bf16 v[86:89], v[164:167], v[196:199], v[86:89]
	v_mfma_f32_16x16x32_bf16 v[82:85], v[172:175], v[196:199], v[82:85]
	v_mfma_f32_16x16x32_bf16 v[70:73], v[164:167], v[212:215], v[70:73]
	v_mfma_f32_16x16x32_bf16 v[66:69], v[172:175], v[212:215], v[66:69]
	v_mfma_f32_16x16x32_bf16 v[118:121], v[168:171], v[184:187], v[118:121]
	v_mfma_f32_16x16x32_bf16 v[114:117], v[176:179], v[184:187], v[114:117]
	v_mfma_f32_16x16x32_bf16 v[102:105], v[168:171], v[192:195], v[102:105]
	v_mfma_f32_16x16x32_bf16 v[98:101], v[176:179], v[192:195], v[98:101]
	v_mfma_f32_16x16x32_bf16 v[86:89], v[168:171], v[208:211], v[86:89]
	v_mfma_f32_16x16x32_bf16 v[82:85], v[176:179], v[208:211], v[82:85]
	v_mfma_f32_16x16x32_bf16 v[70:73], v[168:171], v[216:219], v[70:73]
	v_mfma_f32_16x16x32_bf16 v[66:69], v[176:179], v[216:219], v[66:69]
	s_barrier
	s_setprio 0
	s_add_i32 s0, s33, s26
	s_mov_b32 m0, s0
	ds_read_b128 v[180:183], v147 offset:16384
	ds_read_b128 v[184:187], v147 offset:17408
	ds_read_b128 v[188:191], v147 offset:18432
	ds_read_b128 v[192:195], v147 offset:19456
	ds_read_b128 v[196:199], v147 offset:20480
	ds_read_b128 v[208:211], v147 offset:21504
	ds_read_b128 v[212:215], v147 offset:22528
	ds_read_b128 v[216:219], v147 offset:23552
	global_load_lds_dwordx4 v134, s[2:3]
	s_add_i32 m0, s0, 0x2000
	s_add_u32 s0, s2, 0x80000
	s_addc_u32 s1, s3, 0
	s_add_i32 s33, s55, s26
	global_load_lds_dwordx4 v130, s[2:3]
	s_mov_b32 m0, s33
	s_nop 0
	global_load_lds_dwordx4 v134, s[0:1]
	s_add_i32 m0, s33, 0x2000
	s_nop 0
	global_load_lds_dwordx4 v130, s[0:1]
	s_mov_b32 m0, s27
	s_nop 0
	global_load_lds_dwordx4 v136, s[4:5]
	s_mov_b32 m0, s28
	s_nop 0
	global_load_lds_dwordx4 v132, s[4:5]
	s_waitcnt vmcnt(8)
	s_waitcnt lgkmcnt(0)
	s_setprio 1
	s_barrier
	v_mfma_f32_16x16x32_bf16 v[62:65], v[148:151], v[180:183], v[62:65]
	v_mfma_f32_16x16x32_bf16 v[58:61], v[156:159], v[180:183], v[58:61]
	v_mfma_f32_16x16x32_bf16 v[46:49], v[148:151], v[188:191], v[46:49]
	v_mfma_f32_16x16x32_bf16 v[42:45], v[156:159], v[188:191], v[42:45]
	v_mfma_f32_16x16x32_bf16 v[30:33], v[148:151], v[196:199], v[30:33]
	v_mfma_f32_16x16x32_bf16 v[26:29], v[156:159], v[196:199], v[26:29]
	v_mfma_f32_16x16x32_bf16 v[14:17], v[148:151], v[212:215], v[14:17]
	v_mfma_f32_16x16x32_bf16 v[10:13], v[156:159], v[212:215], v[10:13]
	v_mfma_f32_16x16x32_bf16 v[62:65], v[152:155], v[184:187], v[62:65]
	v_mfma_f32_16x16x32_bf16 v[58:61], v[160:163], v[184:187], v[58:61]
	v_mfma_f32_16x16x32_bf16 v[46:49], v[152:155], v[192:195], v[46:49]
	v_mfma_f32_16x16x32_bf16 v[42:45], v[160:163], v[192:195], v[42:45]
	v_mfma_f32_16x16x32_bf16 v[30:33], v[152:155], v[208:211], v[30:33]
	v_mfma_f32_16x16x32_bf16 v[26:29], v[160:163], v[208:211], v[26:29]
	v_mfma_f32_16x16x32_bf16 v[14:17], v[152:155], v[216:219], v[14:17]
	v_mfma_f32_16x16x32_bf16 v[10:13], v[160:163], v[216:219], v[10:13]
	v_mfma_f32_16x16x32_bf16 v[54:57], v[164:167], v[180:183], v[54:57]
	v_mfma_f32_16x16x32_bf16 v[50:53], v[172:175], v[180:183], v[50:53]
	v_mfma_f32_16x16x32_bf16 v[38:41], v[164:167], v[188:191], v[38:41]
	v_mfma_f32_16x16x32_bf16 v[34:37], v[172:175], v[188:191], v[34:37]
	v_mfma_f32_16x16x32_bf16 v[22:25], v[164:167], v[196:199], v[22:25]
	v_mfma_f32_16x16x32_bf16 v[18:21], v[172:175], v[196:199], v[18:21]
	v_mfma_f32_16x16x32_bf16 v[6:9], v[164:167], v[212:215], v[6:9]
	v_mfma_f32_16x16x32_bf16 v[2:5], v[172:175], v[212:215], v[2:5]
	v_mfma_f32_16x16x32_bf16 v[54:57], v[168:171], v[184:187], v[54:57]
	v_mfma_f32_16x16x32_bf16 v[50:53], v[176:179], v[184:187], v[50:53]
	v_mfma_f32_16x16x32_bf16 v[38:41], v[168:171], v[192:195], v[38:41]
	v_mfma_f32_16x16x32_bf16 v[34:37], v[176:179], v[192:195], v[34:37]
	v_mfma_f32_16x16x32_bf16 v[22:25], v[168:171], v[208:211], v[22:25]
	v_mfma_f32_16x16x32_bf16 v[18:21], v[176:179], v[208:211], v[18:21]
	v_mfma_f32_16x16x32_bf16 v[6:9], v[168:171], v[216:219], v[6:9]
	v_mfma_f32_16x16x32_bf16 v[2:5], v[176:179], v[216:219], v[2:5]
	s_barrier
	s_setprio 0
	s_add_i32 s33, 0, 0x18000
	s_add_i32 s55, 0, 0x1c000
	ds_read_b128 v[148:151], v145 offset:32768
	ds_read_b128 v[152:155], v145 offset:33792
	ds_read_b128 v[156:159], v145 offset:34816
	ds_read_b128 v[160:163], v145 offset:35840
	ds_read_b128 v[164:167], v145 offset:49152
	ds_read_b128 v[168:171], v145 offset:50176
	ds_read_b128 v[172:175], v145 offset:51200
	ds_read_b128 v[176:179], v145 offset:52224
	s_add_u32 s0, s4, 0x80000
	s_addc_u32 s1, s5, 0
	s_mov_b32 m0, s29
	ds_read_b128 v[180:183], v147 offset:32768
	ds_read_b128 v[184:187], v147 offset:33792
	ds_read_b128 v[188:191], v147 offset:34816
	ds_read_b128 v[192:195], v147 offset:35840
	ds_read_b128 v[196:199], v147 offset:36864
	ds_read_b128 v[208:211], v147 offset:37888
	ds_read_b128 v[212:215], v147 offset:38912
	ds_read_b128 v[216:219], v147 offset:39936
	global_load_lds_dwordx4 v136, s[0:1]
	s_mov_b32 m0, s30
	s_nop 0
	global_load_lds_dwordx4 v132, s[0:1]
	s_waitcnt vmcnt(8)
	s_waitcnt lgkmcnt(0)
	s_setprio 1
	s_barrier
	v_mfma_f32_16x16x32_bf16 v[126:129], v[148:151], v[180:183], v[126:129]
	v_mfma_f32_16x16x32_bf16 v[122:125], v[156:159], v[180:183], v[122:125]
	v_mfma_f32_16x16x32_bf16 v[110:113], v[148:151], v[188:191], v[110:113]
	v_mfma_f32_16x16x32_bf16 v[106:109], v[156:159], v[188:191], v[106:109]
	v_mfma_f32_16x16x32_bf16 v[94:97], v[148:151], v[196:199], v[94:97]
	v_mfma_f32_16x16x32_bf16 v[90:93], v[156:159], v[196:199], v[90:93]
	v_mfma_f32_16x16x32_bf16 v[78:81], v[148:151], v[212:215], v[78:81]
	v_mfma_f32_16x16x32_bf16 v[74:77], v[156:159], v[212:215], v[74:77]
	v_mfma_f32_16x16x32_bf16 v[126:129], v[152:155], v[184:187], v[126:129]
	v_mfma_f32_16x16x32_bf16 v[122:125], v[160:163], v[184:187], v[122:125]
	v_mfma_f32_16x16x32_bf16 v[110:113], v[152:155], v[192:195], v[110:113]
	v_mfma_f32_16x16x32_bf16 v[106:109], v[160:163], v[192:195], v[106:109]
	v_mfma_f32_16x16x32_bf16 v[94:97], v[152:155], v[208:211], v[94:97]
	v_mfma_f32_16x16x32_bf16 v[90:93], v[160:163], v[208:211], v[90:93]
	v_mfma_f32_16x16x32_bf16 v[78:81], v[152:155], v[216:219], v[78:81]
	v_mfma_f32_16x16x32_bf16 v[74:77], v[160:163], v[216:219], v[74:77]
	v_mfma_f32_16x16x32_bf16 v[118:121], v[164:167], v[180:183], v[118:121]
	v_mfma_f32_16x16x32_bf16 v[114:117], v[172:175], v[180:183], v[114:117]
	v_mfma_f32_16x16x32_bf16 v[102:105], v[164:167], v[188:191], v[102:105]
	v_mfma_f32_16x16x32_bf16 v[98:101], v[172:175], v[188:191], v[98:101]
	v_mfma_f32_16x16x32_bf16 v[86:89], v[164:167], v[196:199], v[86:89]
	v_mfma_f32_16x16x32_bf16 v[82:85], v[172:175], v[196:199], v[82:85]
	v_mfma_f32_16x16x32_bf16 v[70:73], v[164:167], v[212:215], v[70:73]
	v_mfma_f32_16x16x32_bf16 v[66:69], v[172:175], v[212:215], v[66:69]
	v_mfma_f32_16x16x32_bf16 v[118:121], v[168:171], v[184:187], v[118:121]
	v_mfma_f32_16x16x32_bf16 v[114:117], v[176:179], v[184:187], v[114:117]
	v_mfma_f32_16x16x32_bf16 v[102:105], v[168:171], v[192:195], v[102:105]
	v_mfma_f32_16x16x32_bf16 v[98:101], v[176:179], v[192:195], v[98:101]
	v_mfma_f32_16x16x32_bf16 v[86:89], v[168:171], v[208:211], v[86:89]
	v_mfma_f32_16x16x32_bf16 v[82:85], v[176:179], v[208:211], v[82:85]
	v_mfma_f32_16x16x32_bf16 v[70:73], v[168:171], v[216:219], v[70:73]
	v_mfma_f32_16x16x32_bf16 v[66:69], v[176:179], v[216:219], v[66:69]
	s_barrier
	s_setprio 0
	s_add_i32 s0, s33, s26
	s_add_u32 s100, s2, 0x80
	s_addc_u32 s101, s3, 0
	s_mov_b32 m0, s0
	ds_read_b128 v[180:183], v147 offset:49152
	ds_read_b128 v[184:187], v147 offset:50176
	ds_read_b128 v[188:191], v147 offset:51200
	ds_read_b128 v[192:195], v147 offset:52224
	ds_read_b128 v[196:199], v147 offset:53248
	ds_read_b128 v[208:211], v147 offset:54272
	ds_read_b128 v[212:215], v147 offset:55296
	ds_read_b128 v[216:219], v147 offset:56320
	global_load_lds_dwordx4 v134, s[100:101]
	s_add_i32 m0, s0, 0x2000
	s_add_u32 s100, s2, 0x80
	s_addc_u32 s101, s3, 0
	s_add_u32 s0, s2, 0x80080
	s_addc_u32 s1, s3, 0
	s_add_i32 s2, s55, s26
	global_load_lds_dwordx4 v130, s[100:101]
	s_mov_b32 m0, s2
	s_nop 0
	global_load_lds_dwordx4 v134, s[0:1]
	s_add_i32 m0, s2, 0x2000
	s_nop 0
	global_load_lds_dwordx4 v130, s[0:1]
	s_add_u32 s100, s4, 0x80
	s_addc_u32 s101, s5, 0
	s_mov_b32 m0, s34
	s_nop 0
	global_load_lds_dwordx4 v136, s[100:101]
	s_add_u32 s100, s4, 0x80
	s_addc_u32 s101, s5, 0
	s_mov_b32 m0, s35
	s_nop 0
	global_load_lds_dwordx4 v132, s[100:101]
	s_waitcnt vmcnt(8)
	s_waitcnt lgkmcnt(0)
	s_setprio 1
	s_barrier
	v_mfma_f32_16x16x32_bf16 v[62:65], v[148:151], v[180:183], v[62:65]
	v_mfma_f32_16x16x32_bf16 v[58:61], v[156:159], v[180:183], v[58:61]
	v_mfma_f32_16x16x32_bf16 v[46:49], v[148:151], v[188:191], v[46:49]
	v_mfma_f32_16x16x32_bf16 v[42:45], v[156:159], v[188:191], v[42:45]
	v_mfma_f32_16x16x32_bf16 v[30:33], v[148:151], v[196:199], v[30:33]
	v_mfma_f32_16x16x32_bf16 v[26:29], v[156:159], v[196:199], v[26:29]
	v_mfma_f32_16x16x32_bf16 v[14:17], v[148:151], v[212:215], v[14:17]
	v_mfma_f32_16x16x32_bf16 v[10:13], v[156:159], v[212:215], v[10:13]
	v_mfma_f32_16x16x32_bf16 v[62:65], v[152:155], v[184:187], v[62:65]
	v_mfma_f32_16x16x32_bf16 v[58:61], v[160:163], v[184:187], v[58:61]
	v_mfma_f32_16x16x32_bf16 v[46:49], v[152:155], v[192:195], v[46:49]
	v_mfma_f32_16x16x32_bf16 v[42:45], v[160:163], v[192:195], v[42:45]
	v_mfma_f32_16x16x32_bf16 v[30:33], v[152:155], v[208:211], v[30:33]
	v_mfma_f32_16x16x32_bf16 v[26:29], v[160:163], v[208:211], v[26:29]
	v_mfma_f32_16x16x32_bf16 v[14:17], v[152:155], v[216:219], v[14:17]
	v_mfma_f32_16x16x32_bf16 v[10:13], v[160:163], v[216:219], v[10:13]
	v_mfma_f32_16x16x32_bf16 v[54:57], v[164:167], v[180:183], v[54:57]
	v_mfma_f32_16x16x32_bf16 v[50:53], v[172:175], v[180:183], v[50:53]
	v_mfma_f32_16x16x32_bf16 v[38:41], v[164:167], v[188:191], v[38:41]
	v_mfma_f32_16x16x32_bf16 v[34:37], v[172:175], v[188:191], v[34:37]
	v_mfma_f32_16x16x32_bf16 v[22:25], v[164:167], v[196:199], v[22:25]
	v_mfma_f32_16x16x32_bf16 v[18:21], v[172:175], v[196:199], v[18:21]
	v_mfma_f32_16x16x32_bf16 v[6:9], v[164:167], v[212:215], v[6:9]
	v_mfma_f32_16x16x32_bf16 v[2:5], v[172:175], v[212:215], v[2:5]
	v_mfma_f32_16x16x32_bf16 v[54:57], v[168:171], v[184:187], v[54:57]
	v_mfma_f32_16x16x32_bf16 v[50:53], v[176:179], v[184:187], v[50:53]
	v_mfma_f32_16x16x32_bf16 v[38:41], v[168:171], v[192:195], v[38:41]
	v_mfma_f32_16x16x32_bf16 v[34:37], v[176:179], v[192:195], v[34:37]
	v_mfma_f32_16x16x32_bf16 v[22:25], v[168:171], v[208:211], v[22:25]
	v_mfma_f32_16x16x32_bf16 v[18:21], v[176:179], v[208:211], v[18:21]
	v_mfma_f32_16x16x32_bf16 v[6:9], v[168:171], v[216:219], v[6:9]
	v_mfma_f32_16x16x32_bf16 v[2:5], v[176:179], v[216:219], v[2:5]
	s_barrier
	s_setprio 0
	s_add_i32 s58, s58, 2
	s_add_u32 s22, s22, 0x100
	s_addc_u32 s23, s23, 0
	s_add_u32 s41, s41, 0x100
	s_addc_u32 s49, s49, 0
	s_cmp_gt_u32 s58, 29
	s_cbranch_scc0 .LBB0_1115
	s_and_b64 vcc, exec, s[10:11]
	s_cbranch_vccz .LBB0_1118
	s_barrier

.LBB0_1242:
	s_add_u32 s28, s18, s4
	s_addc_u32 s29, s19, s5
	s_add_u32 s24, s28, 0x100
	s_addc_u32 s25, s29, 0
	s_and_b64 s[0:1], s[2:3], exec
	s_cselect_b32 s25, s49, s25
	s_cselect_b32 s24, s58, s24
	s_add_u32 s0, s20, s4
	s_addc_u32 s1, s21, s5
	s_add_u32 s4, s0, 0x100
	s_addc_u32 s5, s1, 0
	s_add_i32 s55, 0, 0x10000
	s_and_b64 s[0:1], s[2:3], exec
	s_cselect_b32 s27, s59, s5
	s_cselect_b32 s26, s60, s4
	s_add_i32 s0, 0, 0x14000
	s_add_u32 s30, s28, 0x20080
	s_addc_u32 s31, s29, 0
	s_add_i32 s57, s55, s36
	s_add_i32 m0, s37, 0xc000
	s_add_i32 s1, s37, 0xe000
	s_add_i32 s63, s57, 0x2000
	v_add_u32_e32 v138, s55, v141
	s_add_u32 s28, s26, 0x10000
	ds_read_b128 v[144:147], v138
	ds_read_b128 v[148:151], v138 offset:1024
	ds_read_b128 v[152:155], v138 offset:2048
	ds_read_b128 v[156:159], v138 offset:3072
	v_add_u32_e32 v138, s0, v141
	s_addc_u32 s29, s27, 0
	s_add_i32 s33, s0, s36
	ds_read_b128 v[160:163], v138
	ds_read_b128 v[164:167], v138 offset:1024
	ds_read_b128 v[168:171], v138 offset:2048
	ds_read_b128 v[172:175], v138 offset:3072
	s_add_i32 s56, s33, 0x2000
	s_add_i32 vcc_lo, 0, 0x18000
	s_add_i32 vcc_hi, 0, 0x1c000
	s_add_u32 s4, s24, 0x20000
	s_addc_u32 s5, s25, 0
	s_add_i32 s61, vcc_lo, s36
	s_add_i32 s62, s61, 0x2000
	s_add_u32 s2, s26, 0x10080
	s_addc_u32 s3, s27, 0
	s_add_i32 s55, vcc_hi, s36
	s_add_i32 s0, s55, 0x2000
	ds_read_b128 v[176:179], v142
	ds_read_b128 v[180:183], v142 offset:1024
	ds_read_b128 v[184:187], v142 offset:2048
	ds_read_b128 v[188:191], v142 offset:3072
	ds_read_b128 v[192:195], v142 offset:4096
	ds_read_b128 v[196:199], v142 offset:5120
	ds_read_b128 v[208:211], v142 offset:6144
	ds_read_b128 v[212:215], v142 offset:7168
	global_load_lds_dwordx4 v134, s[30:31]
	s_mov_b32 m0, s1
	s_nop 0
	global_load_lds_dwordx4 v132, s[30:31]
	s_waitcnt vmcnt(8)
	s_waitcnt lgkmcnt(0)
	s_setprio 1
	s_barrier
	v_mfma_f32_16x16x32_bf16 v[126:129], v[144:147], v[176:179], v[126:129]
	v_mfma_f32_16x16x32_bf16 v[122:125], v[152:155], v[176:179], v[122:125]
	v_mfma_f32_16x16x32_bf16 v[118:121], v[144:147], v[184:187], v[118:121]
	v_mfma_f32_16x16x32_bf16 v[110:113], v[152:155], v[184:187], v[110:113]
	v_mfma_f32_16x16x32_bf16 v[102:105], v[144:147], v[192:195], v[102:105]
	v_mfma_f32_16x16x32_bf16 v[94:97], v[152:155], v[192:195], v[94:97]
	v_mfma_f32_16x16x32_bf16 v[86:89], v[144:147], v[208:211], v[86:89]
	v_mfma_f32_16x16x32_bf16 v[78:81], v[152:155], v[208:211], v[78:81]
	v_mfma_f32_16x16x32_bf16 v[126:129], v[148:151], v[180:183], v[126:129]
	v_mfma_f32_16x16x32_bf16 v[122:125], v[156:159], v[180:183], v[122:125]
	v_mfma_f32_16x16x32_bf16 v[118:121], v[148:151], v[188:191], v[118:121]
	v_mfma_f32_16x16x32_bf16 v[110:113], v[156:159], v[188:191], v[110:113]
	v_mfma_f32_16x16x32_bf16 v[102:105], v[148:151], v[196:199], v[102:105]
	v_mfma_f32_16x16x32_bf16 v[94:97], v[156:159], v[196:199], v[94:97]
	v_mfma_f32_16x16x32_bf16 v[86:89], v[148:151], v[212:215], v[86:89]
	v_mfma_f32_16x16x32_bf16 v[78:81], v[156:159], v[212:215], v[78:81]
	v_mfma_f32_16x16x32_bf16 v[114:117], v[160:163], v[176:179], v[114:117]
	v_mfma_f32_16x16x32_bf16 v[106:109], v[168:171], v[176:179], v[106:109]
	v_mfma_f32_16x16x32_bf16 v[98:101], v[160:163], v[184:187], v[98:101]
	v_mfma_f32_16x16x32_bf16 v[90:93], v[168:171], v[184:187], v[90:93]
	v_mfma_f32_16x16x32_bf16 v[82:85], v[160:163], v[192:195], v[82:85]
	v_mfma_f32_16x16x32_bf16 v[74:77], v[168:171], v[192:195], v[74:77]
	v_mfma_f32_16x16x32_bf16 v[70:73], v[160:163], v[208:211], v[70:73]
	v_mfma_f32_16x16x32_bf16 v[66:69], v[168:171], v[208:211], v[66:69]
	v_mfma_f32_16x16x32_bf16 v[114:117], v[164:167], v[180:183], v[114:117]
	v_mfma_f32_16x16x32_bf16 v[106:109], v[172:175], v[180:183], v[106:109]
	v_mfma_f32_16x16x32_bf16 v[98:101], v[164:167], v[188:191], v[98:101]
	v_mfma_f32_16x16x32_bf16 v[90:93], v[172:175], v[188:191], v[90:93]
	v_mfma_f32_16x16x32_bf16 v[82:85], v[164:167], v[196:199], v[82:85]
	v_mfma_f32_16x16x32_bf16 v[74:77], v[172:175], v[196:199], v[74:77]
	v_mfma_f32_16x16x32_bf16 v[70:73], v[164:167], v[212:215], v[70:73]
	v_mfma_f32_16x16x32_bf16 v[66:69], v[172:175], v[212:215], v[66:69]
	s_barrier
	s_setprio 0
	s_mov_b32 m0, s57
	ds_read_b128 v[176:179], v142 offset:16384
	ds_read_b128 v[180:183], v142 offset:17408
	ds_read_b128 v[184:187], v142 offset:18432
	ds_read_b128 v[188:191], v142 offset:19456
	ds_read_b128 v[192:195], v142 offset:20480
	ds_read_b128 v[196:199], v142 offset:21504
	ds_read_b128 v[208:211], v142 offset:22528
	ds_read_b128 v[212:215], v142 offset:23552
	global_load_lds_dwordx4 v202, s[26:27]
	s_mov_b32 m0, s63
	s_nop 0
	global_load_lds_dwordx4 v130, s[26:27]
	s_mov_b32 m0, s33
	s_nop 0
	global_load_lds_dwordx4 v202, s[28:29]
	s_mov_b32 m0, s56
	s_nop 0
	global_load_lds_dwordx4 v130, s[28:29]
	s_mov_b32 m0, s37
	s_nop 0
	global_load_lds_dwordx4 v134, s[24:25]
	s_mov_b32 m0, s38
	s_nop 0
	global_load_lds_dwordx4 v132, s[24:25]
	s_waitcnt vmcnt(8)
	s_waitcnt lgkmcnt(0)
	s_setprio 1
	s_barrier
	v_mfma_f32_16x16x32_bf16 v[62:65], v[144:147], v[176:179], v[62:65]
	v_mfma_f32_16x16x32_bf16 v[58:61], v[152:155], v[176:179], v[58:61]
	v_mfma_f32_16x16x32_bf16 v[54:57], v[144:147], v[184:187], v[54:57]
	v_mfma_f32_16x16x32_bf16 v[46:49], v[152:155], v[184:187], v[46:49]
	v_mfma_f32_16x16x32_bf16 v[38:41], v[144:147], v[192:195], v[38:41]
	v_mfma_f32_16x16x32_bf16 v[30:33], v[152:155], v[192:195], v[30:33]
	v_mfma_f32_16x16x32_bf16 v[22:25], v[144:147], v[208:211], v[22:25]
	v_mfma_f32_16x16x32_bf16 v[14:17], v[152:155], v[208:211], v[14:17]
	v_mfma_f32_16x16x32_bf16 v[62:65], v[148:151], v[180:183], v[62:65]
	v_mfma_f32_16x16x32_bf16 v[58:61], v[156:159], v[180:183], v[58:61]
	v_mfma_f32_16x16x32_bf16 v[54:57], v[148:151], v[188:191], v[54:57]
	v_mfma_f32_16x16x32_bf16 v[46:49], v[156:159], v[188:191], v[46:49]
	v_mfma_f32_16x16x32_bf16 v[38:41], v[148:151], v[196:199], v[38:41]
	v_mfma_f32_16x16x32_bf16 v[30:33], v[156:159], v[196:199], v[30:33]
	v_mfma_f32_16x16x32_bf16 v[22:25], v[148:151], v[212:215], v[22:25]
	v_mfma_f32_16x16x32_bf16 v[14:17], v[156:159], v[212:215], v[14:17]
	v_mfma_f32_16x16x32_bf16 v[50:53], v[160:163], v[176:179], v[50:53]
	v_mfma_f32_16x16x32_bf16 v[42:45], v[168:171], v[176:179], v[42:45]
	v_mfma_f32_16x16x32_bf16 v[34:37], v[160:163], v[184:187], v[34:37]
	v_mfma_f32_16x16x32_bf16 v[26:29], v[168:171], v[184:187], v[26:29]
	v_mfma_f32_16x16x32_bf16 v[18:21], v[160:163], v[192:195], v[18:21]
	v_mfma_f32_16x16x32_bf16 v[10:13], v[168:171], v[192:195], v[10:13]
	v_mfma_f32_16x16x32_bf16 v[6:9], v[160:163], v[208:211], v[6:9]
	v_mfma_f32_16x16x32_bf16 v[2:5], v[168:171], v[208:211], v[2:5]
	v_mfma_f32_16x16x32_bf16 v[50:53], v[164:167], v[180:183], v[50:53]
	v_mfma_f32_16x16x32_bf16 v[42:45], v[172:175], v[180:183], v[42:45]
	v_mfma_f32_16x16x32_bf16 v[34:37], v[164:167], v[188:191], v[34:37]
	v_mfma_f32_16x16x32_bf16 v[26:29], v[172:175], v[188:191], v[26:29]
	v_mfma_f32_16x16x32_bf16 v[18:21], v[164:167], v[196:199], v[18:21]
	v_mfma_f32_16x16x32_bf16 v[10:13], v[172:175], v[196:199], v[10:13]
	v_mfma_f32_16x16x32_bf16 v[6:9], v[164:167], v[212:215], v[6:9]
	v_mfma_f32_16x16x32_bf16 v[2:5], v[172:175], v[212:215], v[2:5]
	s_barrier
	s_setprio 0
	v_add_u32_e32 v143, vcc_lo, v141
	ds_read_b128 v[144:147], v143
	ds_read_b128 v[148:151], v143 offset:1024
	ds_read_b128 v[152:155], v143 offset:2048
	ds_read_b128 v[156:159], v143 offset:3072
	v_add_u32_e32 v143, vcc_hi, v141
	ds_read_b128 v[160:163], v143
	ds_read_b128 v[164:167], v143 offset:1024
	ds_read_b128 v[168:171], v143 offset:2048
	ds_read_b128 v[172:175], v143 offset:3072
	s_mov_b32 m0, s39
	ds_read_b128 v[176:179], v142 offset:32768
	ds_read_b128 v[180:183], v142 offset:33792
	ds_read_b128 v[184:187], v142 offset:34816
	ds_read_b128 v[188:191], v142 offset:35840
	ds_read_b128 v[192:195], v142 offset:36864
	ds_read_b128 v[196:199], v142 offset:37888
	ds_read_b128 v[208:211], v142 offset:38912
	ds_read_b128 v[212:215], v142 offset:39936
	global_load_lds_dwordx4 v134, s[4:5]
	s_mov_b32 m0, s40
	s_nop 0
	global_load_lds_dwordx4 v132, s[4:5]
	s_waitcnt vmcnt(8)
	s_waitcnt lgkmcnt(0)
	s_setprio 1
	s_barrier
	v_mfma_f32_16x16x32_bf16 v[126:129], v[144:147], v[176:179], v[126:129]
	v_mfma_f32_16x16x32_bf16 v[122:125], v[152:155], v[176:179], v[122:125]
	v_mfma_f32_16x16x32_bf16 v[118:121], v[144:147], v[184:187], v[118:121]
	v_mfma_f32_16x16x32_bf16 v[110:113], v[152:155], v[184:187], v[110:113]
	v_mfma_f32_16x16x32_bf16 v[102:105], v[144:147], v[192:195], v[102:105]
	v_mfma_f32_16x16x32_bf16 v[94:97], v[152:155], v[192:195], v[94:97]
	v_mfma_f32_16x16x32_bf16 v[86:89], v[144:147], v[208:211], v[86:89]
	v_mfma_f32_16x16x32_bf16 v[78:81], v[152:155], v[208:211], v[78:81]
	v_mfma_f32_16x16x32_bf16 v[126:129], v[148:151], v[180:183], v[126:129]
	v_mfma_f32_16x16x32_bf16 v[122:125], v[156:159], v[180:183], v[122:125]
	v_mfma_f32_16x16x32_bf16 v[118:121], v[148:151], v[188:191], v[118:121]
	v_mfma_f32_16x16x32_bf16 v[110:113], v[156:159], v[188:191], v[110:113]
	v_mfma_f32_16x16x32_bf16 v[102:105], v[148:151], v[196:199], v[102:105]
	v_mfma_f32_16x16x32_bf16 v[94:97], v[156:159], v[196:199], v[94:97]
	v_mfma_f32_16x16x32_bf16 v[86:89], v[148:151], v[212:215], v[86:89]
	v_mfma_f32_16x16x32_bf16 v[78:81], v[156:159], v[212:215], v[78:81]
	v_mfma_f32_16x16x32_bf16 v[114:117], v[160:163], v[176:179], v[114:117]
	v_mfma_f32_16x16x32_bf16 v[106:109], v[168:171], v[176:179], v[106:109]
	v_mfma_f32_16x16x32_bf16 v[98:101], v[160:163], v[184:187], v[98:101]
	v_mfma_f32_16x16x32_bf16 v[90:93], v[168:171], v[184:187], v[90:93]
	v_mfma_f32_16x16x32_bf16 v[82:85], v[160:163], v[192:195], v[82:85]
	v_mfma_f32_16x16x32_bf16 v[74:77], v[168:171], v[192:195], v[74:77]
	v_mfma_f32_16x16x32_bf16 v[70:73], v[160:163], v[208:211], v[70:73]
	v_mfma_f32_16x16x32_bf16 v[66:69], v[168:171], v[208:211], v[66:69]
	v_mfma_f32_16x16x32_bf16 v[114:117], v[164:167], v[180:183], v[114:117]
	v_mfma_f32_16x16x32_bf16 v[106:109], v[172:175], v[180:183], v[106:109]
	v_mfma_f32_16x16x32_bf16 v[98:101], v[164:167], v[188:191], v[98:101]
	v_mfma_f32_16x16x32_bf16 v[90:93], v[172:175], v[188:191], v[90:93]
	v_mfma_f32_16x16x32_bf16 v[82:85], v[164:167], v[196:199], v[82:85]
	v_mfma_f32_16x16x32_bf16 v[74:77], v[172:175], v[196:199], v[74:77]
	v_mfma_f32_16x16x32_bf16 v[70:73], v[164:167], v[212:215], v[70:73]
	v_mfma_f32_16x16x32_bf16 v[66:69], v[172:175], v[212:215], v[66:69]
	s_barrier
	s_setprio 0
	s_mov_b32 m0, s61
	s_add_u32 s100, s26, 0x80
	s_addc_u32 s101, s27, 0
	ds_read_b128 v[176:179], v142 offset:49152
	ds_read_b128 v[180:183], v142 offset:50176
	ds_read_b128 v[184:187], v142 offset:51200
	ds_read_b128 v[188:191], v142 offset:52224
	ds_read_b128 v[192:195], v142 offset:53248
	ds_read_b128 v[196:199], v142 offset:54272
	ds_read_b128 v[208:211], v142 offset:55296
	ds_read_b128 v[212:215], v142 offset:56320
	global_load_lds_dwordx4 v202, s[100:101]
	s_add_u32 s100, s26, 0x80
	s_addc_u32 s101, s27, 0
	s_mov_b32 m0, s62
	s_nop 0
	global_load_lds_dwordx4 v130, s[100:101]
	s_mov_b32 m0, s55
	s_nop 0
	global_load_lds_dwordx4 v202, s[2:3]
	s_mov_b32 m0, s0
	s_nop 0
	global_load_lds_dwordx4 v130, s[2:3]
	s_add_u32 s100, s24, 0x80
	s_addc_u32 s101, s25, 0
	s_mov_b32 m0, s41
	s_nop 0
	global_load_lds_dwordx4 v134, s[100:101]
	s_add_u32 s100, s24, 0x80
	s_addc_u32 s101, s25, 0
	s_mov_b32 m0, s86
	s_nop 0
	global_load_lds_dwordx4 v132, s[100:101]
	s_waitcnt vmcnt(8)
	s_waitcnt lgkmcnt(0)
	s_setprio 1
	s_barrier
	v_mfma_f32_16x16x32_bf16 v[62:65], v[144:147], v[176:179], v[62:65]
	v_mfma_f32_16x16x32_bf16 v[58:61], v[152:155], v[176:179], v[58:61]
	v_mfma_f32_16x16x32_bf16 v[54:57], v[144:147], v[184:187], v[54:57]
	v_mfma_f32_16x16x32_bf16 v[46:49], v[152:155], v[184:187], v[46:49]
	v_mfma_f32_16x16x32_bf16 v[38:41], v[144:147], v[192:195], v[38:41]
	v_mfma_f32_16x16x32_bf16 v[30:33], v[152:155], v[192:195], v[30:33]
	v_mfma_f32_16x16x32_bf16 v[22:25], v[144:147], v[208:211], v[22:25]
	v_mfma_f32_16x16x32_bf16 v[14:17], v[152:155], v[208:211], v[14:17]
	v_mfma_f32_16x16x32_bf16 v[62:65], v[148:151], v[180:183], v[62:65]
	v_mfma_f32_16x16x32_bf16 v[58:61], v[156:159], v[180:183], v[58:61]
	v_mfma_f32_16x16x32_bf16 v[54:57], v[148:151], v[188:191], v[54:57]
	v_mfma_f32_16x16x32_bf16 v[46:49], v[156:159], v[188:191], v[46:49]
	v_mfma_f32_16x16x32_bf16 v[38:41], v[148:151], v[196:199], v[38:41]
	v_mfma_f32_16x16x32_bf16 v[30:33], v[156:159], v[196:199], v[30:33]
	v_mfma_f32_16x16x32_bf16 v[22:25], v[148:151], v[212:215], v[22:25]
	v_mfma_f32_16x16x32_bf16 v[14:17], v[156:159], v[212:215], v[14:17]
	v_mfma_f32_16x16x32_bf16 v[50:53], v[160:163], v[176:179], v[50:53]
	v_mfma_f32_16x16x32_bf16 v[42:45], v[168:171], v[176:179], v[42:45]
	v_mfma_f32_16x16x32_bf16 v[34:37], v[160:163], v[184:187], v[34:37]
	v_mfma_f32_16x16x32_bf16 v[26:29], v[168:171], v[184:187], v[26:29]
	v_mfma_f32_16x16x32_bf16 v[18:21], v[160:163], v[192:195], v[18:21]
	v_mfma_f32_16x16x32_bf16 v[10:13], v[168:171], v[192:195], v[10:13]
	v_mfma_f32_16x16x32_bf16 v[6:9], v[160:163], v[208:211], v[6:9]
	v_mfma_f32_16x16x32_bf16 v[2:5], v[168:171], v[208:211], v[2:5]
	v_mfma_f32_16x16x32_bf16 v[50:53], v[164:167], v[180:183], v[50:53]
	v_mfma_f32_16x16x32_bf16 v[42:45], v[172:175], v[180:183], v[42:45]
	v_mfma_f32_16x16x32_bf16 v[34:37], v[164:167], v[188:191], v[34:37]
	v_mfma_f32_16x16x32_bf16 v[26:29], v[172:175], v[188:191], v[26:29]
	v_mfma_f32_16x16x32_bf16 v[18:21], v[164:167], v[196:199], v[18:21]
	v_mfma_f32_16x16x32_bf16 v[10:13], v[172:175], v[196:199], v[10:13]
	v_mfma_f32_16x16x32_bf16 v[6:9], v[164:167], v[212:215], v[6:9]
	v_mfma_f32_16x16x32_bf16 v[2:5], v[172:175], v[212:215], v[2:5]
	s_barrier
	s_setprio 0
	s_andn2_b64 vcc, exec, s[22:23]
	s_mov_b64 s[2:3], -1
	s_mov_b64 s[22:23], 0
	s_mov_b64 s[4:5], 0x100
	s_cbranch_vccz .LBB0_1242
	s_and_b64 vcc, exec, s[10:11]
	s_cbranch_vccz .LBB0_1245
	s_barrier

.LBB0_1363:
	s_add_u32 s0, s20, 0xfffe0080
	s_addc_u32 s1, s21, -1
	s_add_i32 s33, 0, 0x10000
	s_cmp_eq_u32 s59, 4
	s_cselect_b32 s5, s38, s1
	s_cselect_b32 s4, s39, s0
	s_cselect_b32 s3, s40, s58
	s_cselect_b32 s2, s41, s49
	s_add_i32 s55, 0, 0x14000
	ds_read_b128 v[148:151], v143
	ds_read_b128 v[152:155], v143 offset:1024
	ds_read_b128 v[156:159], v143 offset:2048
	ds_read_b128 v[160:163], v143 offset:3072
	ds_read_b128 v[164:167], v143 offset:16384
	ds_read_b128 v[168:171], v143 offset:17408
	ds_read_b128 v[172:175], v143 offset:18432
	ds_read_b128 v[176:179], v143 offset:19456
	s_add_i32 m0, s25, 0xc000
	ds_read_b128 v[180:183], v146
	ds_read_b128 v[184:187], v146 offset:1024
	ds_read_b128 v[188:191], v146 offset:2048
	ds_read_b128 v[192:195], v146 offset:3072
	ds_read_b128 v[196:199], v146 offset:4096
	ds_read_b128 v[208:211], v146 offset:5120
	ds_read_b128 v[212:215], v146 offset:6144
	ds_read_b128 v[216:219], v146 offset:7168
	global_load_lds_dwordx4 v138, s[20:21]
	s_add_i32 m0, s25, 0xe000
	s_nop 0
	global_load_lds_dwordx4 v140, s[20:21]
	s_waitcnt vmcnt(8)
	s_waitcnt lgkmcnt(0)
	s_setprio 1
	s_barrier
	v_mfma_f32_16x16x32_bf16 v[126:129], v[148:151], v[180:183], v[126:129]
	v_mfma_f32_16x16x32_bf16 v[122:125], v[156:159], v[180:183], v[122:125]
	v_mfma_f32_16x16x32_bf16 v[110:113], v[148:151], v[188:191], v[110:113]
	v_mfma_f32_16x16x32_bf16 v[106:109], v[156:159], v[188:191], v[106:109]
	v_mfma_f32_16x16x32_bf16 v[94:97], v[148:151], v[196:199], v[94:97]
	v_mfma_f32_16x16x32_bf16 v[90:93], v[156:159], v[196:199], v[90:93]
	v_mfma_f32_16x16x32_bf16 v[78:81], v[148:151], v[212:215], v[78:81]
	v_mfma_f32_16x16x32_bf16 v[74:77], v[156:159], v[212:215], v[74:77]
	v_mfma_f32_16x16x32_bf16 v[126:129], v[152:155], v[184:187], v[126:129]
	v_mfma_f32_16x16x32_bf16 v[122:125], v[160:163], v[184:187], v[122:125]
	v_mfma_f32_16x16x32_bf16 v[110:113], v[152:155], v[192:195], v[110:113]
	v_mfma_f32_16x16x32_bf16 v[106:109], v[160:163], v[192:195], v[106:109]
	v_mfma_f32_16x16x32_bf16 v[94:97], v[152:155], v[208:211], v[94:97]
	v_mfma_f32_16x16x32_bf16 v[90:93], v[160:163], v[208:211], v[90:93]
	v_mfma_f32_16x16x32_bf16 v[78:81], v[152:155], v[216:219], v[78:81]
	v_mfma_f32_16x16x32_bf16 v[74:77], v[160:163], v[216:219], v[74:77]
	v_mfma_f32_16x16x32_bf16 v[118:121], v[164:167], v[180:183], v[118:121]
	v_mfma_f32_16x16x32_bf16 v[114:117], v[172:175], v[180:183], v[114:117]
	v_mfma_f32_16x16x32_bf16 v[102:105], v[164:167], v[188:191], v[102:105]
	v_mfma_f32_16x16x32_bf16 v[98:101], v[172:175], v[188:191], v[98:101]
	v_mfma_f32_16x16x32_bf16 v[86:89], v[164:167], v[196:199], v[86:89]
	v_mfma_f32_16x16x32_bf16 v[82:85], v[172:175], v[196:199], v[82:85]
	v_mfma_f32_16x16x32_bf16 v[70:73], v[164:167], v[212:215], v[70:73]
	v_mfma_f32_16x16x32_bf16 v[66:69], v[172:175], v[212:215], v[66:69]
	v_mfma_f32_16x16x32_bf16 v[118:121], v[168:171], v[184:187], v[118:121]
	v_mfma_f32_16x16x32_bf16 v[114:117], v[176:179], v[184:187], v[114:117]
	v_mfma_f32_16x16x32_bf16 v[102:105], v[168:171], v[192:195], v[102:105]
	v_mfma_f32_16x16x32_bf16 v[98:101], v[176:179], v[192:195], v[98:101]
	v_mfma_f32_16x16x32_bf16 v[86:89], v[168:171], v[208:211], v[86:89]
	v_mfma_f32_16x16x32_bf16 v[82:85], v[176:179], v[208:211], v[82:85]
	v_mfma_f32_16x16x32_bf16 v[70:73], v[168:171], v[216:219], v[70:73]
	v_mfma_f32_16x16x32_bf16 v[66:69], v[176:179], v[216:219], v[66:69]
	s_barrier
	s_setprio 0
	s_add_i32 s0, s33, s24
	s_mov_b32 m0, s0
	ds_read_b128 v[180:183], v146 offset:16384
	ds_read_b128 v[184:187], v146 offset:17408
	ds_read_b128 v[188:191], v146 offset:18432
	ds_read_b128 v[192:195], v146 offset:19456
	ds_read_b128 v[196:199], v146 offset:20480
	ds_read_b128 v[208:211], v146 offset:21504
	ds_read_b128 v[212:215], v146 offset:22528
	ds_read_b128 v[216:219], v146 offset:23552
	global_load_lds_dwordx4 v134, s[2:3]
	s_add_i32 m0, s0, 0x2000
	s_add_u32 s0, s2, 0x20000
	s_addc_u32 s1, s3, 0
	s_add_i32 s33, s55, s24
	global_load_lds_dwordx4 v130, s[2:3]
	s_mov_b32 m0, s33
	s_nop 0
	global_load_lds_dwordx4 v134, s[0:1]
	s_add_i32 m0, s33, 0x2000
	s_nop 0
	global_load_lds_dwordx4 v130, s[0:1]
	s_mov_b32 m0, s25
	s_nop 0
	global_load_lds_dwordx4 v136, s[4:5]
	s_mov_b32 m0, s26
	s_nop 0
	global_load_lds_dwordx4 v132, s[4:5]
	s_waitcnt vmcnt(8)
	s_waitcnt lgkmcnt(0)
	s_setprio 1
	s_barrier
	v_mfma_f32_16x16x32_bf16 v[62:65], v[148:151], v[180:183], v[62:65]
	v_mfma_f32_16x16x32_bf16 v[58:61], v[156:159], v[180:183], v[58:61]
	v_mfma_f32_16x16x32_bf16 v[46:49], v[148:151], v[188:191], v[46:49]
	v_mfma_f32_16x16x32_bf16 v[42:45], v[156:159], v[188:191], v[42:45]
	v_mfma_f32_16x16x32_bf16 v[30:33], v[148:151], v[196:199], v[30:33]
	v_mfma_f32_16x16x32_bf16 v[26:29], v[156:159], v[196:199], v[26:29]
	v_mfma_f32_16x16x32_bf16 v[14:17], v[148:151], v[212:215], v[14:17]
	v_mfma_f32_16x16x32_bf16 v[10:13], v[156:159], v[212:215], v[10:13]
	v_mfma_f32_16x16x32_bf16 v[62:65], v[152:155], v[184:187], v[62:65]
	v_mfma_f32_16x16x32_bf16 v[58:61], v[160:163], v[184:187], v[58:61]
	v_mfma_f32_16x16x32_bf16 v[46:49], v[152:155], v[192:195], v[46:49]
	v_mfma_f32_16x16x32_bf16 v[42:45], v[160:163], v[192:195], v[42:45]
	v_mfma_f32_16x16x32_bf16 v[30:33], v[152:155], v[208:211], v[30:33]
	v_mfma_f32_16x16x32_bf16 v[26:29], v[160:163], v[208:211], v[26:29]
	v_mfma_f32_16x16x32_bf16 v[14:17], v[152:155], v[216:219], v[14:17]
	v_mfma_f32_16x16x32_bf16 v[10:13], v[160:163], v[216:219], v[10:13]
	v_mfma_f32_16x16x32_bf16 v[54:57], v[164:167], v[180:183], v[54:57]
	v_mfma_f32_16x16x32_bf16 v[50:53], v[172:175], v[180:183], v[50:53]
	v_mfma_f32_16x16x32_bf16 v[38:41], v[164:167], v[188:191], v[38:41]
	v_mfma_f32_16x16x32_bf16 v[34:37], v[172:175], v[188:191], v[34:37]
	v_mfma_f32_16x16x32_bf16 v[22:25], v[164:167], v[196:199], v[22:25]
	v_mfma_f32_16x16x32_bf16 v[18:21], v[172:175], v[196:199], v[18:21]
	v_mfma_f32_16x16x32_bf16 v[6:9], v[164:167], v[212:215], v[6:9]
	v_mfma_f32_16x16x32_bf16 v[2:5], v[172:175], v[212:215], v[2:5]
	v_mfma_f32_16x16x32_bf16 v[54:57], v[168:171], v[184:187], v[54:57]
	v_mfma_f32_16x16x32_bf16 v[50:53], v[176:179], v[184:187], v[50:53]
	v_mfma_f32_16x16x32_bf16 v[38:41], v[168:171], v[192:195], v[38:41]
	v_mfma_f32_16x16x32_bf16 v[34:37], v[176:179], v[192:195], v[34:37]
	v_mfma_f32_16x16x32_bf16 v[22:25], v[168:171], v[208:211], v[22:25]
	v_mfma_f32_16x16x32_bf16 v[18:21], v[176:179], v[208:211], v[18:21]
	v_mfma_f32_16x16x32_bf16 v[6:9], v[168:171], v[216:219], v[6:9]
	v_mfma_f32_16x16x32_bf16 v[2:5], v[176:179], v[216:219], v[2:5]
	s_barrier
	s_setprio 0
	s_add_i32 s33, 0, 0x18000
	s_add_i32 s55, 0, 0x1c000
	ds_read_b128 v[148:151], v143 offset:32768
	ds_read_b128 v[152:155], v143 offset:33792
	ds_read_b128 v[156:159], v143 offset:34816
	ds_read_b128 v[160:163], v143 offset:35840
	ds_read_b128 v[164:167], v143 offset:49152
	ds_read_b128 v[168:171], v143 offset:50176
	ds_read_b128 v[172:175], v143 offset:51200
	ds_read_b128 v[176:179], v143 offset:52224
	s_add_u32 s0, s4, 0x20000
	s_addc_u32 s1, s5, 0
	s_mov_b32 m0, s27
	ds_read_b128 v[180:183], v146 offset:32768
	ds_read_b128 v[184:187], v146 offset:33792
	ds_read_b128 v[188:191], v146 offset:34816
	ds_read_b128 v[192:195], v146 offset:35840
	ds_read_b128 v[196:199], v146 offset:36864
	ds_read_b128 v[208:211], v146 offset:37888
	ds_read_b128 v[212:215], v146 offset:38912
	ds_read_b128 v[216:219], v146 offset:39936
	global_load_lds_dwordx4 v136, s[0:1]
	s_mov_b32 m0, s28
	s_nop 0
	global_load_lds_dwordx4 v132, s[0:1]
	s_waitcnt vmcnt(8)
	s_waitcnt lgkmcnt(0)
	s_setprio 1
	s_barrier
	v_mfma_f32_16x16x32_bf16 v[126:129], v[148:151], v[180:183], v[126:129]
	v_mfma_f32_16x16x32_bf16 v[122:125], v[156:159], v[180:183], v[122:125]
	v_mfma_f32_16x16x32_bf16 v[110:113], v[148:151], v[188:191], v[110:113]
	v_mfma_f32_16x16x32_bf16 v[106:109], v[156:159], v[188:191], v[106:109]
	v_mfma_f32_16x16x32_bf16 v[94:97], v[148:151], v[196:199], v[94:97]
	v_mfma_f32_16x16x32_bf16 v[90:93], v[156:159], v[196:199], v[90:93]
	v_mfma_f32_16x16x32_bf16 v[78:81], v[148:151], v[212:215], v[78:81]
	v_mfma_f32_16x16x32_bf16 v[74:77], v[156:159], v[212:215], v[74:77]
	v_mfma_f32_16x16x32_bf16 v[126:129], v[152:155], v[184:187], v[126:129]
	v_mfma_f32_16x16x32_bf16 v[122:125], v[160:163], v[184:187], v[122:125]
	v_mfma_f32_16x16x32_bf16 v[110:113], v[152:155], v[192:195], v[110:113]
	v_mfma_f32_16x16x32_bf16 v[106:109], v[160:163], v[192:195], v[106:109]
	v_mfma_f32_16x16x32_bf16 v[94:97], v[152:155], v[208:211], v[94:97]
	v_mfma_f32_16x16x32_bf16 v[90:93], v[160:163], v[208:211], v[90:93]
	v_mfma_f32_16x16x32_bf16 v[78:81], v[152:155], v[216:219], v[78:81]
	v_mfma_f32_16x16x32_bf16 v[74:77], v[160:163], v[216:219], v[74:77]
	v_mfma_f32_16x16x32_bf16 v[118:121], v[164:167], v[180:183], v[118:121]
	v_mfma_f32_16x16x32_bf16 v[114:117], v[172:175], v[180:183], v[114:117]
	v_mfma_f32_16x16x32_bf16 v[102:105], v[164:167], v[188:191], v[102:105]
	v_mfma_f32_16x16x32_bf16 v[98:101], v[172:175], v[188:191], v[98:101]
	v_mfma_f32_16x16x32_bf16 v[86:89], v[164:167], v[196:199], v[86:89]
	v_mfma_f32_16x16x32_bf16 v[82:85], v[172:175], v[196:199], v[82:85]
	v_mfma_f32_16x16x32_bf16 v[70:73], v[164:167], v[212:215], v[70:73]
	v_mfma_f32_16x16x32_bf16 v[66:69], v[172:175], v[212:215], v[66:69]
	v_mfma_f32_16x16x32_bf16 v[118:121], v[168:171], v[184:187], v[118:121]
	v_mfma_f32_16x16x32_bf16 v[114:117], v[176:179], v[184:187], v[114:117]
	v_mfma_f32_16x16x32_bf16 v[102:105], v[168:171], v[192:195], v[102:105]
	v_mfma_f32_16x16x32_bf16 v[98:101], v[176:179], v[192:195], v[98:101]
	v_mfma_f32_16x16x32_bf16 v[86:89], v[168:171], v[208:211], v[86:89]
	v_mfma_f32_16x16x32_bf16 v[82:85], v[176:179], v[208:211], v[82:85]
	v_mfma_f32_16x16x32_bf16 v[70:73], v[168:171], v[216:219], v[70:73]
	v_mfma_f32_16x16x32_bf16 v[66:69], v[176:179], v[216:219], v[66:69]
	s_barrier
	s_setprio 0
	s_add_i32 s0, s33, s24
	s_add_u32 s100, s2, 0x80
	s_addc_u32 s101, s3, 0
	s_mov_b32 m0, s0
	ds_read_b128 v[180:183], v146 offset:49152
	ds_read_b128 v[184:187], v146 offset:50176
	ds_read_b128 v[188:191], v146 offset:51200
	ds_read_b128 v[192:195], v146 offset:52224
	ds_read_b128 v[196:199], v146 offset:53248
	ds_read_b128 v[208:211], v146 offset:54272
	ds_read_b128 v[212:215], v146 offset:55296
	ds_read_b128 v[216:219], v146 offset:56320
	global_load_lds_dwordx4 v134, s[100:101]
	s_add_i32 m0, s0, 0x2000
	s_add_u32 s100, s2, 0x80
	s_addc_u32 s101, s3, 0
	s_add_u32 s0, s2, 0x20080
	s_addc_u32 s1, s3, 0
	s_add_i32 s2, s55, s24
	global_load_lds_dwordx4 v130, s[100:101]
	s_mov_b32 m0, s2
	s_nop 0
	global_load_lds_dwordx4 v134, s[0:1]
	s_add_i32 m0, s2, 0x2000
	s_nop 0
	global_load_lds_dwordx4 v130, s[0:1]
	s_add_u32 s100, s4, 0x80
	s_addc_u32 s101, s5, 0
	s_mov_b32 m0, s29
	s_nop 0
	global_load_lds_dwordx4 v136, s[100:101]
	s_add_u32 s100, s4, 0x80
	s_addc_u32 s101, s5, 0
	s_mov_b32 m0, s30
	s_nop 0
	global_load_lds_dwordx4 v132, s[100:101]
	s_waitcnt vmcnt(8)
	s_waitcnt lgkmcnt(0)
	s_setprio 1
	s_barrier
	v_mfma_f32_16x16x32_bf16 v[62:65], v[148:151], v[180:183], v[62:65]
	v_mfma_f32_16x16x32_bf16 v[58:61], v[156:159], v[180:183], v[58:61]
	v_mfma_f32_16x16x32_bf16 v[46:49], v[148:151], v[188:191], v[46:49]
	v_mfma_f32_16x16x32_bf16 v[42:45], v[156:159], v[188:191], v[42:45]
	v_mfma_f32_16x16x32_bf16 v[30:33], v[148:151], v[196:199], v[30:33]
	v_mfma_f32_16x16x32_bf16 v[26:29], v[156:159], v[196:199], v[26:29]
	v_mfma_f32_16x16x32_bf16 v[14:17], v[148:151], v[212:215], v[14:17]
	v_mfma_f32_16x16x32_bf16 v[10:13], v[156:159], v[212:215], v[10:13]
	v_mfma_f32_16x16x32_bf16 v[62:65], v[152:155], v[184:187], v[62:65]
	v_mfma_f32_16x16x32_bf16 v[58:61], v[160:163], v[184:187], v[58:61]
	v_mfma_f32_16x16x32_bf16 v[46:49], v[152:155], v[192:195], v[46:49]
	v_mfma_f32_16x16x32_bf16 v[42:45], v[160:163], v[192:195], v[42:45]
	v_mfma_f32_16x16x32_bf16 v[30:33], v[152:155], v[208:211], v[30:33]
	v_mfma_f32_16x16x32_bf16 v[26:29], v[160:163], v[208:211], v[26:29]
	v_mfma_f32_16x16x32_bf16 v[14:17], v[152:155], v[216:219], v[14:17]
	v_mfma_f32_16x16x32_bf16 v[10:13], v[160:163], v[216:219], v[10:13]
	v_mfma_f32_16x16x32_bf16 v[54:57], v[164:167], v[180:183], v[54:57]
	v_mfma_f32_16x16x32_bf16 v[50:53], v[172:175], v[180:183], v[50:53]
	v_mfma_f32_16x16x32_bf16 v[38:41], v[164:167], v[188:191], v[38:41]
	v_mfma_f32_16x16x32_bf16 v[34:37], v[172:175], v[188:191], v[34:37]
	v_mfma_f32_16x16x32_bf16 v[22:25], v[164:167], v[196:199], v[22:25]
	v_mfma_f32_16x16x32_bf16 v[18:21], v[172:175], v[196:199], v[18:21]
	v_mfma_f32_16x16x32_bf16 v[6:9], v[164:167], v[212:215], v[6:9]
	v_mfma_f32_16x16x32_bf16 v[2:5], v[172:175], v[212:215], v[2:5]
	v_mfma_f32_16x16x32_bf16 v[54:57], v[168:171], v[184:187], v[54:57]
	v_mfma_f32_16x16x32_bf16 v[50:53], v[176:179], v[184:187], v[50:53]
	v_mfma_f32_16x16x32_bf16 v[38:41], v[168:171], v[192:195], v[38:41]
	v_mfma_f32_16x16x32_bf16 v[34:37], v[176:179], v[192:195], v[34:37]
	v_mfma_f32_16x16x32_bf16 v[22:25], v[168:171], v[208:211], v[22:25]
	v_mfma_f32_16x16x32_bf16 v[18:21], v[176:179], v[208:211], v[18:21]
	v_mfma_f32_16x16x32_bf16 v[6:9], v[168:171], v[216:219], v[6:9]
	v_mfma_f32_16x16x32_bf16 v[2:5], v[176:179], v[216:219], v[2:5]
	s_barrier
	s_setprio 0
	s_add_i32 s59, s59, 2
	s_add_u32 s20, s20, 0x100
	s_addc_u32 s21, s21, 0
	s_add_u32 s49, s49, 0x100
	s_addc_u32 s58, s58, 0
	s_cmp_gt_u32 s59, 5
	s_cbranch_scc0 .LBB0_1363
	s_and_b64 vcc, exec, s[14:15]
	s_cbranch_vccz .LBB0_1366
	s_barrier

.LBB0_1428:
	s_add_u32 s0, s26, 0xfff80080
	s_addc_u32 s1, s27, -1
	s_add_i32 s33, 0, 0x10000
	s_cmp_eq_u32 s61, 28
	s_cselect_b32 s5, s17, s1
	s_cselect_b32 s4, s49, s0
	s_cselect_b32 s3, s15, s60
	s_cselect_b32 s2, s58, s59
	s_add_i32 s55, 0, 0x14000
	ds_read_b128 v[126:129], v187
	ds_read_b128 v[134:137], v187 offset:1024
	ds_read_b128 v[138:141], v187 offset:2048
	ds_read_b128 v[142:145], v187 offset:3072
	ds_read_b128 v[146:149], v187 offset:16384
	ds_read_b128 v[150:153], v187 offset:17408
	ds_read_b128 v[154:157], v187 offset:18432
	ds_read_b128 v[158:161], v187 offset:19456
	s_add_i32 m0, s23, 0xc000
	ds_read_b128 v[172:175], v189
	ds_read_b128 v[176:179], v189 offset:1024
	ds_read_b128 v[180:183], v189 offset:2048
	ds_read_b128 v[190:193], v189 offset:3072
	ds_read_b128 v[194:197], v189 offset:4096
	ds_read_b128 v[198:201], v189 offset:5120
	ds_read_b128 v[208:211], v189 offset:6144
	ds_read_b128 v[212:215], v189 offset:7168
	global_load_lds_dwordx4 v168, s[26:27]
	s_add_i32 m0, s23, 0xe000
	s_nop 0
	global_load_lds_dwordx4 v170, s[26:27]
	s_waitcnt vmcnt(8)
	s_waitcnt lgkmcnt(0)
	s_setprio 1
	s_barrier
	v_mfma_f32_16x16x32_bf16 v[130:133], v[126:129], v[172:175], v[130:133]
	v_mfma_f32_16x16x32_bf16 v[118:121], v[138:141], v[172:175], v[118:121]
	v_mfma_f32_16x16x32_bf16 v[110:113], v[126:129], v[180:183], v[110:113]
	v_mfma_f32_16x16x32_bf16 v[102:105], v[138:141], v[180:183], v[102:105]
	v_mfma_f32_16x16x32_bf16 v[94:97], v[126:129], v[194:197], v[94:97]
	v_mfma_f32_16x16x32_bf16 v[86:89], v[138:141], v[194:197], v[86:89]
	v_mfma_f32_16x16x32_bf16 v[78:81], v[126:129], v[208:211], v[78:81]
	v_mfma_f32_16x16x32_bf16 v[70:73], v[138:141], v[208:211], v[70:73]
	v_mfma_f32_16x16x32_bf16 v[130:133], v[134:137], v[176:179], v[130:133]
	v_mfma_f32_16x16x32_bf16 v[118:121], v[142:145], v[176:179], v[118:121]
	v_mfma_f32_16x16x32_bf16 v[110:113], v[134:137], v[190:193], v[110:113]
	v_mfma_f32_16x16x32_bf16 v[102:105], v[142:145], v[190:193], v[102:105]
	v_mfma_f32_16x16x32_bf16 v[94:97], v[134:137], v[198:201], v[94:97]
	v_mfma_f32_16x16x32_bf16 v[86:89], v[142:145], v[198:201], v[86:89]
	v_mfma_f32_16x16x32_bf16 v[78:81], v[134:137], v[212:215], v[78:81]
	v_mfma_f32_16x16x32_bf16 v[70:73], v[142:145], v[212:215], v[70:73]
	v_mfma_f32_16x16x32_bf16 v[122:125], v[146:149], v[172:175], v[122:125]
	v_mfma_f32_16x16x32_bf16 v[114:117], v[154:157], v[172:175], v[114:117]
	v_mfma_f32_16x16x32_bf16 v[106:109], v[146:149], v[180:183], v[106:109]
	v_mfma_f32_16x16x32_bf16 v[98:101], v[154:157], v[180:183], v[98:101]
	v_mfma_f32_16x16x32_bf16 v[90:93], v[146:149], v[194:197], v[90:93]
	v_mfma_f32_16x16x32_bf16 v[82:85], v[154:157], v[194:197], v[82:85]
	v_mfma_f32_16x16x32_bf16 v[74:77], v[146:149], v[208:211], v[74:77]
	v_mfma_f32_16x16x32_bf16 v[66:69], v[154:157], v[208:211], v[66:69]
	v_mfma_f32_16x16x32_bf16 v[122:125], v[150:153], v[176:179], v[122:125]
	v_mfma_f32_16x16x32_bf16 v[114:117], v[158:161], v[176:179], v[114:117]
	v_mfma_f32_16x16x32_bf16 v[106:109], v[150:153], v[190:193], v[106:109]
	v_mfma_f32_16x16x32_bf16 v[98:101], v[158:161], v[190:193], v[98:101]
	v_mfma_f32_16x16x32_bf16 v[90:93], v[150:153], v[198:201], v[90:93]
	v_mfma_f32_16x16x32_bf16 v[82:85], v[158:161], v[198:201], v[82:85]
	v_mfma_f32_16x16x32_bf16 v[74:77], v[150:153], v[212:215], v[74:77]
	v_mfma_f32_16x16x32_bf16 v[66:69], v[158:161], v[212:215], v[66:69]
	s_barrier
	s_setprio 0
	s_add_i32 s0, s33, s34
	s_mov_b32 m0, s0
	ds_read_b128 v[172:175], v189 offset:16384
	ds_read_b128 v[176:179], v189 offset:17408
	ds_read_b128 v[180:183], v189 offset:18432
	ds_read_b128 v[190:193], v189 offset:19456
	ds_read_b128 v[194:197], v189 offset:20480
	ds_read_b128 v[198:201], v189 offset:21504
	ds_read_b128 v[208:211], v189 offset:22528
	ds_read_b128 v[212:215], v189 offset:23552
	global_load_lds_dwordx4 v202, s[2:3]
	s_add_i32 m0, s0, 0x2000
	s_add_u32 s0, s2, 0x80000
	s_addc_u32 s1, s3, 0
	s_add_i32 s33, s55, s34
	global_load_lds_dwordx4 v162, s[2:3]
	s_mov_b32 m0, s33
	s_nop 0
	global_load_lds_dwordx4 v202, s[0:1]
	s_add_i32 m0, s33, 0x2000
	s_nop 0
	global_load_lds_dwordx4 v162, s[0:1]
	s_mov_b32 m0, s23
	s_nop 0
	global_load_lds_dwordx4 v166, s[4:5]
	s_mov_b32 m0, s25
	s_nop 0
	global_load_lds_dwordx4 v164, s[4:5]
	s_waitcnt vmcnt(8)
	s_waitcnt lgkmcnt(0)
	s_setprio 1
	s_barrier
	v_mfma_f32_16x16x32_bf16 v[62:65], v[126:129], v[172:175], v[62:65]
	v_mfma_f32_16x16x32_bf16 v[54:57], v[138:141], v[172:175], v[54:57]
	v_mfma_f32_16x16x32_bf16 v[46:49], v[126:129], v[180:183], v[46:49]
	v_mfma_f32_16x16x32_bf16 v[38:41], v[138:141], v[180:183], v[38:41]
	v_mfma_f32_16x16x32_bf16 v[30:33], v[126:129], v[194:197], v[30:33]
	v_mfma_f32_16x16x32_bf16 v[22:25], v[138:141], v[194:197], v[22:25]
	v_mfma_f32_16x16x32_bf16 v[14:17], v[126:129], v[208:211], v[14:17]
	v_mfma_f32_16x16x32_bf16 v[6:9], v[138:141], v[208:211], v[6:9]
	v_mfma_f32_16x16x32_bf16 v[62:65], v[134:137], v[176:179], v[62:65]
	v_mfma_f32_16x16x32_bf16 v[54:57], v[142:145], v[176:179], v[54:57]
	v_mfma_f32_16x16x32_bf16 v[46:49], v[134:137], v[190:193], v[46:49]
	v_mfma_f32_16x16x32_bf16 v[38:41], v[142:145], v[190:193], v[38:41]
	v_mfma_f32_16x16x32_bf16 v[30:33], v[134:137], v[198:201], v[30:33]
	v_mfma_f32_16x16x32_bf16 v[22:25], v[142:145], v[198:201], v[22:25]
	v_mfma_f32_16x16x32_bf16 v[14:17], v[134:137], v[212:215], v[14:17]
	v_mfma_f32_16x16x32_bf16 v[6:9], v[142:145], v[212:215], v[6:9]
	v_mfma_f32_16x16x32_bf16 v[58:61], v[146:149], v[172:175], v[58:61]
	v_mfma_f32_16x16x32_bf16 v[50:53], v[154:157], v[172:175], v[50:53]
	v_mfma_f32_16x16x32_bf16 v[42:45], v[146:149], v[180:183], v[42:45]
	v_mfma_f32_16x16x32_bf16 v[34:37], v[154:157], v[180:183], v[34:37]
	v_mfma_f32_16x16x32_bf16 v[26:29], v[146:149], v[194:197], v[26:29]
	v_mfma_f32_16x16x32_bf16 v[18:21], v[154:157], v[194:197], v[18:21]
	v_mfma_f32_16x16x32_bf16 v[10:13], v[146:149], v[208:211], v[10:13]
	v_mfma_f32_16x16x32_bf16 v[2:5], v[154:157], v[208:211], v[2:5]
	v_mfma_f32_16x16x32_bf16 v[58:61], v[150:153], v[176:179], v[58:61]
	v_mfma_f32_16x16x32_bf16 v[50:53], v[158:161], v[176:179], v[50:53]
	v_mfma_f32_16x16x32_bf16 v[42:45], v[150:153], v[190:193], v[42:45]
	v_mfma_f32_16x16x32_bf16 v[34:37], v[158:161], v[190:193], v[34:37]
	v_mfma_f32_16x16x32_bf16 v[26:29], v[150:153], v[198:201], v[26:29]
	v_mfma_f32_16x16x32_bf16 v[18:21], v[158:161], v[198:201], v[18:21]
	v_mfma_f32_16x16x32_bf16 v[10:13], v[150:153], v[212:215], v[10:13]
	v_mfma_f32_16x16x32_bf16 v[2:5], v[158:161], v[212:215], v[2:5]
	s_barrier
	s_setprio 0
	s_add_i32 s33, 0, 0x18000
	s_add_i32 s55, 0, 0x1c000
	ds_read_b128 v[126:129], v187 offset:32768
	ds_read_b128 v[134:137], v187 offset:33792
	ds_read_b128 v[138:141], v187 offset:34816
	ds_read_b128 v[142:145], v187 offset:35840
	ds_read_b128 v[146:149], v187 offset:49152
	ds_read_b128 v[150:153], v187 offset:50176
	ds_read_b128 v[154:157], v187 offset:51200
	ds_read_b128 v[158:161], v187 offset:52224
	s_add_u32 s0, s4, 0x80000
	s_addc_u32 s1, s5, 0
	s_mov_b32 m0, s35
	ds_read_b128 v[172:175], v189 offset:32768
	ds_read_b128 v[176:179], v189 offset:33792
	ds_read_b128 v[180:183], v189 offset:34816
	ds_read_b128 v[190:193], v189 offset:35840
	ds_read_b128 v[194:197], v189 offset:36864
	ds_read_b128 v[198:201], v189 offset:37888
	ds_read_b128 v[208:211], v189 offset:38912
	ds_read_b128 v[212:215], v189 offset:39936
	global_load_lds_dwordx4 v166, s[0:1]
	s_mov_b32 m0, s36
	s_nop 0
	global_load_lds_dwordx4 v164, s[0:1]
	s_waitcnt vmcnt(8)
	s_waitcnt lgkmcnt(0)
	s_setprio 1
	s_barrier
	v_mfma_f32_16x16x32_bf16 v[130:133], v[126:129], v[172:175], v[130:133]
	v_mfma_f32_16x16x32_bf16 v[118:121], v[138:141], v[172:175], v[118:121]
	v_mfma_f32_16x16x32_bf16 v[110:113], v[126:129], v[180:183], v[110:113]
	v_mfma_f32_16x16x32_bf16 v[102:105], v[138:141], v[180:183], v[102:105]
	v_mfma_f32_16x16x32_bf16 v[94:97], v[126:129], v[194:197], v[94:97]
	v_mfma_f32_16x16x32_bf16 v[86:89], v[138:141], v[194:197], v[86:89]
	v_mfma_f32_16x16x32_bf16 v[78:81], v[126:129], v[208:211], v[78:81]
	v_mfma_f32_16x16x32_bf16 v[70:73], v[138:141], v[208:211], v[70:73]
	v_mfma_f32_16x16x32_bf16 v[130:133], v[134:137], v[176:179], v[130:133]
	v_mfma_f32_16x16x32_bf16 v[118:121], v[142:145], v[176:179], v[118:121]
	v_mfma_f32_16x16x32_bf16 v[110:113], v[134:137], v[190:193], v[110:113]
	v_mfma_f32_16x16x32_bf16 v[102:105], v[142:145], v[190:193], v[102:105]
	v_mfma_f32_16x16x32_bf16 v[94:97], v[134:137], v[198:201], v[94:97]
	v_mfma_f32_16x16x32_bf16 v[86:89], v[142:145], v[198:201], v[86:89]
	v_mfma_f32_16x16x32_bf16 v[78:81], v[134:137], v[212:215], v[78:81]
	v_mfma_f32_16x16x32_bf16 v[70:73], v[142:145], v[212:215], v[70:73]
	v_mfma_f32_16x16x32_bf16 v[122:125], v[146:149], v[172:175], v[122:125]
	v_mfma_f32_16x16x32_bf16 v[114:117], v[154:157], v[172:175], v[114:117]
	v_mfma_f32_16x16x32_bf16 v[106:109], v[146:149], v[180:183], v[106:109]
	v_mfma_f32_16x16x32_bf16 v[98:101], v[154:157], v[180:183], v[98:101]
	v_mfma_f32_16x16x32_bf16 v[90:93], v[146:149], v[194:197], v[90:93]
	v_mfma_f32_16x16x32_bf16 v[82:85], v[154:157], v[194:197], v[82:85]
	v_mfma_f32_16x16x32_bf16 v[74:77], v[146:149], v[208:211], v[74:77]
	v_mfma_f32_16x16x32_bf16 v[66:69], v[154:157], v[208:211], v[66:69]
	v_mfma_f32_16x16x32_bf16 v[122:125], v[150:153], v[176:179], v[122:125]
	v_mfma_f32_16x16x32_bf16 v[114:117], v[158:161], v[176:179], v[114:117]
	v_mfma_f32_16x16x32_bf16 v[106:109], v[150:153], v[190:193], v[106:109]
	v_mfma_f32_16x16x32_bf16 v[98:101], v[158:161], v[190:193], v[98:101]
	v_mfma_f32_16x16x32_bf16 v[90:93], v[150:153], v[198:201], v[90:93]
	v_mfma_f32_16x16x32_bf16 v[82:85], v[158:161], v[198:201], v[82:85]
	v_mfma_f32_16x16x32_bf16 v[74:77], v[150:153], v[212:215], v[74:77]
	v_mfma_f32_16x16x32_bf16 v[66:69], v[158:161], v[212:215], v[66:69]
	s_barrier
	s_setprio 0
	s_add_i32 s0, s33, s34
	s_add_u32 s100, s2, 0x80
	s_addc_u32 s101, s3, 0
	s_mov_b32 m0, s0
	ds_read_b128 v[172:175], v189 offset:49152
	ds_read_b128 v[176:179], v189 offset:50176
	ds_read_b128 v[180:183], v189 offset:51200
	ds_read_b128 v[190:193], v189 offset:52224
	ds_read_b128 v[194:197], v189 offset:53248
	ds_read_b128 v[198:201], v189 offset:54272
	ds_read_b128 v[208:211], v189 offset:55296
	ds_read_b128 v[212:215], v189 offset:56320
	global_load_lds_dwordx4 v202, s[100:101]
	s_add_i32 m0, s0, 0x2000
	s_add_u32 s100, s2, 0x80
	s_addc_u32 s101, s3, 0
	s_add_u32 s0, s2, 0x80080
	s_addc_u32 s1, s3, 0
	s_add_i32 s2, s55, s34
	global_load_lds_dwordx4 v162, s[100:101]
	s_mov_b32 m0, s2
	s_nop 0
	global_load_lds_dwordx4 v202, s[0:1]
	s_add_i32 m0, s2, 0x2000
	s_nop 0
	global_load_lds_dwordx4 v162, s[0:1]
	s_add_u32 s100, s4, 0x80
	s_addc_u32 s101, s5, 0
	s_mov_b32 m0, s39
	s_nop 0
	global_load_lds_dwordx4 v166, s[100:101]
	s_add_u32 s100, s4, 0x80
	s_addc_u32 s101, s5, 0
	s_mov_b32 m0, s40
	s_nop 0
	global_load_lds_dwordx4 v164, s[100:101]
	s_waitcnt vmcnt(8)
	s_waitcnt lgkmcnt(0)
	s_setprio 1
	s_barrier
	v_mfma_f32_16x16x32_bf16 v[62:65], v[126:129], v[172:175], v[62:65]
	v_mfma_f32_16x16x32_bf16 v[54:57], v[138:141], v[172:175], v[54:57]
	v_mfma_f32_16x16x32_bf16 v[46:49], v[126:129], v[180:183], v[46:49]
	v_mfma_f32_16x16x32_bf16 v[38:41], v[138:141], v[180:183], v[38:41]
	v_mfma_f32_16x16x32_bf16 v[30:33], v[126:129], v[194:197], v[30:33]
	v_mfma_f32_16x16x32_bf16 v[22:25], v[138:141], v[194:197], v[22:25]
	v_mfma_f32_16x16x32_bf16 v[14:17], v[126:129], v[208:211], v[14:17]
	v_mfma_f32_16x16x32_bf16 v[6:9], v[138:141], v[208:211], v[6:9]
	v_mfma_f32_16x16x32_bf16 v[62:65], v[134:137], v[176:179], v[62:65]
	v_mfma_f32_16x16x32_bf16 v[54:57], v[142:145], v[176:179], v[54:57]
	v_mfma_f32_16x16x32_bf16 v[46:49], v[134:137], v[190:193], v[46:49]
	v_mfma_f32_16x16x32_bf16 v[38:41], v[142:145], v[190:193], v[38:41]
	v_mfma_f32_16x16x32_bf16 v[30:33], v[134:137], v[198:201], v[30:33]
	v_mfma_f32_16x16x32_bf16 v[22:25], v[142:145], v[198:201], v[22:25]
	v_mfma_f32_16x16x32_bf16 v[14:17], v[134:137], v[212:215], v[14:17]
	v_mfma_f32_16x16x32_bf16 v[6:9], v[142:145], v[212:215], v[6:9]
	v_mfma_f32_16x16x32_bf16 v[58:61], v[146:149], v[172:175], v[58:61]
	v_mfma_f32_16x16x32_bf16 v[50:53], v[154:157], v[172:175], v[50:53]
	v_mfma_f32_16x16x32_bf16 v[42:45], v[146:149], v[180:183], v[42:45]
	v_mfma_f32_16x16x32_bf16 v[34:37], v[154:157], v[180:183], v[34:37]
	v_mfma_f32_16x16x32_bf16 v[26:29], v[146:149], v[194:197], v[26:29]
	v_mfma_f32_16x16x32_bf16 v[18:21], v[154:157], v[194:197], v[18:21]
	v_mfma_f32_16x16x32_bf16 v[10:13], v[146:149], v[208:211], v[10:13]
	v_mfma_f32_16x16x32_bf16 v[2:5], v[154:157], v[208:211], v[2:5]
	v_mfma_f32_16x16x32_bf16 v[58:61], v[150:153], v[176:179], v[58:61]
	v_mfma_f32_16x16x32_bf16 v[50:53], v[158:161], v[176:179], v[50:53]
	v_mfma_f32_16x16x32_bf16 v[42:45], v[150:153], v[190:193], v[42:45]
	v_mfma_f32_16x16x32_bf16 v[34:37], v[158:161], v[190:193], v[34:37]
	v_mfma_f32_16x16x32_bf16 v[26:29], v[150:153], v[198:201], v[26:29]
	v_mfma_f32_16x16x32_bf16 v[18:21], v[158:161], v[198:201], v[18:21]
	v_mfma_f32_16x16x32_bf16 v[10:13], v[150:153], v[212:215], v[10:13]
	v_mfma_f32_16x16x32_bf16 v[2:5], v[158:161], v[212:215], v[2:5]
	s_barrier
	s_setprio 0
	s_add_i32 s61, s61, 2
	s_add_u32 s26, s26, 0x100
	s_addc_u32 s27, s27, 0
	s_add_u32 s59, s59, 0x100
	s_addc_u32 s60, s60, 0
	s_cmp_gt_u32 s61, 29
	s_cbranch_scc0 .LBB0_1428
	s_and_b64 vcc, exec, s[10:11]
	s_cbranch_vccz .LBB0_1431
	s_barrier

.LBB0_1594:
	s_add_u32 s0, s28, 0xfff80080
	s_addc_u32 s1, s29, -1
	s_add_i32 s33, 0, 0x10000
	s_cmp_eq_u32 s61, 28
	s_cselect_b32 s5, s19, s1
	s_cselect_b32 s4, s49, s0
	s_cselect_b32 s3, s17, s60
	s_cselect_b32 s2, s58, s59
	s_add_i32 s55, 0, 0x14000
	ds_read_b128 v[146:149], v143
	ds_read_b128 v[150:153], v143 offset:1024
	ds_read_b128 v[154:157], v143 offset:2048
	ds_read_b128 v[158:161], v143 offset:3072
	ds_read_b128 v[162:165], v143 offset:16384
	ds_read_b128 v[166:169], v143 offset:17408
	ds_read_b128 v[170:173], v143 offset:18432
	ds_read_b128 v[174:177], v143 offset:19456
	s_add_i32 m0, s25, 0xc000
	ds_read_b128 v[178:181], v145
	ds_read_b128 v[182:185], v145 offset:1024
	ds_read_b128 v[186:189], v145 offset:2048
	ds_read_b128 v[190:193], v145 offset:3072
	ds_read_b128 v[194:197], v145 offset:4096
	ds_read_b128 v[198:201], v145 offset:5120
	ds_read_b128 v[208:211], v145 offset:6144
	ds_read_b128 v[212:215], v145 offset:7168
	global_load_lds_dwordx4 v136, s[28:29]
	s_add_i32 m0, s25, 0xe000
	s_nop 0
	global_load_lds_dwordx4 v138, s[28:29]
	s_waitcnt vmcnt(8)
	s_waitcnt lgkmcnt(0)
	s_setprio 1
	s_barrier
	v_mfma_f32_16x16x32_bf16 v[126:129], v[146:149], v[178:181], v[126:129]
	v_mfma_f32_16x16x32_bf16 v[118:121], v[154:157], v[178:181], v[118:121]
	v_mfma_f32_16x16x32_bf16 v[110:113], v[146:149], v[186:189], v[110:113]
	v_mfma_f32_16x16x32_bf16 v[102:105], v[154:157], v[186:189], v[102:105]
	v_mfma_f32_16x16x32_bf16 v[94:97], v[146:149], v[194:197], v[94:97]
	v_mfma_f32_16x16x32_bf16 v[86:89], v[154:157], v[194:197], v[86:89]
	v_mfma_f32_16x16x32_bf16 v[78:81], v[146:149], v[208:211], v[78:81]
	v_mfma_f32_16x16x32_bf16 v[70:73], v[154:157], v[208:211], v[70:73]
	v_mfma_f32_16x16x32_bf16 v[126:129], v[150:153], v[182:185], v[126:129]
	v_mfma_f32_16x16x32_bf16 v[118:121], v[158:161], v[182:185], v[118:121]
	v_mfma_f32_16x16x32_bf16 v[110:113], v[150:153], v[190:193], v[110:113]
	v_mfma_f32_16x16x32_bf16 v[102:105], v[158:161], v[190:193], v[102:105]
	v_mfma_f32_16x16x32_bf16 v[94:97], v[150:153], v[198:201], v[94:97]
	v_mfma_f32_16x16x32_bf16 v[86:89], v[158:161], v[198:201], v[86:89]
	v_mfma_f32_16x16x32_bf16 v[78:81], v[150:153], v[212:215], v[78:81]
	v_mfma_f32_16x16x32_bf16 v[70:73], v[158:161], v[212:215], v[70:73]
	v_mfma_f32_16x16x32_bf16 v[122:125], v[162:165], v[178:181], v[122:125]
	v_mfma_f32_16x16x32_bf16 v[114:117], v[170:173], v[178:181], v[114:117]
	v_mfma_f32_16x16x32_bf16 v[106:109], v[162:165], v[186:189], v[106:109]
	v_mfma_f32_16x16x32_bf16 v[98:101], v[170:173], v[186:189], v[98:101]
	v_mfma_f32_16x16x32_bf16 v[90:93], v[162:165], v[194:197], v[90:93]
	v_mfma_f32_16x16x32_bf16 v[82:85], v[170:173], v[194:197], v[82:85]
	v_mfma_f32_16x16x32_bf16 v[74:77], v[162:165], v[208:211], v[74:77]
	v_mfma_f32_16x16x32_bf16 v[66:69], v[170:173], v[208:211], v[66:69]
	v_mfma_f32_16x16x32_bf16 v[122:125], v[166:169], v[182:185], v[122:125]
	v_mfma_f32_16x16x32_bf16 v[114:117], v[174:177], v[182:185], v[114:117]
	v_mfma_f32_16x16x32_bf16 v[106:109], v[166:169], v[190:193], v[106:109]
	v_mfma_f32_16x16x32_bf16 v[98:101], v[174:177], v[190:193], v[98:101]
	v_mfma_f32_16x16x32_bf16 v[90:93], v[166:169], v[198:201], v[90:93]
	v_mfma_f32_16x16x32_bf16 v[82:85], v[174:177], v[198:201], v[82:85]
	v_mfma_f32_16x16x32_bf16 v[74:77], v[166:169], v[212:215], v[74:77]
	v_mfma_f32_16x16x32_bf16 v[66:69], v[174:177], v[212:215], v[66:69]
	s_barrier
	s_setprio 0
	s_add_i32 s0, s33, s36
	s_mov_b32 m0, s0
	ds_read_b128 v[178:181], v145 offset:16384
	ds_read_b128 v[182:185], v145 offset:17408
	ds_read_b128 v[186:189], v145 offset:18432
	ds_read_b128 v[190:193], v145 offset:19456
	ds_read_b128 v[194:197], v145 offset:20480
	ds_read_b128 v[198:201], v145 offset:21504
	ds_read_b128 v[208:211], v145 offset:22528
	ds_read_b128 v[212:215], v145 offset:23552
	global_load_lds_dwordx4 v202, s[2:3]
	s_add_i32 m0, s0, 0x2000
	s_add_u32 s0, s2, 0x80000
	s_addc_u32 s1, s3, 0
	s_add_i32 s33, s55, s36
	global_load_lds_dwordx4 v130, s[2:3]
	s_mov_b32 m0, s33
	s_nop 0
	global_load_lds_dwordx4 v202, s[0:1]
	s_add_i32 m0, s33, 0x2000
	s_nop 0
	global_load_lds_dwordx4 v130, s[0:1]
	s_mov_b32 m0, s25
	s_nop 0
	global_load_lds_dwordx4 v134, s[4:5]
	s_mov_b32 m0, s27
	s_nop 0
	global_load_lds_dwordx4 v132, s[4:5]
	s_waitcnt vmcnt(8)
	s_waitcnt lgkmcnt(0)
	s_setprio 1
	s_barrier
	v_mfma_f32_16x16x32_bf16 v[62:65], v[146:149], v[178:181], v[62:65]
	v_mfma_f32_16x16x32_bf16 v[54:57], v[154:157], v[178:181], v[54:57]
	v_mfma_f32_16x16x32_bf16 v[46:49], v[146:149], v[186:189], v[46:49]
	v_mfma_f32_16x16x32_bf16 v[38:41], v[154:157], v[186:189], v[38:41]
	v_mfma_f32_16x16x32_bf16 v[30:33], v[146:149], v[194:197], v[30:33]
	v_mfma_f32_16x16x32_bf16 v[22:25], v[154:157], v[194:197], v[22:25]
	v_mfma_f32_16x16x32_bf16 v[14:17], v[146:149], v[208:211], v[14:17]
	v_mfma_f32_16x16x32_bf16 v[6:9], v[154:157], v[208:211], v[6:9]
	v_mfma_f32_16x16x32_bf16 v[62:65], v[150:153], v[182:185], v[62:65]
	v_mfma_f32_16x16x32_bf16 v[54:57], v[158:161], v[182:185], v[54:57]
	v_mfma_f32_16x16x32_bf16 v[46:49], v[150:153], v[190:193], v[46:49]
	v_mfma_f32_16x16x32_bf16 v[38:41], v[158:161], v[190:193], v[38:41]
	v_mfma_f32_16x16x32_bf16 v[30:33], v[150:153], v[198:201], v[30:33]
	v_mfma_f32_16x16x32_bf16 v[22:25], v[158:161], v[198:201], v[22:25]
	v_mfma_f32_16x16x32_bf16 v[14:17], v[150:153], v[212:215], v[14:17]
	v_mfma_f32_16x16x32_bf16 v[6:9], v[158:161], v[212:215], v[6:9]
	v_mfma_f32_16x16x32_bf16 v[58:61], v[162:165], v[178:181], v[58:61]
	v_mfma_f32_16x16x32_bf16 v[50:53], v[170:173], v[178:181], v[50:53]
	v_mfma_f32_16x16x32_bf16 v[42:45], v[162:165], v[186:189], v[42:45]
	v_mfma_f32_16x16x32_bf16 v[34:37], v[170:173], v[186:189], v[34:37]
	v_mfma_f32_16x16x32_bf16 v[26:29], v[162:165], v[194:197], v[26:29]
	v_mfma_f32_16x16x32_bf16 v[18:21], v[170:173], v[194:197], v[18:21]
	v_mfma_f32_16x16x32_bf16 v[10:13], v[162:165], v[208:211], v[10:13]
	v_mfma_f32_16x16x32_bf16 v[2:5], v[170:173], v[208:211], v[2:5]
	v_mfma_f32_16x16x32_bf16 v[58:61], v[166:169], v[182:185], v[58:61]
	v_mfma_f32_16x16x32_bf16 v[50:53], v[174:177], v[182:185], v[50:53]
	v_mfma_f32_16x16x32_bf16 v[42:45], v[166:169], v[190:193], v[42:45]
	v_mfma_f32_16x16x32_bf16 v[34:37], v[174:177], v[190:193], v[34:37]
	v_mfma_f32_16x16x32_bf16 v[26:29], v[166:169], v[198:201], v[26:29]
	v_mfma_f32_16x16x32_bf16 v[18:21], v[174:177], v[198:201], v[18:21]
	v_mfma_f32_16x16x32_bf16 v[10:13], v[166:169], v[212:215], v[10:13]
	v_mfma_f32_16x16x32_bf16 v[2:5], v[174:177], v[212:215], v[2:5]
	s_barrier
	s_setprio 0
	s_add_i32 s33, 0, 0x18000
	s_add_i32 s55, 0, 0x1c000
	ds_read_b128 v[146:149], v143 offset:32768
	ds_read_b128 v[150:153], v143 offset:33792
	ds_read_b128 v[154:157], v143 offset:34816
	ds_read_b128 v[158:161], v143 offset:35840
	ds_read_b128 v[162:165], v143 offset:49152
	ds_read_b128 v[166:169], v143 offset:50176
	ds_read_b128 v[170:173], v143 offset:51200
	ds_read_b128 v[174:177], v143 offset:52224
	s_add_u32 s0, s4, 0x80000
	s_addc_u32 s1, s5, 0
	s_mov_b32 m0, s37
	ds_read_b128 v[178:181], v145 offset:32768
	ds_read_b128 v[182:185], v145 offset:33792
	ds_read_b128 v[186:189], v145 offset:34816
	ds_read_b128 v[190:193], v145 offset:35840
	ds_read_b128 v[194:197], v145 offset:36864
	ds_read_b128 v[198:201], v145 offset:37888
	ds_read_b128 v[208:211], v145 offset:38912
	ds_read_b128 v[212:215], v145 offset:39936
	global_load_lds_dwordx4 v134, s[0:1]
	s_mov_b32 m0, s38
	s_nop 0
	global_load_lds_dwordx4 v132, s[0:1]
	s_waitcnt vmcnt(8)
	s_waitcnt lgkmcnt(0)
	s_setprio 1
	s_barrier
	v_mfma_f32_16x16x32_bf16 v[126:129], v[146:149], v[178:181], v[126:129]
	v_mfma_f32_16x16x32_bf16 v[118:121], v[154:157], v[178:181], v[118:121]
	v_mfma_f32_16x16x32_bf16 v[110:113], v[146:149], v[186:189], v[110:113]
	v_mfma_f32_16x16x32_bf16 v[102:105], v[154:157], v[186:189], v[102:105]
	v_mfma_f32_16x16x32_bf16 v[94:97], v[146:149], v[194:197], v[94:97]
	v_mfma_f32_16x16x32_bf16 v[86:89], v[154:157], v[194:197], v[86:89]
	v_mfma_f32_16x16x32_bf16 v[78:81], v[146:149], v[208:211], v[78:81]
	v_mfma_f32_16x16x32_bf16 v[70:73], v[154:157], v[208:211], v[70:73]
	v_mfma_f32_16x16x32_bf16 v[126:129], v[150:153], v[182:185], v[126:129]
	v_mfma_f32_16x16x32_bf16 v[118:121], v[158:161], v[182:185], v[118:121]
	v_mfma_f32_16x16x32_bf16 v[110:113], v[150:153], v[190:193], v[110:113]
	v_mfma_f32_16x16x32_bf16 v[102:105], v[158:161], v[190:193], v[102:105]
	v_mfma_f32_16x16x32_bf16 v[94:97], v[150:153], v[198:201], v[94:97]
	v_mfma_f32_16x16x32_bf16 v[86:89], v[158:161], v[198:201], v[86:89]
	v_mfma_f32_16x16x32_bf16 v[78:81], v[150:153], v[212:215], v[78:81]
	v_mfma_f32_16x16x32_bf16 v[70:73], v[158:161], v[212:215], v[70:73]
	v_mfma_f32_16x16x32_bf16 v[122:125], v[162:165], v[178:181], v[122:125]
	v_mfma_f32_16x16x32_bf16 v[114:117], v[170:173], v[178:181], v[114:117]
	v_mfma_f32_16x16x32_bf16 v[106:109], v[162:165], v[186:189], v[106:109]
	v_mfma_f32_16x16x32_bf16 v[98:101], v[170:173], v[186:189], v[98:101]
	v_mfma_f32_16x16x32_bf16 v[90:93], v[162:165], v[194:197], v[90:93]
	v_mfma_f32_16x16x32_bf16 v[82:85], v[170:173], v[194:197], v[82:85]
	v_mfma_f32_16x16x32_bf16 v[74:77], v[162:165], v[208:211], v[74:77]
	v_mfma_f32_16x16x32_bf16 v[66:69], v[170:173], v[208:211], v[66:69]
	v_mfma_f32_16x16x32_bf16 v[122:125], v[166:169], v[182:185], v[122:125]
	v_mfma_f32_16x16x32_bf16 v[114:117], v[174:177], v[182:185], v[114:117]
	v_mfma_f32_16x16x32_bf16 v[106:109], v[166:169], v[190:193], v[106:109]
	v_mfma_f32_16x16x32_bf16 v[98:101], v[174:177], v[190:193], v[98:101]
	v_mfma_f32_16x16x32_bf16 v[90:93], v[166:169], v[198:201], v[90:93]
	v_mfma_f32_16x16x32_bf16 v[82:85], v[174:177], v[198:201], v[82:85]
	v_mfma_f32_16x16x32_bf16 v[74:77], v[166:169], v[212:215], v[74:77]
	v_mfma_f32_16x16x32_bf16 v[66:69], v[174:177], v[212:215], v[66:69]
	s_barrier
	s_setprio 0
	s_add_i32 s0, s33, s36
	s_add_u32 s100, s2, 0x80
	s_addc_u32 s101, s3, 0
	s_mov_b32 m0, s0
	ds_read_b128 v[178:181], v145 offset:49152
	ds_read_b128 v[182:185], v145 offset:50176
	ds_read_b128 v[186:189], v145 offset:51200
	ds_read_b128 v[190:193], v145 offset:52224
	ds_read_b128 v[194:197], v145 offset:53248
	ds_read_b128 v[198:201], v145 offset:54272
	ds_read_b128 v[208:211], v145 offset:55296
	ds_read_b128 v[212:215], v145 offset:56320
	global_load_lds_dwordx4 v202, s[100:101]
	s_add_i32 m0, s0, 0x2000
	s_add_u32 s100, s2, 0x80
	s_addc_u32 s101, s3, 0
	s_add_u32 s0, s2, 0x80080
	s_addc_u32 s1, s3, 0
	s_add_i32 s2, s55, s36
	global_load_lds_dwordx4 v130, s[100:101]
	s_mov_b32 m0, s2
	s_nop 0
	global_load_lds_dwordx4 v202, s[0:1]
	s_add_i32 m0, s2, 0x2000
	s_nop 0
	global_load_lds_dwordx4 v130, s[0:1]
	s_add_u32 s100, s4, 0x80
	s_addc_u32 s101, s5, 0
	s_mov_b32 m0, s39
	s_nop 0
	global_load_lds_dwordx4 v134, s[100:101]
	s_add_u32 s100, s4, 0x80
	s_addc_u32 s101, s5, 0
	s_mov_b32 m0, s40
	s_nop 0
	global_load_lds_dwordx4 v132, s[100:101]
	s_waitcnt vmcnt(8)
	s_waitcnt lgkmcnt(0)
	s_setprio 1
	s_barrier
	v_mfma_f32_16x16x32_bf16 v[62:65], v[146:149], v[178:181], v[62:65]
	v_mfma_f32_16x16x32_bf16 v[54:57], v[154:157], v[178:181], v[54:57]
	v_mfma_f32_16x16x32_bf16 v[46:49], v[146:149], v[186:189], v[46:49]
	v_mfma_f32_16x16x32_bf16 v[38:41], v[154:157], v[186:189], v[38:41]
	v_mfma_f32_16x16x32_bf16 v[30:33], v[146:149], v[194:197], v[30:33]
	v_mfma_f32_16x16x32_bf16 v[22:25], v[154:157], v[194:197], v[22:25]
	v_mfma_f32_16x16x32_bf16 v[14:17], v[146:149], v[208:211], v[14:17]
	v_mfma_f32_16x16x32_bf16 v[6:9], v[154:157], v[208:211], v[6:9]
	v_mfma_f32_16x16x32_bf16 v[62:65], v[150:153], v[182:185], v[62:65]
	v_mfma_f32_16x16x32_bf16 v[54:57], v[158:161], v[182:185], v[54:57]
	v_mfma_f32_16x16x32_bf16 v[46:49], v[150:153], v[190:193], v[46:49]
	v_mfma_f32_16x16x32_bf16 v[38:41], v[158:161], v[190:193], v[38:41]
	v_mfma_f32_16x16x32_bf16 v[30:33], v[150:153], v[198:201], v[30:33]
	v_mfma_f32_16x16x32_bf16 v[22:25], v[158:161], v[198:201], v[22:25]
	v_mfma_f32_16x16x32_bf16 v[14:17], v[150:153], v[212:215], v[14:17]
	v_mfma_f32_16x16x32_bf16 v[6:9], v[158:161], v[212:215], v[6:9]
	v_mfma_f32_16x16x32_bf16 v[58:61], v[162:165], v[178:181], v[58:61]
	v_mfma_f32_16x16x32_bf16 v[50:53], v[170:173], v[178:181], v[50:53]
	v_mfma_f32_16x16x32_bf16 v[42:45], v[162:165], v[186:189], v[42:45]
	v_mfma_f32_16x16x32_bf16 v[34:37], v[170:173], v[186:189], v[34:37]
	v_mfma_f32_16x16x32_bf16 v[26:29], v[162:165], v[194:197], v[26:29]
	v_mfma_f32_16x16x32_bf16 v[18:21], v[170:173], v[194:197], v[18:21]
	v_mfma_f32_16x16x32_bf16 v[10:13], v[162:165], v[208:211], v[10:13]
	v_mfma_f32_16x16x32_bf16 v[2:5], v[170:173], v[208:211], v[2:5]
	v_mfma_f32_16x16x32_bf16 v[58:61], v[166:169], v[182:185], v[58:61]
	v_mfma_f32_16x16x32_bf16 v[50:53], v[174:177], v[182:185], v[50:53]
	v_mfma_f32_16x16x32_bf16 v[42:45], v[166:169], v[190:193], v[42:45]
	v_mfma_f32_16x16x32_bf16 v[34:37], v[174:177], v[190:193], v[34:37]
	v_mfma_f32_16x16x32_bf16 v[26:29], v[166:169], v[198:201], v[26:29]
	v_mfma_f32_16x16x32_bf16 v[18:21], v[174:177], v[198:201], v[18:21]
	v_mfma_f32_16x16x32_bf16 v[10:13], v[166:169], v[212:215], v[10:13]
	v_mfma_f32_16x16x32_bf16 v[2:5], v[174:177], v[212:215], v[2:5]
	s_barrier
	s_setprio 0
	s_add_i32 s61, s61, 2
	s_add_u32 s28, s28, 0x100
	s_addc_u32 s29, s29, 0
	s_add_u32 s59, s59, 0x100
	s_addc_u32 s60, s60, 0
	s_cmp_gt_u32 s61, 29
	s_cbranch_scc0 .LBB0_1594
	s_and_b64 vcc, exec, s[14:15]
	s_cbranch_vccz .LBB0_1597
	s_barrier

.LBB0_1718:
	s_add_u32 s18, s4, 0x100
	s_addc_u32 s19, s5, 0
	s_add_i32 s0, 0, 0x10000
	s_cmpk_eq_i32 s59, 0x54
	s_cselect_b32 s23, s9, s19
	s_cselect_b32 s22, s8, s18
	s_cselect_b32 s21, s17, s58
	s_cselect_b32 s20, s16, s49
	s_add_i32 s33, 0, 0x14000
	ds_read_b128 v[78:81], v205
	ds_read_b128 v[82:85], v205 offset:1024
	ds_read_b128 v[94:97], v205 offset:2048
	ds_read_b128 v[98:101], v205 offset:3072
	ds_read_b128 v[106:109], v205 offset:16384
	ds_read_b128 v[110:113], v205 offset:17408
	ds_read_b128 v[126:129], v205 offset:18432
	ds_read_b128 v[134:137], v205 offset:19456
	s_add_i32 m0, s27, 0xc000
	ds_read_b128 v[146:149], v239
	ds_read_b128 v[158:161], v239 offset:1024
	ds_read_b128 v[166:169], v239 offset:2048
	ds_read_b128 v[174:177], v239 offset:3072
	ds_read_b128 v[178:181], v239 offset:4096
	ds_read_b128 v[182:185], v239 offset:5120
	ds_read_b128 v[186:189], v239 offset:6144
	ds_read_b128 v[190:193], v239 offset:7168
	global_load_lds_dwordx4 v214, s[4:5]
	s_add_i32 m0, s27, 0xe000
	s_nop 0
	global_load_lds_dwordx4 v216, s[4:5]
	s_waitcnt vmcnt(8)
	s_waitcnt lgkmcnt(0)
	s_setprio 1
	s_barrier
	v_mfma_f32_16x16x32_bf16 v[170:173], v[78:81], v[146:149], v[170:173]
	v_mfma_f32_16x16x32_bf16 v[162:165], v[94:97], v[146:149], v[162:165]
	v_mfma_f32_16x16x32_bf16 v[142:145], v[78:81], v[166:169], v[142:145]
	v_mfma_f32_16x16x32_bf16 v[138:141], v[94:97], v[166:169], v[138:141]
	v_mfma_f32_16x16x32_bf16 v[118:121], v[78:81], v[178:181], v[118:121]
	v_mfma_f32_16x16x32_bf16 v[114:117], v[94:97], v[178:181], v[114:117]
	v_mfma_f32_16x16x32_bf16 v[86:89], v[78:81], v[186:189], v[86:89]
	v_mfma_f32_16x16x32_bf16 v[74:77], v[94:97], v[186:189], v[74:77]
	v_mfma_f32_16x16x32_bf16 v[170:173], v[82:85], v[158:161], v[170:173]
	v_mfma_f32_16x16x32_bf16 v[162:165], v[98:101], v[158:161], v[162:165]
	v_mfma_f32_16x16x32_bf16 v[142:145], v[82:85], v[174:177], v[142:145]
	v_mfma_f32_16x16x32_bf16 v[138:141], v[98:101], v[174:177], v[138:141]
	v_mfma_f32_16x16x32_bf16 v[118:121], v[82:85], v[182:185], v[118:121]
	v_mfma_f32_16x16x32_bf16 v[114:117], v[98:101], v[182:185], v[114:117]
	v_mfma_f32_16x16x32_bf16 v[86:89], v[82:85], v[190:193], v[86:89]
	v_mfma_f32_16x16x32_bf16 v[74:77], v[98:101], v[190:193], v[74:77]
	v_mfma_f32_16x16x32_bf16 v[154:157], v[106:109], v[146:149], v[154:157]
	v_mfma_f32_16x16x32_bf16 v[130:133], v[106:109], v[166:169], v[130:133]
	v_mfma_f32_16x16x32_bf16 v[122:125], v[126:129], v[166:169], v[122:125]
	v_mfma_f32_16x16x32_bf16 v[102:105], v[106:109], v[178:181], v[102:105]
	v_mfma_f32_16x16x32_bf16 v[90:93], v[126:129], v[178:181], v[90:93]
	v_mfma_f32_16x16x32_bf16 v[70:73], v[106:109], v[186:189], v[70:73]
	v_mfma_f32_16x16x32_bf16 v[66:69], v[126:129], v[186:189], v[66:69]
	v_mfma_f32_16x16x32_bf16 v[154:157], v[110:113], v[158:161], v[154:157]
	v_mfma_f32_16x16x32_bf16 v[146:149], v[126:129], v[146:149], v[150:153]
	v_mfma_f32_16x16x32_bf16 v[130:133], v[110:113], v[174:177], v[130:133]
	v_mfma_f32_16x16x32_bf16 v[122:125], v[134:137], v[174:177], v[122:125]
	v_mfma_f32_16x16x32_bf16 v[102:105], v[110:113], v[182:185], v[102:105]
	v_mfma_f32_16x16x32_bf16 v[90:93], v[134:137], v[182:185], v[90:93]
	v_mfma_f32_16x16x32_bf16 v[70:73], v[110:113], v[190:193], v[70:73]
	v_mfma_f32_16x16x32_bf16 v[66:69], v[134:137], v[190:193], v[66:69]
	v_mfma_f32_16x16x32_bf16 v[146:149], v[134:137], v[158:161], v[146:149]
	s_barrier
	s_setprio 0
	s_add_i32 s0, s0, s26
	s_mov_b32 m0, s0
	ds_read_b128 v[150:153], v239 offset:16384
	ds_read_b128 v[158:161], v239 offset:17408
	ds_read_b128 v[166:169], v239 offset:18432
	ds_read_b128 v[174:177], v239 offset:19456
	ds_read_b128 v[178:181], v239 offset:20480
	ds_read_b128 v[182:185], v239 offset:21504
	ds_read_b128 v[186:189], v239 offset:22528
	ds_read_b128 v[190:193], v239 offset:23552
	global_load_lds_dwordx4 v202, s[20:21]
	s_add_i32 m0, s0, 0x2000
	s_add_u32 s0, s20, 0x160000
	s_addc_u32 s1, s21, 0
	s_add_i32 s4, s33, s26
	global_load_lds_dwordx4 v208, s[20:21]
	s_mov_b32 m0, s4
	s_nop 0
	global_load_lds_dwordx4 v202, s[0:1]
	s_add_i32 m0, s4, 0x2000
	s_nop 0
	global_load_lds_dwordx4 v208, s[0:1]
	s_mov_b32 m0, s27
	s_nop 0
	global_load_lds_dwordx4 v212, s[22:23]
	s_mov_b32 m0, s28
	s_nop 0
	global_load_lds_dwordx4 v210, s[22:23]
	s_waitcnt vmcnt(8)
	s_waitcnt lgkmcnt(0)
	s_setprio 1
	s_barrier
	v_mfma_f32_16x16x32_bf16 v[62:65], v[78:81], v[150:153], v[62:65]
	v_mfma_f32_16x16x32_bf16 v[58:61], v[94:97], v[150:153], v[58:61]
	v_mfma_f32_16x16x32_bf16 v[46:49], v[78:81], v[166:169], v[46:49]
	v_mfma_f32_16x16x32_bf16 v[42:45], v[94:97], v[166:169], v[42:45]
	v_mfma_f32_16x16x32_bf16 v[30:33], v[78:81], v[178:181], v[30:33]
	v_mfma_f32_16x16x32_bf16 v[26:29], v[94:97], v[178:181], v[26:29]
	v_mfma_f32_16x16x32_bf16 v[14:17], v[78:81], v[186:189], v[14:17]
	v_mfma_f32_16x16x32_bf16 v[10:13], v[94:97], v[186:189], v[10:13]
	v_mfma_f32_16x16x32_bf16 v[62:65], v[82:85], v[158:161], v[62:65]
	v_mfma_f32_16x16x32_bf16 v[58:61], v[98:101], v[158:161], v[58:61]
	v_mfma_f32_16x16x32_bf16 v[46:49], v[82:85], v[174:177], v[46:49]
	v_mfma_f32_16x16x32_bf16 v[42:45], v[98:101], v[174:177], v[42:45]
	v_mfma_f32_16x16x32_bf16 v[30:33], v[82:85], v[182:185], v[30:33]
	v_mfma_f32_16x16x32_bf16 v[26:29], v[98:101], v[182:185], v[26:29]
	v_mfma_f32_16x16x32_bf16 v[14:17], v[82:85], v[190:193], v[14:17]
	v_mfma_f32_16x16x32_bf16 v[10:13], v[98:101], v[190:193], v[10:13]
	v_mfma_f32_16x16x32_bf16 v[54:57], v[106:109], v[150:153], v[54:57]
	v_mfma_f32_16x16x32_bf16 v[50:53], v[126:129], v[150:153], v[50:53]
	v_mfma_f32_16x16x32_bf16 v[38:41], v[106:109], v[166:169], v[38:41]
	v_mfma_f32_16x16x32_bf16 v[34:37], v[126:129], v[166:169], v[34:37]
	v_mfma_f32_16x16x32_bf16 v[22:25], v[106:109], v[178:181], v[22:25]
	v_mfma_f32_16x16x32_bf16 v[18:21], v[126:129], v[178:181], v[18:21]
	v_mfma_f32_16x16x32_bf16 v[6:9], v[106:109], v[186:189], v[6:9]
	v_mfma_f32_16x16x32_bf16 v[2:5], v[126:129], v[186:189], v[2:5]
	v_mfma_f32_16x16x32_bf16 v[54:57], v[110:113], v[158:161], v[54:57]
	v_mfma_f32_16x16x32_bf16 v[50:53], v[134:137], v[158:161], v[50:53]
	v_mfma_f32_16x16x32_bf16 v[38:41], v[110:113], v[174:177], v[38:41]
	v_mfma_f32_16x16x32_bf16 v[34:37], v[134:137], v[174:177], v[34:37]
	v_mfma_f32_16x16x32_bf16 v[22:25], v[110:113], v[182:185], v[22:25]
	v_mfma_f32_16x16x32_bf16 v[18:21], v[134:137], v[182:185], v[18:21]
	v_mfma_f32_16x16x32_bf16 v[6:9], v[110:113], v[190:193], v[6:9]
	v_mfma_f32_16x16x32_bf16 v[2:5], v[134:137], v[190:193], v[2:5]
	s_barrier
	s_setprio 0
	s_add_i32 s4, 0, 0x18000
	s_add_i32 s5, 0, 0x1c000
	ds_read_b128 v[78:81], v205 offset:32768
	ds_read_b128 v[82:85], v205 offset:33792
	ds_read_b128 v[94:97], v205 offset:34816
	ds_read_b128 v[98:101], v205 offset:35840
	ds_read_b128 v[106:109], v205 offset:49152
	ds_read_b128 v[110:113], v205 offset:50176
	ds_read_b128 v[126:129], v205 offset:51200
	ds_read_b128 v[134:137], v205 offset:52224
	s_add_u32 s0, s22, 0x160000
	s_addc_u32 s1, s23, 0
	s_mov_b32 m0, s29
	ds_read_b128 v[150:153], v239 offset:32768
	ds_read_b128 v[158:161], v239 offset:33792
	ds_read_b128 v[166:169], v239 offset:34816
	ds_read_b128 v[174:177], v239 offset:35840
	ds_read_b128 v[178:181], v239 offset:36864
	ds_read_b128 v[182:185], v239 offset:37888
	ds_read_b128 v[186:189], v239 offset:38912
	ds_read_b128 v[190:193], v239 offset:39936
	global_load_lds_dwordx4 v212, s[0:1]
	s_mov_b32 m0, s30
	s_nop 0
	global_load_lds_dwordx4 v210, s[0:1]
	s_waitcnt vmcnt(8)
	s_waitcnt lgkmcnt(0)
	s_setprio 1
	s_barrier
	v_mfma_f32_16x16x32_bf16 v[170:173], v[78:81], v[150:153], v[170:173]
	v_mfma_f32_16x16x32_bf16 v[162:165], v[94:97], v[150:153], v[162:165]
	v_mfma_f32_16x16x32_bf16 v[142:145], v[78:81], v[166:169], v[142:145]
	v_mfma_f32_16x16x32_bf16 v[138:141], v[94:97], v[166:169], v[138:141]
	v_mfma_f32_16x16x32_bf16 v[118:121], v[78:81], v[178:181], v[118:121]
	v_mfma_f32_16x16x32_bf16 v[114:117], v[94:97], v[178:181], v[114:117]
	v_mfma_f32_16x16x32_bf16 v[86:89], v[78:81], v[186:189], v[86:89]
	v_mfma_f32_16x16x32_bf16 v[74:77], v[94:97], v[186:189], v[74:77]
	v_mfma_f32_16x16x32_bf16 v[170:173], v[82:85], v[158:161], v[170:173]
	v_mfma_f32_16x16x32_bf16 v[162:165], v[98:101], v[158:161], v[162:165]
	v_mfma_f32_16x16x32_bf16 v[142:145], v[82:85], v[174:177], v[142:145]
	v_mfma_f32_16x16x32_bf16 v[138:141], v[98:101], v[174:177], v[138:141]
	v_mfma_f32_16x16x32_bf16 v[118:121], v[82:85], v[182:185], v[118:121]
	v_mfma_f32_16x16x32_bf16 v[114:117], v[98:101], v[182:185], v[114:117]
	v_mfma_f32_16x16x32_bf16 v[86:89], v[82:85], v[190:193], v[86:89]
	v_mfma_f32_16x16x32_bf16 v[74:77], v[98:101], v[190:193], v[74:77]
	v_mfma_f32_16x16x32_bf16 v[154:157], v[106:109], v[150:153], v[154:157]
	v_mfma_f32_16x16x32_bf16 v[146:149], v[126:129], v[150:153], v[146:149]
	v_mfma_f32_16x16x32_bf16 v[130:133], v[106:109], v[166:169], v[130:133]
	v_mfma_f32_16x16x32_bf16 v[122:125], v[126:129], v[166:169], v[122:125]
	v_mfma_f32_16x16x32_bf16 v[102:105], v[106:109], v[178:181], v[102:105]
	v_mfma_f32_16x16x32_bf16 v[90:93], v[126:129], v[178:181], v[90:93]
	v_mfma_f32_16x16x32_bf16 v[70:73], v[106:109], v[186:189], v[70:73]
	v_mfma_f32_16x16x32_bf16 v[66:69], v[126:129], v[186:189], v[66:69]
	v_mfma_f32_16x16x32_bf16 v[154:157], v[110:113], v[158:161], v[154:157]
	v_mfma_f32_16x16x32_bf16 v[150:153], v[134:137], v[158:161], v[146:149]
	v_mfma_f32_16x16x32_bf16 v[130:133], v[110:113], v[174:177], v[130:133]
	v_mfma_f32_16x16x32_bf16 v[122:125], v[134:137], v[174:177], v[122:125]
	v_mfma_f32_16x16x32_bf16 v[102:105], v[110:113], v[182:185], v[102:105]
	v_mfma_f32_16x16x32_bf16 v[90:93], v[134:137], v[182:185], v[90:93]
	v_mfma_f32_16x16x32_bf16 v[70:73], v[110:113], v[190:193], v[70:73]
	v_mfma_f32_16x16x32_bf16 v[66:69], v[134:137], v[190:193], v[66:69]
	s_barrier
	s_setprio 0
	s_add_i32 s0, s4, s26
	s_add_u32 s100, s20, 0x80
	s_addc_u32 s101, s21, 0
	s_mov_b32 m0, s0
	ds_read_b128 v[146:149], v239 offset:49152
	ds_read_b128 v[158:161], v239 offset:50176
	ds_read_b128 v[166:169], v239 offset:51200
	ds_read_b128 v[174:177], v239 offset:52224
	ds_read_b128 v[178:181], v239 offset:53248
	ds_read_b128 v[182:185], v239 offset:54272
	ds_read_b128 v[186:189], v239 offset:55296
	ds_read_b128 v[190:193], v239 offset:56320
	global_load_lds_dwordx4 v202, s[100:101]
	s_add_i32 m0, s0, 0x2000
	s_add_u32 s100, s20, 0x80
	s_addc_u32 s101, s21, 0
	s_add_u32 s0, s20, 0x160080
	s_addc_u32 s1, s21, 0
	s_add_i32 s4, s5, s26
	global_load_lds_dwordx4 v208, s[100:101]
	s_mov_b32 m0, s4
	s_nop 0
	global_load_lds_dwordx4 v202, s[0:1]
	s_add_i32 m0, s4, 0x2000
	s_nop 0
	global_load_lds_dwordx4 v208, s[0:1]
	s_add_u32 s100, s22, 0x80
	s_addc_u32 s101, s23, 0
	s_mov_b32 m0, s35
	s_nop 0
	global_load_lds_dwordx4 v212, s[100:101]
	s_add_u32 s100, s22, 0x80
	s_addc_u32 s101, s23, 0
	s_mov_b32 m0, s36
	s_nop 0
	global_load_lds_dwordx4 v210, s[100:101]
	s_waitcnt vmcnt(8)
	s_waitcnt lgkmcnt(0)
	s_setprio 1
	s_barrier
	v_mfma_f32_16x16x32_bf16 v[62:65], v[78:81], v[146:149], v[62:65]
	v_mfma_f32_16x16x32_bf16 v[58:61], v[94:97], v[146:149], v[58:61]
	v_mfma_f32_16x16x32_bf16 v[46:49], v[78:81], v[166:169], v[46:49]
	v_mfma_f32_16x16x32_bf16 v[42:45], v[94:97], v[166:169], v[42:45]
	v_mfma_f32_16x16x32_bf16 v[30:33], v[78:81], v[178:181], v[30:33]
	v_mfma_f32_16x16x32_bf16 v[26:29], v[94:97], v[178:181], v[26:29]
	v_mfma_f32_16x16x32_bf16 v[14:17], v[78:81], v[186:189], v[14:17]
	v_mfma_f32_16x16x32_bf16 v[10:13], v[94:97], v[186:189], v[10:13]
	v_mfma_f32_16x16x32_bf16 v[62:65], v[82:85], v[158:161], v[62:65]
	v_mfma_f32_16x16x32_bf16 v[58:61], v[98:101], v[158:161], v[58:61]
	v_mfma_f32_16x16x32_bf16 v[46:49], v[82:85], v[174:177], v[46:49]
	v_mfma_f32_16x16x32_bf16 v[42:45], v[98:101], v[174:177], v[42:45]
	v_mfma_f32_16x16x32_bf16 v[30:33], v[82:85], v[182:185], v[30:33]
	v_mfma_f32_16x16x32_bf16 v[26:29], v[98:101], v[182:185], v[26:29]
	v_mfma_f32_16x16x32_bf16 v[14:17], v[82:85], v[190:193], v[14:17]
	v_mfma_f32_16x16x32_bf16 v[10:13], v[98:101], v[190:193], v[10:13]
	v_mfma_f32_16x16x32_bf16 v[54:57], v[106:109], v[146:149], v[54:57]
	v_mfma_f32_16x16x32_bf16 v[50:53], v[126:129], v[146:149], v[50:53]
	v_mfma_f32_16x16x32_bf16 v[38:41], v[106:109], v[166:169], v[38:41]
	v_mfma_f32_16x16x32_bf16 v[34:37], v[126:129], v[166:169], v[34:37]
	v_mfma_f32_16x16x32_bf16 v[22:25], v[106:109], v[178:181], v[22:25]
	v_mfma_f32_16x16x32_bf16 v[18:21], v[126:129], v[178:181], v[18:21]
	v_mfma_f32_16x16x32_bf16 v[6:9], v[106:109], v[186:189], v[6:9]
	v_mfma_f32_16x16x32_bf16 v[2:5], v[126:129], v[186:189], v[2:5]
	v_mfma_f32_16x16x32_bf16 v[54:57], v[110:113], v[158:161], v[54:57]
	v_mfma_f32_16x16x32_bf16 v[50:53], v[134:137], v[158:161], v[50:53]
	v_mfma_f32_16x16x32_bf16 v[38:41], v[110:113], v[174:177], v[38:41]
	v_mfma_f32_16x16x32_bf16 v[34:37], v[134:137], v[174:177], v[34:37]
	v_mfma_f32_16x16x32_bf16 v[22:25], v[110:113], v[182:185], v[22:25]
	v_mfma_f32_16x16x32_bf16 v[18:21], v[134:137], v[182:185], v[18:21]
	v_mfma_f32_16x16x32_bf16 v[6:9], v[110:113], v[190:193], v[6:9]
	v_mfma_f32_16x16x32_bf16 v[2:5], v[134:137], v[190:193], v[2:5]
	s_barrier
	s_setprio 0
	s_add_i32 s59, s59, 2
	s_add_u32 s49, s49, 0x100
	s_addc_u32 s58, s58, 0
	s_cmpk_gt_u32 s59, 0x55
	s_mov_b64 s[4:5], s[18:19]
	s_cbranch_scc0 .LBB0_1718
	s_and_b64 vcc, exec, s[14:15]
	s_cbranch_vccz .LBB0_1721
	s_barrier

.LBB0_1739:
	s_add_u32 s16, s14, 0x100
	s_addc_u32 s17, s15, 0
	s_add_i32 s0, 0, 0x10000
	s_cmp_eq_u32 s49, 4
	s_cselect_b32 s21, s9, s17
	s_cselect_b32 s20, s8, s16
	s_cselect_b32 s19, s11, s41
	s_cselect_b32 s18, s10, s40
	s_add_i32 s33, 0, 0x14000
	ds_read_b128 v[140:143], v136
	ds_read_b128 v[144:147], v136 offset:1024
	ds_read_b128 v[148:151], v136 offset:2048
	ds_read_b128 v[152:155], v136 offset:3072
	ds_read_b128 v[156:159], v136 offset:16384
	ds_read_b128 v[160:163], v136 offset:17408
	ds_read_b128 v[164:167], v136 offset:18432
	ds_read_b128 v[168:171], v136 offset:19456
	s_add_i32 m0, s23, 0xc000
	ds_read_b128 v[172:175], v139
	ds_read_b128 v[176:179], v139 offset:1024
	ds_read_b128 v[180:183], v139 offset:2048
	ds_read_b128 v[184:187], v139 offset:3072
	ds_read_b128 v[188:191], v139 offset:4096
	ds_read_b128 v[192:195], v139 offset:5120
	ds_read_b128 v[196:199], v139 offset:6144
	ds_read_b128 v[208:211], v139 offset:7168
	global_load_lds_dwordx4 v132, s[14:15]
	s_add_i32 m0, s23, 0xe000
	s_nop 0
	global_load_lds_dwordx4 v134, s[14:15]
	s_waitcnt vmcnt(8)
	s_waitcnt lgkmcnt(0)
	s_setprio 1
	s_barrier
	v_mfma_f32_16x16x32_bf16 v[126:129], v[140:143], v[172:175], v[126:129]
	v_mfma_f32_16x16x32_bf16 v[122:125], v[148:151], v[172:175], v[122:125]
	v_mfma_f32_16x16x32_bf16 v[118:121], v[140:143], v[180:183], v[118:121]
	v_mfma_f32_16x16x32_bf16 v[114:117], v[148:151], v[180:183], v[114:117]
	v_mfma_f32_16x16x32_bf16 v[106:109], v[140:143], v[188:191], v[106:109]
	v_mfma_f32_16x16x32_bf16 v[98:101], v[148:151], v[188:191], v[98:101]
	v_mfma_f32_16x16x32_bf16 v[90:93], v[140:143], v[196:199], v[90:93]
	v_mfma_f32_16x16x32_bf16 v[82:85], v[148:151], v[196:199], v[82:85]
	v_mfma_f32_16x16x32_bf16 v[126:129], v[144:147], v[176:179], v[126:129]
	v_mfma_f32_16x16x32_bf16 v[122:125], v[152:155], v[176:179], v[122:125]
	v_mfma_f32_16x16x32_bf16 v[118:121], v[144:147], v[184:187], v[118:121]
	v_mfma_f32_16x16x32_bf16 v[114:117], v[152:155], v[184:187], v[114:117]
	v_mfma_f32_16x16x32_bf16 v[106:109], v[144:147], v[192:195], v[106:109]
	v_mfma_f32_16x16x32_bf16 v[98:101], v[152:155], v[192:195], v[98:101]
	v_mfma_f32_16x16x32_bf16 v[90:93], v[144:147], v[208:211], v[90:93]
	v_mfma_f32_16x16x32_bf16 v[82:85], v[152:155], v[208:211], v[82:85]
	v_mfma_f32_16x16x32_bf16 v[110:113], v[156:159], v[172:175], v[110:113]
	v_mfma_f32_16x16x32_bf16 v[102:105], v[164:167], v[172:175], v[102:105]
	v_mfma_f32_16x16x32_bf16 v[94:97], v[156:159], v[180:183], v[94:97]
	v_mfma_f32_16x16x32_bf16 v[86:89], v[164:167], v[180:183], v[86:89]
	v_mfma_f32_16x16x32_bf16 v[78:81], v[156:159], v[188:191], v[78:81]
	v_mfma_f32_16x16x32_bf16 v[74:77], v[164:167], v[188:191], v[74:77]
	v_mfma_f32_16x16x32_bf16 v[70:73], v[156:159], v[196:199], v[70:73]
	v_mfma_f32_16x16x32_bf16 v[66:69], v[164:167], v[196:199], v[66:69]
	v_mfma_f32_16x16x32_bf16 v[110:113], v[160:163], v[176:179], v[110:113]
	v_mfma_f32_16x16x32_bf16 v[102:105], v[168:171], v[176:179], v[102:105]
	v_mfma_f32_16x16x32_bf16 v[94:97], v[160:163], v[184:187], v[94:97]
	v_mfma_f32_16x16x32_bf16 v[86:89], v[168:171], v[184:187], v[86:89]
	v_mfma_f32_16x16x32_bf16 v[78:81], v[160:163], v[192:195], v[78:81]
	v_mfma_f32_16x16x32_bf16 v[74:77], v[168:171], v[192:195], v[74:77]
	v_mfma_f32_16x16x32_bf16 v[70:73], v[160:163], v[208:211], v[70:73]
	v_mfma_f32_16x16x32_bf16 v[66:69], v[168:171], v[208:211], v[66:69]
	s_barrier
	s_setprio 0
	s_add_i32 s0, s0, s22
	s_mov_b32 m0, s0
	ds_read_b128 v[172:175], v139 offset:16384
	ds_read_b128 v[176:179], v139 offset:17408
	ds_read_b128 v[180:183], v139 offset:18432
	ds_read_b128 v[184:187], v139 offset:19456
	ds_read_b128 v[188:191], v139 offset:20480
	ds_read_b128 v[192:195], v139 offset:21504
	ds_read_b128 v[196:199], v139 offset:22528
	ds_read_b128 v[208:211], v139 offset:23552
	global_load_lds_dwordx4 v202, s[18:19]
	s_add_i32 m0, s0, 0x2000
	s_add_u32 s0, s18, 0x160000
	s_addc_u32 s1, s19, 0
	s_add_i32 s14, s33, s22
	global_load_lds_dwordx4 v130, s[18:19]
	s_mov_b32 m0, s14
	s_nop 0
	global_load_lds_dwordx4 v202, s[0:1]
	s_add_i32 m0, s14, 0x2000
	s_nop 0
	global_load_lds_dwordx4 v130, s[0:1]
	s_mov_b32 m0, s23
	s_nop 0
	global_load_lds_dwordx4 v202, s[20:21]
	s_mov_b32 m0, s26
	s_nop 0
	global_load_lds_dwordx4 v130, s[20:21]
	s_waitcnt vmcnt(8)
	s_waitcnt lgkmcnt(0)
	s_setprio 1
	s_barrier
	v_mfma_f32_16x16x32_bf16 v[62:65], v[140:143], v[172:175], v[62:65]
	v_mfma_f32_16x16x32_bf16 v[58:61], v[148:151], v[172:175], v[58:61]
	v_mfma_f32_16x16x32_bf16 v[54:57], v[140:143], v[180:183], v[54:57]
	v_mfma_f32_16x16x32_bf16 v[50:53], v[148:151], v[180:183], v[50:53]
	v_mfma_f32_16x16x32_bf16 v[38:41], v[140:143], v[188:191], v[38:41]
	v_mfma_f32_16x16x32_bf16 v[34:37], v[148:151], v[188:191], v[34:37]
	v_mfma_f32_16x16x32_bf16 v[22:25], v[140:143], v[196:199], v[22:25]
	v_mfma_f32_16x16x32_bf16 v[18:21], v[148:151], v[196:199], v[18:21]
	v_mfma_f32_16x16x32_bf16 v[62:65], v[144:147], v[176:179], v[62:65]
	v_mfma_f32_16x16x32_bf16 v[58:61], v[152:155], v[176:179], v[58:61]
	v_mfma_f32_16x16x32_bf16 v[54:57], v[144:147], v[184:187], v[54:57]
	v_mfma_f32_16x16x32_bf16 v[50:53], v[152:155], v[184:187], v[50:53]
	v_mfma_f32_16x16x32_bf16 v[38:41], v[144:147], v[192:195], v[38:41]
	v_mfma_f32_16x16x32_bf16 v[34:37], v[152:155], v[192:195], v[34:37]
	v_mfma_f32_16x16x32_bf16 v[22:25], v[144:147], v[208:211], v[22:25]
	v_mfma_f32_16x16x32_bf16 v[18:21], v[152:155], v[208:211], v[18:21]
	v_mfma_f32_16x16x32_bf16 v[46:49], v[156:159], v[172:175], v[46:49]
	v_mfma_f32_16x16x32_bf16 v[42:45], v[164:167], v[172:175], v[42:45]
	v_mfma_f32_16x16x32_bf16 v[30:33], v[156:159], v[180:183], v[30:33]
	v_mfma_f32_16x16x32_bf16 v[26:29], v[164:167], v[180:183], v[26:29]
	v_mfma_f32_16x16x32_bf16 v[14:17], v[156:159], v[188:191], v[14:17]
	v_mfma_f32_16x16x32_bf16 v[10:13], v[164:167], v[188:191], v[10:13]
	v_mfma_f32_16x16x32_bf16 v[6:9], v[156:159], v[196:199], v[6:9]
	v_mfma_f32_16x16x32_bf16 v[2:5], v[164:167], v[196:199], v[2:5]
	v_mfma_f32_16x16x32_bf16 v[46:49], v[160:163], v[176:179], v[46:49]
	v_mfma_f32_16x16x32_bf16 v[42:45], v[168:171], v[176:179], v[42:45]
	v_mfma_f32_16x16x32_bf16 v[30:33], v[160:163], v[184:187], v[30:33]
	v_mfma_f32_16x16x32_bf16 v[26:29], v[168:171], v[184:187], v[26:29]
	v_mfma_f32_16x16x32_bf16 v[14:17], v[160:163], v[192:195], v[14:17]
	v_mfma_f32_16x16x32_bf16 v[10:13], v[168:171], v[192:195], v[10:13]
	v_mfma_f32_16x16x32_bf16 v[6:9], v[160:163], v[208:211], v[6:9]
	v_mfma_f32_16x16x32_bf16 v[2:5], v[168:171], v[208:211], v[2:5]
	s_barrier
	s_setprio 0
	s_add_i32 s14, 0, 0x18000
	s_add_i32 s15, 0, 0x1c000
	ds_read_b128 v[140:143], v136 offset:32768
	ds_read_b128 v[144:147], v136 offset:33792
	ds_read_b128 v[148:151], v136 offset:34816
	ds_read_b128 v[152:155], v136 offset:35840
	ds_read_b128 v[156:159], v136 offset:49152
	ds_read_b128 v[160:163], v136 offset:50176
	ds_read_b128 v[164:167], v136 offset:51200
	ds_read_b128 v[168:171], v136 offset:52224
	s_add_u32 s0, s20, 0x160000
	s_addc_u32 s1, s21, 0
	s_mov_b32 m0, s27
	ds_read_b128 v[172:175], v139 offset:32768
	ds_read_b128 v[176:179], v139 offset:33792
	ds_read_b128 v[180:183], v139 offset:34816
	ds_read_b128 v[184:187], v139 offset:35840
	ds_read_b128 v[188:191], v139 offset:36864
	ds_read_b128 v[192:195], v139 offset:37888
	ds_read_b128 v[196:199], v139 offset:38912
	ds_read_b128 v[208:211], v139 offset:39936
	global_load_lds_dwordx4 v202, s[0:1]
	s_mov_b32 m0, s28
	s_nop 0
	global_load_lds_dwordx4 v130, s[0:1]
	s_waitcnt vmcnt(8)
	s_waitcnt lgkmcnt(0)
	s_setprio 1
	s_barrier
	v_mfma_f32_16x16x32_bf16 v[126:129], v[140:143], v[172:175], v[126:129]
	v_mfma_f32_16x16x32_bf16 v[122:125], v[148:151], v[172:175], v[122:125]
	v_mfma_f32_16x16x32_bf16 v[118:121], v[140:143], v[180:183], v[118:121]
	v_mfma_f32_16x16x32_bf16 v[114:117], v[148:151], v[180:183], v[114:117]
	v_mfma_f32_16x16x32_bf16 v[106:109], v[140:143], v[188:191], v[106:109]
	v_mfma_f32_16x16x32_bf16 v[98:101], v[148:151], v[188:191], v[98:101]
	v_mfma_f32_16x16x32_bf16 v[90:93], v[140:143], v[196:199], v[90:93]
	v_mfma_f32_16x16x32_bf16 v[82:85], v[148:151], v[196:199], v[82:85]
	v_mfma_f32_16x16x32_bf16 v[126:129], v[144:147], v[176:179], v[126:129]
	v_mfma_f32_16x16x32_bf16 v[122:125], v[152:155], v[176:179], v[122:125]
	v_mfma_f32_16x16x32_bf16 v[118:121], v[144:147], v[184:187], v[118:121]
	v_mfma_f32_16x16x32_bf16 v[114:117], v[152:155], v[184:187], v[114:117]
	v_mfma_f32_16x16x32_bf16 v[106:109], v[144:147], v[192:195], v[106:109]
	v_mfma_f32_16x16x32_bf16 v[98:101], v[152:155], v[192:195], v[98:101]
	v_mfma_f32_16x16x32_bf16 v[90:93], v[144:147], v[208:211], v[90:93]
	v_mfma_f32_16x16x32_bf16 v[82:85], v[152:155], v[208:211], v[82:85]
	v_mfma_f32_16x16x32_bf16 v[110:113], v[156:159], v[172:175], v[110:113]
	v_mfma_f32_16x16x32_bf16 v[102:105], v[164:167], v[172:175], v[102:105]
	v_mfma_f32_16x16x32_bf16 v[94:97], v[156:159], v[180:183], v[94:97]
	v_mfma_f32_16x16x32_bf16 v[86:89], v[164:167], v[180:183], v[86:89]
	v_mfma_f32_16x16x32_bf16 v[78:81], v[156:159], v[188:191], v[78:81]
	v_mfma_f32_16x16x32_bf16 v[74:77], v[164:167], v[188:191], v[74:77]
	v_mfma_f32_16x16x32_bf16 v[70:73], v[156:159], v[196:199], v[70:73]
	v_mfma_f32_16x16x32_bf16 v[66:69], v[164:167], v[196:199], v[66:69]
	v_mfma_f32_16x16x32_bf16 v[110:113], v[160:163], v[176:179], v[110:113]
	v_mfma_f32_16x16x32_bf16 v[102:105], v[168:171], v[176:179], v[102:105]
	v_mfma_f32_16x16x32_bf16 v[94:97], v[160:163], v[184:187], v[94:97]
	v_mfma_f32_16x16x32_bf16 v[86:89], v[168:171], v[184:187], v[86:89]
	v_mfma_f32_16x16x32_bf16 v[78:81], v[160:163], v[192:195], v[78:81]
	v_mfma_f32_16x16x32_bf16 v[74:77], v[168:171], v[192:195], v[74:77]
	v_mfma_f32_16x16x32_bf16 v[70:73], v[160:163], v[208:211], v[70:73]
	v_mfma_f32_16x16x32_bf16 v[66:69], v[168:171], v[208:211], v[66:69]
	s_barrier
	s_setprio 0
	s_add_i32 s0, s14, s22
	s_add_u32 s100, s18, 0x80
	s_addc_u32 s101, s19, 0
	s_mov_b32 m0, s0
	ds_read_b128 v[172:175], v139 offset:49152
	ds_read_b128 v[176:179], v139 offset:50176
	ds_read_b128 v[180:183], v139 offset:51200
	ds_read_b128 v[184:187], v139 offset:52224
	ds_read_b128 v[188:191], v139 offset:53248
	ds_read_b128 v[192:195], v139 offset:54272
	ds_read_b128 v[196:199], v139 offset:55296
	ds_read_b128 v[208:211], v139 offset:56320
	global_load_lds_dwordx4 v202, s[100:101]
	s_add_i32 m0, s0, 0x2000
	s_add_u32 s100, s18, 0x80
	s_addc_u32 s101, s19, 0
	s_add_u32 s0, s18, 0x160080
	s_addc_u32 s1, s19, 0
	s_add_i32 s14, s15, s22
	global_load_lds_dwordx4 v130, s[100:101]
	s_mov_b32 m0, s14
	s_nop 0
	global_load_lds_dwordx4 v202, s[0:1]
	s_add_i32 m0, s14, 0x2000
	s_nop 0
	global_load_lds_dwordx4 v130, s[0:1]
	s_add_u32 s100, s20, 0x80
	s_addc_u32 s101, s21, 0
	s_mov_b32 m0, s29
	s_nop 0
	global_load_lds_dwordx4 v202, s[100:101]
	s_add_u32 s100, s20, 0x80
	s_addc_u32 s101, s21, 0
	s_mov_b32 m0, s30
	s_nop 0
	global_load_lds_dwordx4 v130, s[100:101]
	s_waitcnt vmcnt(8)
	s_waitcnt lgkmcnt(0)
	s_setprio 1
	s_barrier
	v_mfma_f32_16x16x32_bf16 v[62:65], v[140:143], v[172:175], v[62:65]
	v_mfma_f32_16x16x32_bf16 v[58:61], v[148:151], v[172:175], v[58:61]
	v_mfma_f32_16x16x32_bf16 v[54:57], v[140:143], v[180:183], v[54:57]
	v_mfma_f32_16x16x32_bf16 v[50:53], v[148:151], v[180:183], v[50:53]
	v_mfma_f32_16x16x32_bf16 v[38:41], v[140:143], v[188:191], v[38:41]
	v_mfma_f32_16x16x32_bf16 v[34:37], v[148:151], v[188:191], v[34:37]
	v_mfma_f32_16x16x32_bf16 v[22:25], v[140:143], v[196:199], v[22:25]
	v_mfma_f32_16x16x32_bf16 v[18:21], v[148:151], v[196:199], v[18:21]
	v_mfma_f32_16x16x32_bf16 v[62:65], v[144:147], v[176:179], v[62:65]
	v_mfma_f32_16x16x32_bf16 v[58:61], v[152:155], v[176:179], v[58:61]
	v_mfma_f32_16x16x32_bf16 v[54:57], v[144:147], v[184:187], v[54:57]
	v_mfma_f32_16x16x32_bf16 v[50:53], v[152:155], v[184:187], v[50:53]
	v_mfma_f32_16x16x32_bf16 v[38:41], v[144:147], v[192:195], v[38:41]
	v_mfma_f32_16x16x32_bf16 v[34:37], v[152:155], v[192:195], v[34:37]
	v_mfma_f32_16x16x32_bf16 v[22:25], v[144:147], v[208:211], v[22:25]
	v_mfma_f32_16x16x32_bf16 v[18:21], v[152:155], v[208:211], v[18:21]
	v_mfma_f32_16x16x32_bf16 v[46:49], v[156:159], v[172:175], v[46:49]
	v_mfma_f32_16x16x32_bf16 v[42:45], v[164:167], v[172:175], v[42:45]
	v_mfma_f32_16x16x32_bf16 v[30:33], v[156:159], v[180:183], v[30:33]
	v_mfma_f32_16x16x32_bf16 v[26:29], v[164:167], v[180:183], v[26:29]
	v_mfma_f32_16x16x32_bf16 v[14:17], v[156:159], v[188:191], v[14:17]
	v_mfma_f32_16x16x32_bf16 v[10:13], v[164:167], v[188:191], v[10:13]
	v_mfma_f32_16x16x32_bf16 v[6:9], v[156:159], v[196:199], v[6:9]
	v_mfma_f32_16x16x32_bf16 v[2:5], v[164:167], v[196:199], v[2:5]
	v_mfma_f32_16x16x32_bf16 v[46:49], v[160:163], v[176:179], v[46:49]
	v_mfma_f32_16x16x32_bf16 v[42:45], v[168:171], v[176:179], v[42:45]
	v_mfma_f32_16x16x32_bf16 v[30:33], v[160:163], v[184:187], v[30:33]
	v_mfma_f32_16x16x32_bf16 v[26:29], v[168:171], v[184:187], v[26:29]
	v_mfma_f32_16x16x32_bf16 v[14:17], v[160:163], v[192:195], v[14:17]
	v_mfma_f32_16x16x32_bf16 v[10:13], v[168:171], v[192:195], v[10:13]
	v_mfma_f32_16x16x32_bf16 v[6:9], v[160:163], v[208:211], v[6:9]
	v_mfma_f32_16x16x32_bf16 v[2:5], v[168:171], v[208:211], v[2:5]
	s_barrier
	s_setprio 0
	s_add_i32 s49, s49, 2
	s_add_u32 s40, s40, 0x100
	s_addc_u32 s41, s41, 0
	s_cmp_gt_u32 s49, 5
	s_mov_b64 s[14:15], s[16:17]
	s_cbranch_scc0 .LBB0_1739
	s_and_b64 vcc, exec, s[6:7]
	s_cbranch_vccz .LBB0_1742
	s_barrier
